# sel radix descent specialised by the number of live 2048-key mask words per lane (1-4 variants chosen from the visible-key count)
# speedup vs baseline: 1.0134x; 1.0070x over previous
.LBB0_843:
	s_lshl_b32 s6, s12, 10
	s_add_i32 s40, s6, 0
	s_add_i32 s40, s40, 0x20000
	s_add_i32 s41, s41, s12
	s_cmpk_gt_i32 s19, 0x100
	s_mov_b64 s[6:7], -1
	s_cbranch_scc0 .LBB0_1135
	v_xad_u32 v0, v99, 63, s19
	v_lshrrev_b32_e32 v1, 6, v0
	v_lshlrev_b32_e64 v2, v1, -1
	v_not_b32_e32 v2, v2
	v_cmp_gt_u32_e32 vcc, s49, v0
	v_subrev_u32_e32 v8, 32, v1
	v_lshlrev_b32_e64 v8, v8, -1
	v_cndmask_b32_e32 v7, -1, v2, vcc
	v_not_b32_e32 v8, v8
	v_cmp_lt_u32_e32 vcc, s50, v0
	v_subrev_u32_e32 v9, 64, v1
	v_lshlrev_b32_e64 v9, v9, -1
	v_cndmask_b32_e32 v8, 0, v8, vcc
	v_cmp_gt_u32_e32 vcc, s27, v0
	v_not_b32_e32 v9, v9
	v_add_u32_e32 v1, 0xffffffa0, v1
	v_cndmask_b32_e32 v6, -1, v8, vcc
	v_cmp_lt_u32_e32 vcc, s51, v0
	v_lshlrev_b32_e64 v1, v1, -1
	v_not_b32_e32 v1, v1
	v_cndmask_b32_e32 v9, 0, v9, vcc
	v_cmp_gt_u32_e32 vcc, s52, v0
	s_mov_b32 s57, 0
	v_mov_b32_e32 v3, 0
	v_cndmask_b32_e32 v5, -1, v9, vcc
	v_cmp_lt_u32_e32 vcc, s53, v0
	v_mov_b32_e32 v2, 0
	s_nop 0
	v_cndmask_b32_e32 v1, 0, v1, vcc
	v_cmp_gt_u32_e32 vcc, s48, v0
	v_mov_b32_e32 v0, 0
	s_nop 0
	v_cndmask_b32_e32 v4, -1, v1, vcc
	v_mov_b32_e32 v1, 0
	s_cmpk_gt_u32 s19, 0x1800
	s_cbranch_scc1 .Lrdx_w4
	s_cmpk_gt_u32 s19, 0x1000
	s_cbranch_scc1 .Lrdx_w3
	s_cmpk_gt_u32 s19, 0x800
	s_cbranch_scc1 .Lrdx_w2
	v_mov_b32_e32 v9, 0
	v_mov_b32_e32 v10, 0
	v_mov_b32_e32 v11, 0
	v_and_b32_e32 v8, v7, v189
	v_bcnt_u32_b32 v12, v8, 0
	s_nop 1
	v_add_u32_dpp v12, v12, v12 row_ror:8 row_mask:0xf bank_mask:0xf bound_ctrl:1
	s_nop 1
	v_add_u32_dpp v12, v12, v12 row_ror:4 row_mask:0xf bank_mask:0xf bound_ctrl:1
	s_nop 1
	v_add_u32_dpp v12, v12, v12 row_ror:2 row_mask:0xf bank_mask:0xf bound_ctrl:1
	s_nop 1
	v_add_u32_dpp v12, v12, v12 row_ror:1 row_mask:0xf bank_mask:0xf bound_ctrl:1
	s_nop 0
	v_readlane_b32 s6, v12, 0
	v_readlane_b32 s7, v12, 16
	v_readlane_b32 s8, v12, 32
	v_readlane_b32 s9, v12, 48
	s_add_i32 s6, s6, s7
	s_add_i32 s8, s8, s9
	s_add_i32 s6, s6, s57
	s_add_i32 s8, s6, s8
	s_cmpk_eq_i32 s8, 0x100
	s_cbranch_scc1 .Lrdx_eq
	s_cmpk_lt_i32 s8, 0x100
	s_cselect_b32 s6, -1, 0
	s_cselect_b32 s57, s8, s57
	v_bitop3_b32 v7, v7, v189, s6 bitop3:0x60
	v_bitop3_b32 v3, v3, v8, s6 bitop3:0xf8
	v_and_b32_e32 v8, v7, v188
	v_bcnt_u32_b32 v12, v8, 0
	s_nop 1
	v_add_u32_dpp v12, v12, v12 row_ror:8 row_mask:0xf bank_mask:0xf bound_ctrl:1
	s_nop 1
	v_add_u32_dpp v12, v12, v12 row_ror:4 row_mask:0xf bank_mask:0xf bound_ctrl:1
	s_nop 1
	v_add_u32_dpp v12, v12, v12 row_ror:2 row_mask:0xf bank_mask:0xf bound_ctrl:1
	s_nop 1
	v_add_u32_dpp v12, v12, v12 row_ror:1 row_mask:0xf bank_mask:0xf bound_ctrl:1
	s_nop 0
	v_readlane_b32 s6, v12, 0
	v_readlane_b32 s7, v12, 16
	v_readlane_b32 s8, v12, 32
	v_readlane_b32 s9, v12, 48
	s_add_i32 s6, s6, s7
	s_add_i32 s8, s8, s9
	s_add_i32 s6, s6, s57
	s_add_i32 s8, s6, s8
	s_cmpk_eq_i32 s8, 0x100
	s_cbranch_scc1 .Lrdx_eq
	s_cmpk_lt_i32 s8, 0x100
	s_cselect_b32 s6, -1, 0
	s_cselect_b32 s57, s8, s57
	v_bitop3_b32 v7, v7, v188, s6 bitop3:0x60
	v_bitop3_b32 v3, v3, v8, s6 bitop3:0xf8
	v_and_b32_e32 v8, v7, v187
	v_bcnt_u32_b32 v12, v8, 0
	s_nop 1
	v_add_u32_dpp v12, v12, v12 row_ror:8 row_mask:0xf bank_mask:0xf bound_ctrl:1
	s_nop 1
	v_add_u32_dpp v12, v12, v12 row_ror:4 row_mask:0xf bank_mask:0xf bound_ctrl:1
	s_nop 1
	v_add_u32_dpp v12, v12, v12 row_ror:2 row_mask:0xf bank_mask:0xf bound_ctrl:1
	s_nop 1
	v_add_u32_dpp v12, v12, v12 row_ror:1 row_mask:0xf bank_mask:0xf bound_ctrl:1
	s_nop 0
	v_readlane_b32 s6, v12, 0
	v_readlane_b32 s7, v12, 16
	v_readlane_b32 s8, v12, 32
	v_readlane_b32 s9, v12, 48
	s_add_i32 s6, s6, s7
	s_add_i32 s8, s8, s9
	s_add_i32 s6, s6, s57
	s_add_i32 s8, s6, s8
	s_cmpk_eq_i32 s8, 0x100
	s_cbranch_scc1 .Lrdx_eq
	s_cmpk_lt_i32 s8, 0x100
	s_cselect_b32 s6, -1, 0
	s_cselect_b32 s57, s8, s57
	v_bitop3_b32 v7, v7, v187, s6 bitop3:0x60
	v_bitop3_b32 v3, v3, v8, s6 bitop3:0xf8
	v_and_b32_e32 v8, v7, v184
	v_bcnt_u32_b32 v12, v8, 0
	s_nop 1
	v_add_u32_dpp v12, v12, v12 row_ror:8 row_mask:0xf bank_mask:0xf bound_ctrl:1
	s_nop 1
	v_add_u32_dpp v12, v12, v12 row_ror:4 row_mask:0xf bank_mask:0xf bound_ctrl:1
	s_nop 1
	v_add_u32_dpp v12, v12, v12 row_ror:2 row_mask:0xf bank_mask:0xf bound_ctrl:1
	s_nop 1
	v_add_u32_dpp v12, v12, v12 row_ror:1 row_mask:0xf bank_mask:0xf bound_ctrl:1
	s_nop 0
	v_readlane_b32 s6, v12, 0
	v_readlane_b32 s7, v12, 16
	v_readlane_b32 s8, v12, 32
	v_readlane_b32 s9, v12, 48
	s_add_i32 s6, s6, s7
	s_add_i32 s8, s8, s9
	s_add_i32 s6, s6, s57
	s_add_i32 s8, s6, s8
	s_cmpk_eq_i32 s8, 0x100
	s_cbranch_scc1 .Lrdx_eq
	s_cmpk_lt_i32 s8, 0x100
	s_cselect_b32 s6, -1, 0
	s_cselect_b32 s57, s8, s57
	v_bitop3_b32 v7, v7, v184, s6 bitop3:0x60
	v_bitop3_b32 v3, v3, v8, s6 bitop3:0xf8
	v_and_b32_e32 v8, v7, v181
	v_bcnt_u32_b32 v12, v8, 0
	s_nop 1
	v_add_u32_dpp v12, v12, v12 row_ror:8 row_mask:0xf bank_mask:0xf bound_ctrl:1
	s_nop 1
	v_add_u32_dpp v12, v12, v12 row_ror:4 row_mask:0xf bank_mask:0xf bound_ctrl:1
	s_nop 1
	v_add_u32_dpp v12, v12, v12 row_ror:2 row_mask:0xf bank_mask:0xf bound_ctrl:1
	s_nop 1
	v_add_u32_dpp v12, v12, v12 row_ror:1 row_mask:0xf bank_mask:0xf bound_ctrl:1
	s_nop 0
	v_readlane_b32 s6, v12, 0
	v_readlane_b32 s7, v12, 16
	v_readlane_b32 s8, v12, 32
	v_readlane_b32 s9, v12, 48
	s_add_i32 s6, s6, s7
	s_add_i32 s8, s8, s9
	s_add_i32 s6, s6, s57
	s_add_i32 s8, s6, s8
	s_cmpk_eq_i32 s8, 0x100
	s_cbranch_scc1 .Lrdx_eq
	s_cmpk_lt_i32 s8, 0x100
	s_cselect_b32 s6, -1, 0
	s_cselect_b32 s57, s8, s57
	v_bitop3_b32 v7, v7, v181, s6 bitop3:0x60
	v_bitop3_b32 v3, v3, v8, s6 bitop3:0xf8
	v_and_b32_e32 v8, v7, v160
	v_bcnt_u32_b32 v12, v8, 0
	s_nop 1
	v_add_u32_dpp v12, v12, v12 row_ror:8 row_mask:0xf bank_mask:0xf bound_ctrl:1
	s_nop 1
	v_add_u32_dpp v12, v12, v12 row_ror:4 row_mask:0xf bank_mask:0xf bound_ctrl:1
	s_nop 1
	v_add_u32_dpp v12, v12, v12 row_ror:2 row_mask:0xf bank_mask:0xf bound_ctrl:1
	s_nop 1
	v_add_u32_dpp v12, v12, v12 row_ror:1 row_mask:0xf bank_mask:0xf bound_ctrl:1
	s_nop 0
	v_readlane_b32 s6, v12, 0
	v_readlane_b32 s7, v12, 16
	v_readlane_b32 s8, v12, 32
	v_readlane_b32 s9, v12, 48
	s_add_i32 s6, s6, s7
	s_add_i32 s8, s8, s9
	s_add_i32 s6, s6, s57
	s_add_i32 s8, s6, s8
	s_cmpk_eq_i32 s8, 0x100
	s_cbranch_scc1 .Lrdx_eq
	s_cmpk_lt_i32 s8, 0x100
	s_cselect_b32 s6, -1, 0
	s_cselect_b32 s57, s8, s57
	v_bitop3_b32 v7, v7, v160, s6 bitop3:0x60
	v_bitop3_b32 v3, v3, v8, s6 bitop3:0xf8
	v_and_b32_e32 v8, v7, v158
	v_bcnt_u32_b32 v12, v8, 0
	s_nop 1
	v_add_u32_dpp v12, v12, v12 row_ror:8 row_mask:0xf bank_mask:0xf bound_ctrl:1
	s_nop 1
	v_add_u32_dpp v12, v12, v12 row_ror:4 row_mask:0xf bank_mask:0xf bound_ctrl:1
	s_nop 1
	v_add_u32_dpp v12, v12, v12 row_ror:2 row_mask:0xf bank_mask:0xf bound_ctrl:1
	s_nop 1
	v_add_u32_dpp v12, v12, v12 row_ror:1 row_mask:0xf bank_mask:0xf bound_ctrl:1
	s_nop 0
	v_readlane_b32 s6, v12, 0
	v_readlane_b32 s7, v12, 16
	v_readlane_b32 s8, v12, 32
	v_readlane_b32 s9, v12, 48
	s_add_i32 s6, s6, s7
	s_add_i32 s8, s8, s9
	s_add_i32 s6, s6, s57
	s_add_i32 s8, s6, s8
	s_cmpk_eq_i32 s8, 0x100
	s_cbranch_scc1 .Lrdx_eq
	s_cmpk_lt_i32 s8, 0x100
	s_cselect_b32 s6, -1, 0
	s_cselect_b32 s57, s8, s57
	v_bitop3_b32 v7, v7, v158, s6 bitop3:0x60
	v_bitop3_b32 v3, v3, v8, s6 bitop3:0xf8
	v_and_b32_e32 v8, v7, v156
	v_bcnt_u32_b32 v12, v8, 0
	s_nop 1
	v_add_u32_dpp v12, v12, v12 row_ror:8 row_mask:0xf bank_mask:0xf bound_ctrl:1
	s_nop 1
	v_add_u32_dpp v12, v12, v12 row_ror:4 row_mask:0xf bank_mask:0xf bound_ctrl:1
	s_nop 1
	v_add_u32_dpp v12, v12, v12 row_ror:2 row_mask:0xf bank_mask:0xf bound_ctrl:1
	s_nop 1
	v_add_u32_dpp v12, v12, v12 row_ror:1 row_mask:0xf bank_mask:0xf bound_ctrl:1
	s_nop 0
	v_readlane_b32 s6, v12, 0
	v_readlane_b32 s7, v12, 16
	v_readlane_b32 s8, v12, 32
	v_readlane_b32 s9, v12, 48
	s_add_i32 s6, s6, s7
	s_add_i32 s8, s8, s9
	s_add_i32 s6, s6, s57
	s_add_i32 s8, s6, s8
	s_cmpk_eq_i32 s8, 0x100
	s_cbranch_scc1 .Lrdx_eq
	s_cmpk_lt_i32 s8, 0x100
	s_cselect_b32 s6, -1, 0
	s_cselect_b32 s57, s8, s57
	v_bitop3_b32 v7, v7, v156, s6 bitop3:0x60
	v_bitop3_b32 v3, v3, v8, s6 bitop3:0xf8
	v_and_b32_e32 v8, v7, v154
	v_bcnt_u32_b32 v12, v8, 0
	s_nop 1
	v_add_u32_dpp v12, v12, v12 row_ror:8 row_mask:0xf bank_mask:0xf bound_ctrl:1
	s_nop 1
	v_add_u32_dpp v12, v12, v12 row_ror:4 row_mask:0xf bank_mask:0xf bound_ctrl:1
	s_nop 1
	v_add_u32_dpp v12, v12, v12 row_ror:2 row_mask:0xf bank_mask:0xf bound_ctrl:1
	s_nop 1
	v_add_u32_dpp v12, v12, v12 row_ror:1 row_mask:0xf bank_mask:0xf bound_ctrl:1
	s_nop 0
	v_readlane_b32 s6, v12, 0
	v_readlane_b32 s7, v12, 16
	v_readlane_b32 s8, v12, 32
	v_readlane_b32 s9, v12, 48
	s_add_i32 s6, s6, s7
	s_add_i32 s8, s8, s9
	s_add_i32 s6, s6, s57
	s_add_i32 s8, s6, s8
	s_cmpk_eq_i32 s8, 0x100
	s_cbranch_scc1 .Lrdx_eq
	s_cmpk_lt_i32 s8, 0x100
	s_cselect_b32 s6, -1, 0
	s_cselect_b32 s57, s8, s57
	v_bitop3_b32 v7, v7, v154, s6 bitop3:0x60
	v_bitop3_b32 v3, v3, v8, s6 bitop3:0xf8
	v_and_b32_e32 v8, v7, v152
	v_bcnt_u32_b32 v12, v8, 0
	s_nop 1
	v_add_u32_dpp v12, v12, v12 row_ror:8 row_mask:0xf bank_mask:0xf bound_ctrl:1
	s_nop 1
	v_add_u32_dpp v12, v12, v12 row_ror:4 row_mask:0xf bank_mask:0xf bound_ctrl:1
	s_nop 1
	v_add_u32_dpp v12, v12, v12 row_ror:2 row_mask:0xf bank_mask:0xf bound_ctrl:1
	s_nop 1
	v_add_u32_dpp v12, v12, v12 row_ror:1 row_mask:0xf bank_mask:0xf bound_ctrl:1
	s_nop 0
	v_readlane_b32 s6, v12, 0
	v_readlane_b32 s7, v12, 16
	v_readlane_b32 s8, v12, 32
	v_readlane_b32 s9, v12, 48
	s_add_i32 s6, s6, s7
	s_add_i32 s8, s8, s9
	s_add_i32 s6, s6, s57
	s_add_i32 s8, s6, s8
	s_cmpk_eq_i32 s8, 0x100
	s_cbranch_scc1 .Lrdx_eq
	s_cmpk_lt_i32 s8, 0x100
	s_cselect_b32 s6, -1, 0
	s_cselect_b32 s57, s8, s57
	v_bitop3_b32 v7, v7, v152, s6 bitop3:0x60
	v_bitop3_b32 v3, v3, v8, s6 bitop3:0xf8
	v_and_b32_e32 v8, v7, v150
	v_bcnt_u32_b32 v12, v8, 0
	s_nop 1
	v_add_u32_dpp v12, v12, v12 row_ror:8 row_mask:0xf bank_mask:0xf bound_ctrl:1
	s_nop 1
	v_add_u32_dpp v12, v12, v12 row_ror:4 row_mask:0xf bank_mask:0xf bound_ctrl:1
	s_nop 1
	v_add_u32_dpp v12, v12, v12 row_ror:2 row_mask:0xf bank_mask:0xf bound_ctrl:1
	s_nop 1
	v_add_u32_dpp v12, v12, v12 row_ror:1 row_mask:0xf bank_mask:0xf bound_ctrl:1
	s_nop 0
	v_readlane_b32 s6, v12, 0
	v_readlane_b32 s7, v12, 16
	v_readlane_b32 s8, v12, 32
	v_readlane_b32 s9, v12, 48
	s_add_i32 s6, s6, s7
	s_add_i32 s8, s8, s9
	s_add_i32 s6, s6, s57
	s_add_i32 s8, s6, s8
	s_cmpk_eq_i32 s8, 0x100
	s_cbranch_scc1 .Lrdx_eq
	s_cmpk_lt_i32 s8, 0x100
	s_cselect_b32 s6, -1, 0
	s_cselect_b32 s57, s8, s57
	v_bitop3_b32 v7, v7, v150, s6 bitop3:0x60
	v_bitop3_b32 v3, v3, v8, s6 bitop3:0xf8
	v_and_b32_e32 v8, v7, v148
	v_bcnt_u32_b32 v12, v8, 0
	s_nop 1
	v_add_u32_dpp v12, v12, v12 row_ror:8 row_mask:0xf bank_mask:0xf bound_ctrl:1
	s_nop 1
	v_add_u32_dpp v12, v12, v12 row_ror:4 row_mask:0xf bank_mask:0xf bound_ctrl:1
	s_nop 1
	v_add_u32_dpp v12, v12, v12 row_ror:2 row_mask:0xf bank_mask:0xf bound_ctrl:1
	s_nop 1
	v_add_u32_dpp v12, v12, v12 row_ror:1 row_mask:0xf bank_mask:0xf bound_ctrl:1
	s_nop 0
	v_readlane_b32 s6, v12, 0
	v_readlane_b32 s7, v12, 16
	v_readlane_b32 s8, v12, 32
	v_readlane_b32 s9, v12, 48
	s_add_i32 s6, s6, s7
	s_add_i32 s8, s8, s9
	s_add_i32 s6, s6, s57
	s_add_i32 s8, s6, s8
	s_cmpk_eq_i32 s8, 0x100
	s_cbranch_scc1 .Lrdx_eq
	s_cmpk_lt_i32 s8, 0x100
	s_cselect_b32 s6, -1, 0
	s_cselect_b32 s57, s8, s57
	v_bitop3_b32 v7, v7, v148, s6 bitop3:0x60
	v_bitop3_b32 v3, v3, v8, s6 bitop3:0xf8
	v_and_b32_e32 v8, v7, v146
	v_bcnt_u32_b32 v12, v8, 0
	s_nop 1
	v_add_u32_dpp v12, v12, v12 row_ror:8 row_mask:0xf bank_mask:0xf bound_ctrl:1
	s_nop 1
	v_add_u32_dpp v12, v12, v12 row_ror:4 row_mask:0xf bank_mask:0xf bound_ctrl:1
	s_nop 1
	v_add_u32_dpp v12, v12, v12 row_ror:2 row_mask:0xf bank_mask:0xf bound_ctrl:1
	s_nop 1
	v_add_u32_dpp v12, v12, v12 row_ror:1 row_mask:0xf bank_mask:0xf bound_ctrl:1
	s_nop 0
	v_readlane_b32 s6, v12, 0
	v_readlane_b32 s7, v12, 16
	v_readlane_b32 s8, v12, 32
	v_readlane_b32 s9, v12, 48
	s_add_i32 s6, s6, s7
	s_add_i32 s8, s8, s9
	s_add_i32 s6, s6, s57
	s_add_i32 s8, s6, s8
	s_cmpk_eq_i32 s8, 0x100
	s_cbranch_scc1 .Lrdx_eq
	s_cmpk_lt_i32 s8, 0x100
	s_cselect_b32 s6, -1, 0
	s_cselect_b32 s57, s8, s57
	v_bitop3_b32 v7, v7, v146, s6 bitop3:0x60
	v_bitop3_b32 v3, v3, v8, s6 bitop3:0xf8
	v_and_b32_e32 v8, v7, v144
	v_bcnt_u32_b32 v12, v8, 0
	s_nop 1
	v_add_u32_dpp v12, v12, v12 row_ror:8 row_mask:0xf bank_mask:0xf bound_ctrl:1
	s_nop 1
	v_add_u32_dpp v12, v12, v12 row_ror:4 row_mask:0xf bank_mask:0xf bound_ctrl:1
	s_nop 1
	v_add_u32_dpp v12, v12, v12 row_ror:2 row_mask:0xf bank_mask:0xf bound_ctrl:1
	s_nop 1
	v_add_u32_dpp v12, v12, v12 row_ror:1 row_mask:0xf bank_mask:0xf bound_ctrl:1
	s_nop 0
	v_readlane_b32 s6, v12, 0
	v_readlane_b32 s7, v12, 16
	v_readlane_b32 s8, v12, 32
	v_readlane_b32 s9, v12, 48
	s_add_i32 s6, s6, s7
	s_add_i32 s8, s8, s9
	s_add_i32 s6, s6, s57
	s_add_i32 s8, s6, s8
	s_cmpk_eq_i32 s8, 0x100
	s_cbranch_scc1 .Lrdx_eq
	s_cmpk_lt_i32 s8, 0x100
	s_cselect_b32 s6, -1, 0
	s_cselect_b32 s57, s8, s57
	v_bitop3_b32 v7, v7, v144, s6 bitop3:0x60
	v_bitop3_b32 v3, v3, v8, s6 bitop3:0xf8
	v_and_b32_e32 v8, v7, v142
	v_bcnt_u32_b32 v12, v8, 0
	s_nop 1
	v_add_u32_dpp v12, v12, v12 row_ror:8 row_mask:0xf bank_mask:0xf bound_ctrl:1
	s_nop 1
	v_add_u32_dpp v12, v12, v12 row_ror:4 row_mask:0xf bank_mask:0xf bound_ctrl:1
	s_nop 1
	v_add_u32_dpp v12, v12, v12 row_ror:2 row_mask:0xf bank_mask:0xf bound_ctrl:1
	s_nop 1
	v_add_u32_dpp v12, v12, v12 row_ror:1 row_mask:0xf bank_mask:0xf bound_ctrl:1
	s_nop 0
	v_readlane_b32 s6, v12, 0
	v_readlane_b32 s7, v12, 16
	v_readlane_b32 s8, v12, 32
	v_readlane_b32 s9, v12, 48
	s_add_i32 s6, s6, s7
	s_add_i32 s8, s8, s9
	s_add_i32 s6, s6, s57
	s_add_i32 s8, s6, s8
	s_cmpk_eq_i32 s8, 0x100
	s_cbranch_scc1 .Lrdx_eq
	s_cmpk_lt_i32 s8, 0x100
	s_cselect_b32 s6, -1, 0
	s_cselect_b32 s57, s8, s57
	v_bitop3_b32 v7, v7, v142, s6 bitop3:0x60
	v_bitop3_b32 v3, v3, v8, s6 bitop3:0xf8
	v_and_b32_e32 v8, v7, v140
	v_bcnt_u32_b32 v12, v8, 0
	s_nop 1
	v_add_u32_dpp v12, v12, v12 row_ror:8 row_mask:0xf bank_mask:0xf bound_ctrl:1
	s_nop 1
	v_add_u32_dpp v12, v12, v12 row_ror:4 row_mask:0xf bank_mask:0xf bound_ctrl:1
	s_nop 1
	v_add_u32_dpp v12, v12, v12 row_ror:2 row_mask:0xf bank_mask:0xf bound_ctrl:1
	s_nop 1
	v_add_u32_dpp v12, v12, v12 row_ror:1 row_mask:0xf bank_mask:0xf bound_ctrl:1
	s_nop 0
	v_readlane_b32 s6, v12, 0
	v_readlane_b32 s7, v12, 16
	v_readlane_b32 s8, v12, 32
	v_readlane_b32 s9, v12, 48
	s_add_i32 s6, s6, s7
	s_add_i32 s8, s8, s9
	s_add_i32 s6, s6, s57
	s_add_i32 s8, s6, s8
	s_cmpk_eq_i32 s8, 0x100
	s_cbranch_scc1 .Lrdx_eq
	s_cmpk_lt_i32 s8, 0x100
	s_cselect_b32 s6, -1, 0
	s_cselect_b32 s57, s8, s57
	v_bitop3_b32 v7, v7, v140, s6 bitop3:0x60
	v_bitop3_b32 v3, v3, v8, s6 bitop3:0xf8
	v_and_b32_e32 v8, v7, v138
	v_bcnt_u32_b32 v12, v8, 0
	s_nop 1
	v_add_u32_dpp v12, v12, v12 row_ror:8 row_mask:0xf bank_mask:0xf bound_ctrl:1
	s_nop 1
	v_add_u32_dpp v12, v12, v12 row_ror:4 row_mask:0xf bank_mask:0xf bound_ctrl:1
	s_nop 1
	v_add_u32_dpp v12, v12, v12 row_ror:2 row_mask:0xf bank_mask:0xf bound_ctrl:1
	s_nop 1
	v_add_u32_dpp v12, v12, v12 row_ror:1 row_mask:0xf bank_mask:0xf bound_ctrl:1
	s_nop 0
	v_readlane_b32 s6, v12, 0
	v_readlane_b32 s7, v12, 16
	v_readlane_b32 s8, v12, 32
	v_readlane_b32 s9, v12, 48
	s_add_i32 s6, s6, s7
	s_add_i32 s8, s8, s9
	s_add_i32 s6, s6, s57
	s_add_i32 s8, s6, s8
	s_cmpk_eq_i32 s8, 0x100
	s_cbranch_scc1 .Lrdx_eq
	s_cmpk_lt_i32 s8, 0x100
	s_cselect_b32 s6, -1, 0
	s_cselect_b32 s57, s8, s57
	v_bitop3_b32 v7, v7, v138, s6 bitop3:0x60
	v_bitop3_b32 v3, v3, v8, s6 bitop3:0xf8
	v_and_b32_e32 v8, v7, v136
	v_bcnt_u32_b32 v12, v8, 0
	s_nop 1
	v_add_u32_dpp v12, v12, v12 row_ror:8 row_mask:0xf bank_mask:0xf bound_ctrl:1
	s_nop 1
	v_add_u32_dpp v12, v12, v12 row_ror:4 row_mask:0xf bank_mask:0xf bound_ctrl:1
	s_nop 1
	v_add_u32_dpp v12, v12, v12 row_ror:2 row_mask:0xf bank_mask:0xf bound_ctrl:1
	s_nop 1
	v_add_u32_dpp v12, v12, v12 row_ror:1 row_mask:0xf bank_mask:0xf bound_ctrl:1
	s_nop 0
	v_readlane_b32 s6, v12, 0
	v_readlane_b32 s7, v12, 16
	v_readlane_b32 s8, v12, 32
	v_readlane_b32 s9, v12, 48
	s_add_i32 s6, s6, s7
	s_add_i32 s8, s8, s9
	s_add_i32 s6, s6, s57
	s_add_i32 s8, s6, s8
	s_cmpk_eq_i32 s8, 0x100
	s_cbranch_scc1 .Lrdx_eq
	s_cmpk_lt_i32 s8, 0x100
	s_cselect_b32 s6, -1, 0
	s_cselect_b32 s57, s8, s57
	v_bitop3_b32 v7, v7, v136, s6 bitop3:0x60
	v_bitop3_b32 v3, v3, v8, s6 bitop3:0xf8
	v_and_b32_e32 v8, v7, v134
	v_bcnt_u32_b32 v12, v8, 0
	s_nop 1
	v_add_u32_dpp v12, v12, v12 row_ror:8 row_mask:0xf bank_mask:0xf bound_ctrl:1
	s_nop 1
	v_add_u32_dpp v12, v12, v12 row_ror:4 row_mask:0xf bank_mask:0xf bound_ctrl:1
	s_nop 1
	v_add_u32_dpp v12, v12, v12 row_ror:2 row_mask:0xf bank_mask:0xf bound_ctrl:1
	s_nop 1
	v_add_u32_dpp v12, v12, v12 row_ror:1 row_mask:0xf bank_mask:0xf bound_ctrl:1
	s_nop 0
	v_readlane_b32 s6, v12, 0
	v_readlane_b32 s7, v12, 16
	v_readlane_b32 s8, v12, 32
	v_readlane_b32 s9, v12, 48
	s_add_i32 s6, s6, s7
	s_add_i32 s8, s8, s9
	s_add_i32 s6, s6, s57
	s_add_i32 s8, s6, s8
	s_cmpk_eq_i32 s8, 0x100
	s_cbranch_scc1 .Lrdx_eq
	s_cmpk_lt_i32 s8, 0x100
	s_cselect_b32 s6, -1, 0
	s_cselect_b32 s57, s8, s57
	v_bitop3_b32 v7, v7, v134, s6 bitop3:0x60
	v_bitop3_b32 v3, v3, v8, s6 bitop3:0xf8
	v_and_b32_e32 v8, v7, v132
	v_bcnt_u32_b32 v12, v8, 0
	s_nop 1
	v_add_u32_dpp v12, v12, v12 row_ror:8 row_mask:0xf bank_mask:0xf bound_ctrl:1
	s_nop 1
	v_add_u32_dpp v12, v12, v12 row_ror:4 row_mask:0xf bank_mask:0xf bound_ctrl:1
	s_nop 1
	v_add_u32_dpp v12, v12, v12 row_ror:2 row_mask:0xf bank_mask:0xf bound_ctrl:1
	s_nop 1
	v_add_u32_dpp v12, v12, v12 row_ror:1 row_mask:0xf bank_mask:0xf bound_ctrl:1
	s_nop 0
	v_readlane_b32 s6, v12, 0
	v_readlane_b32 s7, v12, 16
	v_readlane_b32 s8, v12, 32
	v_readlane_b32 s9, v12, 48
	s_add_i32 s6, s6, s7
	s_add_i32 s8, s8, s9
	s_add_i32 s6, s6, s57
	s_add_i32 s8, s6, s8
	s_cmpk_eq_i32 s8, 0x100
	s_cbranch_scc1 .Lrdx_eq
	s_cmpk_lt_i32 s8, 0x100
	s_cselect_b32 s6, -1, 0
	s_cselect_b32 s57, s8, s57
	v_bitop3_b32 v7, v7, v132, s6 bitop3:0x60
	v_bitop3_b32 v3, v3, v8, s6 bitop3:0xf8
	v_and_b32_e32 v8, v7, v130
	v_bcnt_u32_b32 v12, v8, 0
	s_nop 1
	v_add_u32_dpp v12, v12, v12 row_ror:8 row_mask:0xf bank_mask:0xf bound_ctrl:1
	s_nop 1
	v_add_u32_dpp v12, v12, v12 row_ror:4 row_mask:0xf bank_mask:0xf bound_ctrl:1
	s_nop 1
	v_add_u32_dpp v12, v12, v12 row_ror:2 row_mask:0xf bank_mask:0xf bound_ctrl:1
	s_nop 1
	v_add_u32_dpp v12, v12, v12 row_ror:1 row_mask:0xf bank_mask:0xf bound_ctrl:1
	s_nop 0
	v_readlane_b32 s6, v12, 0
	v_readlane_b32 s7, v12, 16
	v_readlane_b32 s8, v12, 32
	v_readlane_b32 s9, v12, 48
	s_add_i32 s6, s6, s7
	s_add_i32 s8, s8, s9
	s_add_i32 s6, s6, s57
	s_add_i32 s8, s6, s8
	s_cmpk_eq_i32 s8, 0x100
	s_cbranch_scc1 .Lrdx_eq
	s_cmpk_lt_i32 s8, 0x100
	s_cselect_b32 s6, -1, 0
	s_cselect_b32 s57, s8, s57
	v_bitop3_b32 v7, v7, v130, s6 bitop3:0x60
	v_bitop3_b32 v3, v3, v8, s6 bitop3:0xf8
	v_and_b32_e32 v8, v7, v128
	v_bcnt_u32_b32 v12, v8, 0
	s_nop 1
	v_add_u32_dpp v12, v12, v12 row_ror:8 row_mask:0xf bank_mask:0xf bound_ctrl:1
	s_nop 1
	v_add_u32_dpp v12, v12, v12 row_ror:4 row_mask:0xf bank_mask:0xf bound_ctrl:1
	s_nop 1
	v_add_u32_dpp v12, v12, v12 row_ror:2 row_mask:0xf bank_mask:0xf bound_ctrl:1
	s_nop 1
	v_add_u32_dpp v12, v12, v12 row_ror:1 row_mask:0xf bank_mask:0xf bound_ctrl:1
	s_nop 0
	v_readlane_b32 s6, v12, 0
	v_readlane_b32 s7, v12, 16
	v_readlane_b32 s8, v12, 32
	v_readlane_b32 s9, v12, 48
	s_add_i32 s6, s6, s7
	s_add_i32 s8, s8, s9
	s_add_i32 s6, s6, s57
	s_add_i32 s8, s6, s8
	s_cmpk_eq_i32 s8, 0x100
	s_cbranch_scc1 .Lrdx_eq
	s_cmpk_lt_i32 s8, 0x100
	s_cselect_b32 s6, -1, 0
	s_cselect_b32 s57, s8, s57
	v_bitop3_b32 v7, v7, v128, s6 bitop3:0x60
	v_bitop3_b32 v3, v3, v8, s6 bitop3:0xf8
	v_and_b32_e32 v8, v7, v126
	v_bcnt_u32_b32 v12, v8, 0
	s_nop 1
	v_add_u32_dpp v12, v12, v12 row_ror:8 row_mask:0xf bank_mask:0xf bound_ctrl:1
	s_nop 1
	v_add_u32_dpp v12, v12, v12 row_ror:4 row_mask:0xf bank_mask:0xf bound_ctrl:1
	s_nop 1
	v_add_u32_dpp v12, v12, v12 row_ror:2 row_mask:0xf bank_mask:0xf bound_ctrl:1
	s_nop 1
	v_add_u32_dpp v12, v12, v12 row_ror:1 row_mask:0xf bank_mask:0xf bound_ctrl:1
	s_nop 0
	v_readlane_b32 s6, v12, 0
	v_readlane_b32 s7, v12, 16
	v_readlane_b32 s8, v12, 32
	v_readlane_b32 s9, v12, 48
	s_add_i32 s6, s6, s7
	s_add_i32 s8, s8, s9
	s_add_i32 s6, s6, s57
	s_add_i32 s8, s6, s8
	s_cmpk_eq_i32 s8, 0x100
	s_cbranch_scc1 .Lrdx_eq
	s_cmpk_lt_i32 s8, 0x100
	s_cselect_b32 s6, -1, 0
	s_cselect_b32 s57, s8, s57
	v_bitop3_b32 v7, v7, v126, s6 bitop3:0x60
	v_bitop3_b32 v3, v3, v8, s6 bitop3:0xf8
	v_and_b32_e32 v8, v7, v124
	v_bcnt_u32_b32 v12, v8, 0
	s_nop 1
	v_add_u32_dpp v12, v12, v12 row_ror:8 row_mask:0xf bank_mask:0xf bound_ctrl:1
	s_nop 1
	v_add_u32_dpp v12, v12, v12 row_ror:4 row_mask:0xf bank_mask:0xf bound_ctrl:1
	s_nop 1
	v_add_u32_dpp v12, v12, v12 row_ror:2 row_mask:0xf bank_mask:0xf bound_ctrl:1
	s_nop 1
	v_add_u32_dpp v12, v12, v12 row_ror:1 row_mask:0xf bank_mask:0xf bound_ctrl:1
	s_nop 0
	v_readlane_b32 s6, v12, 0
	v_readlane_b32 s7, v12, 16
	v_readlane_b32 s8, v12, 32
	v_readlane_b32 s9, v12, 48
	s_add_i32 s6, s6, s7
	s_add_i32 s8, s8, s9
	s_add_i32 s6, s6, s57
	s_add_i32 s8, s6, s8
	s_cmpk_eq_i32 s8, 0x100
	s_cbranch_scc1 .Lrdx_eq
	s_cmpk_lt_i32 s8, 0x100
	s_cselect_b32 s6, -1, 0
	s_cselect_b32 s57, s8, s57
	v_bitop3_b32 v7, v7, v124, s6 bitop3:0x60
	v_bitop3_b32 v3, v3, v8, s6 bitop3:0xf8
	v_and_b32_e32 v8, v7, v122
	v_bcnt_u32_b32 v12, v8, 0
	s_nop 1
	v_add_u32_dpp v12, v12, v12 row_ror:8 row_mask:0xf bank_mask:0xf bound_ctrl:1
	s_nop 1
	v_add_u32_dpp v12, v12, v12 row_ror:4 row_mask:0xf bank_mask:0xf bound_ctrl:1
	s_nop 1
	v_add_u32_dpp v12, v12, v12 row_ror:2 row_mask:0xf bank_mask:0xf bound_ctrl:1
	s_nop 1
	v_add_u32_dpp v12, v12, v12 row_ror:1 row_mask:0xf bank_mask:0xf bound_ctrl:1
	s_nop 0
	v_readlane_b32 s6, v12, 0
	v_readlane_b32 s7, v12, 16
	v_readlane_b32 s8, v12, 32
	v_readlane_b32 s9, v12, 48
	s_add_i32 s6, s6, s7
	s_add_i32 s8, s8, s9
	s_add_i32 s6, s6, s57
	s_add_i32 s8, s6, s8
	s_cmpk_eq_i32 s8, 0x100
	s_cbranch_scc1 .Lrdx_eq
	s_cmpk_lt_i32 s8, 0x100
	s_cselect_b32 s6, -1, 0
	s_cselect_b32 s57, s8, s57
	v_bitop3_b32 v7, v7, v122, s6 bitop3:0x60
	v_bitop3_b32 v3, v3, v8, s6 bitop3:0xf8
	v_and_b32_e32 v8, v7, v120
	v_bcnt_u32_b32 v12, v8, 0
	s_nop 1
	v_add_u32_dpp v12, v12, v12 row_ror:8 row_mask:0xf bank_mask:0xf bound_ctrl:1
	s_nop 1
	v_add_u32_dpp v12, v12, v12 row_ror:4 row_mask:0xf bank_mask:0xf bound_ctrl:1
	s_nop 1
	v_add_u32_dpp v12, v12, v12 row_ror:2 row_mask:0xf bank_mask:0xf bound_ctrl:1
	s_nop 1
	v_add_u32_dpp v12, v12, v12 row_ror:1 row_mask:0xf bank_mask:0xf bound_ctrl:1
	s_nop 0
	v_readlane_b32 s6, v12, 0
	v_readlane_b32 s7, v12, 16
	v_readlane_b32 s8, v12, 32
	v_readlane_b32 s9, v12, 48
	s_add_i32 s6, s6, s7
	s_add_i32 s8, s8, s9
	s_add_i32 s6, s6, s57
	s_add_i32 s8, s6, s8
	s_cmpk_eq_i32 s8, 0x100
	s_cbranch_scc1 .Lrdx_eq
	s_cmpk_lt_i32 s8, 0x100
	s_cselect_b32 s6, -1, 0
	s_cselect_b32 s57, s8, s57
	v_bitop3_b32 v7, v7, v120, s6 bitop3:0x60
	v_bitop3_b32 v3, v3, v8, s6 bitop3:0xf8
	v_and_b32_e32 v8, v7, v118
	v_bcnt_u32_b32 v12, v8, 0
	s_nop 1
	v_add_u32_dpp v12, v12, v12 row_ror:8 row_mask:0xf bank_mask:0xf bound_ctrl:1
	s_nop 1
	v_add_u32_dpp v12, v12, v12 row_ror:4 row_mask:0xf bank_mask:0xf bound_ctrl:1
	s_nop 1
	v_add_u32_dpp v12, v12, v12 row_ror:2 row_mask:0xf bank_mask:0xf bound_ctrl:1
	s_nop 1
	v_add_u32_dpp v12, v12, v12 row_ror:1 row_mask:0xf bank_mask:0xf bound_ctrl:1
	s_nop 0
	v_readlane_b32 s6, v12, 0
	v_readlane_b32 s7, v12, 16
	v_readlane_b32 s8, v12, 32
	v_readlane_b32 s9, v12, 48
	s_add_i32 s6, s6, s7
	s_add_i32 s8, s8, s9
	s_add_i32 s6, s6, s57
	s_add_i32 s8, s6, s8
	s_cmpk_eq_i32 s8, 0x100
	s_cbranch_scc1 .Lrdx_eq
	s_cmpk_lt_i32 s8, 0x100
	s_cselect_b32 s6, -1, 0
	s_cselect_b32 s57, s8, s57
	v_bitop3_b32 v7, v7, v118, s6 bitop3:0x60
	v_bitop3_b32 v3, v3, v8, s6 bitop3:0xf8
	v_and_b32_e32 v8, v7, v116
	v_bcnt_u32_b32 v12, v8, 0
	s_nop 1
	v_add_u32_dpp v12, v12, v12 row_ror:8 row_mask:0xf bank_mask:0xf bound_ctrl:1
	s_nop 1
	v_add_u32_dpp v12, v12, v12 row_ror:4 row_mask:0xf bank_mask:0xf bound_ctrl:1
	s_nop 1
	v_add_u32_dpp v12, v12, v12 row_ror:2 row_mask:0xf bank_mask:0xf bound_ctrl:1
	s_nop 1
	v_add_u32_dpp v12, v12, v12 row_ror:1 row_mask:0xf bank_mask:0xf bound_ctrl:1
	s_nop 0
	v_readlane_b32 s6, v12, 0
	v_readlane_b32 s7, v12, 16
	v_readlane_b32 s8, v12, 32
	v_readlane_b32 s9, v12, 48
	s_add_i32 s6, s6, s7
	s_add_i32 s8, s8, s9
	s_add_i32 s6, s6, s57
	s_add_i32 s8, s6, s8
	s_cmpk_eq_i32 s8, 0x100
	s_cbranch_scc1 .Lrdx_eq
	s_cmpk_lt_i32 s8, 0x100
	s_cselect_b32 s6, -1, 0
	s_cselect_b32 s57, s8, s57
	v_bitop3_b32 v7, v7, v116, s6 bitop3:0x60
	v_bitop3_b32 v3, v3, v8, s6 bitop3:0xf8
	v_and_b32_e32 v8, v7, v114
	v_bcnt_u32_b32 v12, v8, 0
	s_nop 1
	v_add_u32_dpp v12, v12, v12 row_ror:8 row_mask:0xf bank_mask:0xf bound_ctrl:1
	s_nop 1
	v_add_u32_dpp v12, v12, v12 row_ror:4 row_mask:0xf bank_mask:0xf bound_ctrl:1
	s_nop 1
	v_add_u32_dpp v12, v12, v12 row_ror:2 row_mask:0xf bank_mask:0xf bound_ctrl:1
	s_nop 1
	v_add_u32_dpp v12, v12, v12 row_ror:1 row_mask:0xf bank_mask:0xf bound_ctrl:1
	s_nop 0
	v_readlane_b32 s6, v12, 0
	v_readlane_b32 s7, v12, 16
	v_readlane_b32 s8, v12, 32
	v_readlane_b32 s9, v12, 48
	s_add_i32 s6, s6, s7
	s_add_i32 s8, s8, s9
	s_add_i32 s6, s6, s57
	s_add_i32 s8, s6, s8
	s_cmpk_eq_i32 s8, 0x100
	s_cbranch_scc1 .Lrdx_eq
	s_cmpk_lt_i32 s8, 0x100
	s_cselect_b32 s6, -1, 0
	s_cselect_b32 s57, s8, s57
	v_bitop3_b32 v7, v7, v114, s6 bitop3:0x60
	v_bitop3_b32 v3, v3, v8, s6 bitop3:0xf8
	v_and_b32_e32 v8, v7, v112
	v_bcnt_u32_b32 v12, v8, 0
	s_nop 1
	v_add_u32_dpp v12, v12, v12 row_ror:8 row_mask:0xf bank_mask:0xf bound_ctrl:1
	s_nop 1
	v_add_u32_dpp v12, v12, v12 row_ror:4 row_mask:0xf bank_mask:0xf bound_ctrl:1
	s_nop 1
	v_add_u32_dpp v12, v12, v12 row_ror:2 row_mask:0xf bank_mask:0xf bound_ctrl:1
	s_nop 1
	v_add_u32_dpp v12, v12, v12 row_ror:1 row_mask:0xf bank_mask:0xf bound_ctrl:1
	s_nop 0
	v_readlane_b32 s6, v12, 0
	v_readlane_b32 s7, v12, 16
	v_readlane_b32 s8, v12, 32
	v_readlane_b32 s9, v12, 48
	s_add_i32 s6, s6, s7
	s_add_i32 s8, s8, s9
	s_add_i32 s6, s6, s57
	s_add_i32 s8, s6, s8
	s_cmpk_eq_i32 s8, 0x100
	s_cbranch_scc1 .Lrdx_eq
	s_cmpk_lt_i32 s8, 0x100
	s_cselect_b32 s6, -1, 0
	s_cselect_b32 s57, s8, s57
	v_bitop3_b32 v7, v7, v112, s6 bitop3:0x60
	v_bitop3_b32 v3, v3, v8, s6 bitop3:0xf8
	v_and_b32_e32 v8, v7, v110
	v_bcnt_u32_b32 v12, v8, 0
	s_nop 1
	v_add_u32_dpp v12, v12, v12 row_ror:8 row_mask:0xf bank_mask:0xf bound_ctrl:1
	s_nop 1
	v_add_u32_dpp v12, v12, v12 row_ror:4 row_mask:0xf bank_mask:0xf bound_ctrl:1
	s_nop 1
	v_add_u32_dpp v12, v12, v12 row_ror:2 row_mask:0xf bank_mask:0xf bound_ctrl:1
	s_nop 1
	v_add_u32_dpp v12, v12, v12 row_ror:1 row_mask:0xf bank_mask:0xf bound_ctrl:1
	s_nop 0
	v_readlane_b32 s6, v12, 0
	v_readlane_b32 s7, v12, 16
	v_readlane_b32 s8, v12, 32
	v_readlane_b32 s9, v12, 48
	s_add_i32 s6, s6, s7
	s_add_i32 s8, s8, s9
	s_add_i32 s6, s6, s57
	s_add_i32 s8, s6, s8
	s_cmpk_eq_i32 s8, 0x100
	s_cbranch_scc1 .Lrdx_eq
	s_cmpk_lt_i32 s8, 0x100
	s_cselect_b32 s6, -1, 0
	s_cselect_b32 s57, s8, s57
	v_bitop3_b32 v7, v7, v110, s6 bitop3:0x60
	v_bitop3_b32 v3, v3, v8, s6 bitop3:0xf8
	v_and_b32_e32 v8, v7, v108
	v_bcnt_u32_b32 v12, v8, 0
	s_nop 1
	v_add_u32_dpp v12, v12, v12 row_ror:8 row_mask:0xf bank_mask:0xf bound_ctrl:1
	s_nop 1
	v_add_u32_dpp v12, v12, v12 row_ror:4 row_mask:0xf bank_mask:0xf bound_ctrl:1
	s_nop 1
	v_add_u32_dpp v12, v12, v12 row_ror:2 row_mask:0xf bank_mask:0xf bound_ctrl:1
	s_nop 1
	v_add_u32_dpp v12, v12, v12 row_ror:1 row_mask:0xf bank_mask:0xf bound_ctrl:1
	s_nop 0
	v_readlane_b32 s6, v12, 0
	v_readlane_b32 s7, v12, 16
	v_readlane_b32 s8, v12, 32
	v_readlane_b32 s9, v12, 48
	s_add_i32 s6, s6, s7
	s_add_i32 s8, s8, s9
	s_add_i32 s6, s6, s57
	s_add_i32 s8, s6, s8
	s_cmpk_eq_i32 s8, 0x100
	s_cbranch_scc1 .Lrdx_eq
	s_cmpk_lt_i32 s8, 0x100
	s_cselect_b32 s6, -1, 0
	s_cselect_b32 s57, s8, s57
	v_bitop3_b32 v7, v7, v108, s6 bitop3:0x60
	v_bitop3_b32 v3, v3, v8, s6 bitop3:0xf8
	s_branch .LBB0_1099
.Lrdx_w2:
	v_mov_b32_e32 v10, 0
	v_mov_b32_e32 v11, 0
	v_and_b32_e32 v8, v7, v189
	v_and_b32_e32 v9, v6, v186
	v_bcnt_u32_b32 v12, v8, 0
	v_bcnt_u32_b32 v12, v9, v12
	s_nop 1
	v_add_u32_dpp v12, v12, v12 row_ror:8 row_mask:0xf bank_mask:0xf bound_ctrl:1
	s_nop 1
	v_add_u32_dpp v12, v12, v12 row_ror:4 row_mask:0xf bank_mask:0xf bound_ctrl:1
	s_nop 1
	v_add_u32_dpp v12, v12, v12 row_ror:2 row_mask:0xf bank_mask:0xf bound_ctrl:1
	s_nop 1
	v_add_u32_dpp v12, v12, v12 row_ror:1 row_mask:0xf bank_mask:0xf bound_ctrl:1
	s_nop 0
	v_readlane_b32 s6, v12, 0
	v_readlane_b32 s7, v12, 16
	v_readlane_b32 s8, v12, 32
	v_readlane_b32 s9, v12, 48
	s_add_i32 s6, s6, s7
	s_add_i32 s8, s8, s9
	s_add_i32 s6, s6, s57
	s_add_i32 s8, s6, s8
	s_cmpk_eq_i32 s8, 0x100
	s_cbranch_scc1 .Lrdx_eq
	s_cmpk_lt_i32 s8, 0x100
	s_cselect_b32 s6, -1, 0
	s_cselect_b32 s57, s8, s57
	v_bitop3_b32 v7, v7, v189, s6 bitop3:0x60
	v_bitop3_b32 v6, v6, v186, s6 bitop3:0x60
	v_bitop3_b32 v3, v3, v8, s6 bitop3:0xf8
	v_bitop3_b32 v2, v2, v9, s6 bitop3:0xf8
	v_and_b32_e32 v8, v7, v188
	v_and_b32_e32 v9, v6, v185
	v_bcnt_u32_b32 v12, v8, 0
	v_bcnt_u32_b32 v12, v9, v12
	s_nop 1
	v_add_u32_dpp v12, v12, v12 row_ror:8 row_mask:0xf bank_mask:0xf bound_ctrl:1
	s_nop 1
	v_add_u32_dpp v12, v12, v12 row_ror:4 row_mask:0xf bank_mask:0xf bound_ctrl:1
	s_nop 1
	v_add_u32_dpp v12, v12, v12 row_ror:2 row_mask:0xf bank_mask:0xf bound_ctrl:1
	s_nop 1
	v_add_u32_dpp v12, v12, v12 row_ror:1 row_mask:0xf bank_mask:0xf bound_ctrl:1
	s_nop 0
	v_readlane_b32 s6, v12, 0
	v_readlane_b32 s7, v12, 16
	v_readlane_b32 s8, v12, 32
	v_readlane_b32 s9, v12, 48
	s_add_i32 s6, s6, s7
	s_add_i32 s8, s8, s9
	s_add_i32 s6, s6, s57
	s_add_i32 s8, s6, s8
	s_cmpk_eq_i32 s8, 0x100
	s_cbranch_scc1 .Lrdx_eq
	s_cmpk_lt_i32 s8, 0x100
	s_cselect_b32 s6, -1, 0
	s_cselect_b32 s57, s8, s57
	v_bitop3_b32 v7, v7, v188, s6 bitop3:0x60
	v_bitop3_b32 v6, v6, v185, s6 bitop3:0x60
	v_bitop3_b32 v3, v3, v8, s6 bitop3:0xf8
	v_bitop3_b32 v2, v2, v9, s6 bitop3:0xf8
	v_and_b32_e32 v8, v7, v187
	v_and_b32_e32 v9, v6, v183
	v_bcnt_u32_b32 v12, v8, 0
	v_bcnt_u32_b32 v12, v9, v12
	s_nop 1
	v_add_u32_dpp v12, v12, v12 row_ror:8 row_mask:0xf bank_mask:0xf bound_ctrl:1
	s_nop 1
	v_add_u32_dpp v12, v12, v12 row_ror:4 row_mask:0xf bank_mask:0xf bound_ctrl:1
	s_nop 1
	v_add_u32_dpp v12, v12, v12 row_ror:2 row_mask:0xf bank_mask:0xf bound_ctrl:1
	s_nop 1
	v_add_u32_dpp v12, v12, v12 row_ror:1 row_mask:0xf bank_mask:0xf bound_ctrl:1
	s_nop 0
	v_readlane_b32 s6, v12, 0
	v_readlane_b32 s7, v12, 16
	v_readlane_b32 s8, v12, 32
	v_readlane_b32 s9, v12, 48
	s_add_i32 s6, s6, s7
	s_add_i32 s8, s8, s9
	s_add_i32 s6, s6, s57
	s_add_i32 s8, s6, s8
	s_cmpk_eq_i32 s8, 0x100
	s_cbranch_scc1 .Lrdx_eq
	s_cmpk_lt_i32 s8, 0x100
	s_cselect_b32 s6, -1, 0
	s_cselect_b32 s57, s8, s57
	v_bitop3_b32 v7, v7, v187, s6 bitop3:0x60
	v_bitop3_b32 v6, v6, v183, s6 bitop3:0x60
	v_bitop3_b32 v3, v3, v8, s6 bitop3:0xf8
	v_bitop3_b32 v2, v2, v9, s6 bitop3:0xf8
	v_and_b32_e32 v8, v7, v184
	v_and_b32_e32 v9, v6, v161
	v_bcnt_u32_b32 v12, v8, 0
	v_bcnt_u32_b32 v12, v9, v12
	s_nop 1
	v_add_u32_dpp v12, v12, v12 row_ror:8 row_mask:0xf bank_mask:0xf bound_ctrl:1
	s_nop 1
	v_add_u32_dpp v12, v12, v12 row_ror:4 row_mask:0xf bank_mask:0xf bound_ctrl:1
	s_nop 1
	v_add_u32_dpp v12, v12, v12 row_ror:2 row_mask:0xf bank_mask:0xf bound_ctrl:1
	s_nop 1
	v_add_u32_dpp v12, v12, v12 row_ror:1 row_mask:0xf bank_mask:0xf bound_ctrl:1
	s_nop 0
	v_readlane_b32 s6, v12, 0
	v_readlane_b32 s7, v12, 16
	v_readlane_b32 s8, v12, 32
	v_readlane_b32 s9, v12, 48
	s_add_i32 s6, s6, s7
	s_add_i32 s8, s8, s9
	s_add_i32 s6, s6, s57
	s_add_i32 s8, s6, s8
	s_cmpk_eq_i32 s8, 0x100
	s_cbranch_scc1 .Lrdx_eq
	s_cmpk_lt_i32 s8, 0x100
	s_cselect_b32 s6, -1, 0
	s_cselect_b32 s57, s8, s57
	v_bitop3_b32 v7, v7, v184, s6 bitop3:0x60
	v_bitop3_b32 v6, v6, v161, s6 bitop3:0x60
	v_bitop3_b32 v3, v3, v8, s6 bitop3:0xf8
	v_bitop3_b32 v2, v2, v9, s6 bitop3:0xf8
	v_and_b32_e32 v8, v7, v181
	v_and_b32_e32 v9, v6, v159
	v_bcnt_u32_b32 v12, v8, 0
	v_bcnt_u32_b32 v12, v9, v12
	s_nop 1
	v_add_u32_dpp v12, v12, v12 row_ror:8 row_mask:0xf bank_mask:0xf bound_ctrl:1
	s_nop 1
	v_add_u32_dpp v12, v12, v12 row_ror:4 row_mask:0xf bank_mask:0xf bound_ctrl:1
	s_nop 1
	v_add_u32_dpp v12, v12, v12 row_ror:2 row_mask:0xf bank_mask:0xf bound_ctrl:1
	s_nop 1
	v_add_u32_dpp v12, v12, v12 row_ror:1 row_mask:0xf bank_mask:0xf bound_ctrl:1
	s_nop 0
	v_readlane_b32 s6, v12, 0
	v_readlane_b32 s7, v12, 16
	v_readlane_b32 s8, v12, 32
	v_readlane_b32 s9, v12, 48
	s_add_i32 s6, s6, s7
	s_add_i32 s8, s8, s9
	s_add_i32 s6, s6, s57
	s_add_i32 s8, s6, s8
	s_cmpk_eq_i32 s8, 0x100
	s_cbranch_scc1 .Lrdx_eq
	s_cmpk_lt_i32 s8, 0x100
	s_cselect_b32 s6, -1, 0
	s_cselect_b32 s57, s8, s57
	v_bitop3_b32 v7, v7, v181, s6 bitop3:0x60
	v_bitop3_b32 v6, v6, v159, s6 bitop3:0x60
	v_bitop3_b32 v3, v3, v8, s6 bitop3:0xf8
	v_bitop3_b32 v2, v2, v9, s6 bitop3:0xf8
	v_and_b32_e32 v8, v7, v160
	v_and_b32_e32 v9, v6, v157
	v_bcnt_u32_b32 v12, v8, 0
	v_bcnt_u32_b32 v12, v9, v12
	s_nop 1
	v_add_u32_dpp v12, v12, v12 row_ror:8 row_mask:0xf bank_mask:0xf bound_ctrl:1
	s_nop 1
	v_add_u32_dpp v12, v12, v12 row_ror:4 row_mask:0xf bank_mask:0xf bound_ctrl:1
	s_nop 1
	v_add_u32_dpp v12, v12, v12 row_ror:2 row_mask:0xf bank_mask:0xf bound_ctrl:1
	s_nop 1
	v_add_u32_dpp v12, v12, v12 row_ror:1 row_mask:0xf bank_mask:0xf bound_ctrl:1
	s_nop 0
	v_readlane_b32 s6, v12, 0
	v_readlane_b32 s7, v12, 16
	v_readlane_b32 s8, v12, 32
	v_readlane_b32 s9, v12, 48
	s_add_i32 s6, s6, s7
	s_add_i32 s8, s8, s9
	s_add_i32 s6, s6, s57
	s_add_i32 s8, s6, s8
	s_cmpk_eq_i32 s8, 0x100
	s_cbranch_scc1 .Lrdx_eq
	s_cmpk_lt_i32 s8, 0x100
	s_cselect_b32 s6, -1, 0
	s_cselect_b32 s57, s8, s57
	v_bitop3_b32 v7, v7, v160, s6 bitop3:0x60
	v_bitop3_b32 v6, v6, v157, s6 bitop3:0x60
	v_bitop3_b32 v3, v3, v8, s6 bitop3:0xf8
	v_bitop3_b32 v2, v2, v9, s6 bitop3:0xf8
	v_and_b32_e32 v8, v7, v158
	v_and_b32_e32 v9, v6, v155
	v_bcnt_u32_b32 v12, v8, 0
	v_bcnt_u32_b32 v12, v9, v12
	s_nop 1
	v_add_u32_dpp v12, v12, v12 row_ror:8 row_mask:0xf bank_mask:0xf bound_ctrl:1
	s_nop 1
	v_add_u32_dpp v12, v12, v12 row_ror:4 row_mask:0xf bank_mask:0xf bound_ctrl:1
	s_nop 1
	v_add_u32_dpp v12, v12, v12 row_ror:2 row_mask:0xf bank_mask:0xf bound_ctrl:1
	s_nop 1
	v_add_u32_dpp v12, v12, v12 row_ror:1 row_mask:0xf bank_mask:0xf bound_ctrl:1
	s_nop 0
	v_readlane_b32 s6, v12, 0
	v_readlane_b32 s7, v12, 16
	v_readlane_b32 s8, v12, 32
	v_readlane_b32 s9, v12, 48
	s_add_i32 s6, s6, s7
	s_add_i32 s8, s8, s9
	s_add_i32 s6, s6, s57
	s_add_i32 s8, s6, s8
	s_cmpk_eq_i32 s8, 0x100
	s_cbranch_scc1 .Lrdx_eq
	s_cmpk_lt_i32 s8, 0x100
	s_cselect_b32 s6, -1, 0
	s_cselect_b32 s57, s8, s57
	v_bitop3_b32 v7, v7, v158, s6 bitop3:0x60
	v_bitop3_b32 v6, v6, v155, s6 bitop3:0x60
	v_bitop3_b32 v3, v3, v8, s6 bitop3:0xf8
	v_bitop3_b32 v2, v2, v9, s6 bitop3:0xf8
	v_and_b32_e32 v8, v7, v156
	v_and_b32_e32 v9, v6, v153
	v_bcnt_u32_b32 v12, v8, 0
	v_bcnt_u32_b32 v12, v9, v12
	s_nop 1
	v_add_u32_dpp v12, v12, v12 row_ror:8 row_mask:0xf bank_mask:0xf bound_ctrl:1
	s_nop 1
	v_add_u32_dpp v12, v12, v12 row_ror:4 row_mask:0xf bank_mask:0xf bound_ctrl:1
	s_nop 1
	v_add_u32_dpp v12, v12, v12 row_ror:2 row_mask:0xf bank_mask:0xf bound_ctrl:1
	s_nop 1
	v_add_u32_dpp v12, v12, v12 row_ror:1 row_mask:0xf bank_mask:0xf bound_ctrl:1
	s_nop 0
	v_readlane_b32 s6, v12, 0
	v_readlane_b32 s7, v12, 16
	v_readlane_b32 s8, v12, 32
	v_readlane_b32 s9, v12, 48
	s_add_i32 s6, s6, s7
	s_add_i32 s8, s8, s9
	s_add_i32 s6, s6, s57
	s_add_i32 s8, s6, s8
	s_cmpk_eq_i32 s8, 0x100
	s_cbranch_scc1 .Lrdx_eq
	s_cmpk_lt_i32 s8, 0x100
	s_cselect_b32 s6, -1, 0
	s_cselect_b32 s57, s8, s57
	v_bitop3_b32 v7, v7, v156, s6 bitop3:0x60
	v_bitop3_b32 v6, v6, v153, s6 bitop3:0x60
	v_bitop3_b32 v3, v3, v8, s6 bitop3:0xf8
	v_bitop3_b32 v2, v2, v9, s6 bitop3:0xf8
	v_and_b32_e32 v8, v7, v154
	v_and_b32_e32 v9, v6, v151
	v_bcnt_u32_b32 v12, v8, 0
	v_bcnt_u32_b32 v12, v9, v12
	s_nop 1
	v_add_u32_dpp v12, v12, v12 row_ror:8 row_mask:0xf bank_mask:0xf bound_ctrl:1
	s_nop 1
	v_add_u32_dpp v12, v12, v12 row_ror:4 row_mask:0xf bank_mask:0xf bound_ctrl:1
	s_nop 1
	v_add_u32_dpp v12, v12, v12 row_ror:2 row_mask:0xf bank_mask:0xf bound_ctrl:1
	s_nop 1
	v_add_u32_dpp v12, v12, v12 row_ror:1 row_mask:0xf bank_mask:0xf bound_ctrl:1
	s_nop 0
	v_readlane_b32 s6, v12, 0
	v_readlane_b32 s7, v12, 16
	v_readlane_b32 s8, v12, 32
	v_readlane_b32 s9, v12, 48
	s_add_i32 s6, s6, s7
	s_add_i32 s8, s8, s9
	s_add_i32 s6, s6, s57
	s_add_i32 s8, s6, s8
	s_cmpk_eq_i32 s8, 0x100
	s_cbranch_scc1 .Lrdx_eq
	s_cmpk_lt_i32 s8, 0x100
	s_cselect_b32 s6, -1, 0
	s_cselect_b32 s57, s8, s57
	v_bitop3_b32 v7, v7, v154, s6 bitop3:0x60
	v_bitop3_b32 v6, v6, v151, s6 bitop3:0x60
	v_bitop3_b32 v3, v3, v8, s6 bitop3:0xf8
	v_bitop3_b32 v2, v2, v9, s6 bitop3:0xf8
	v_and_b32_e32 v8, v7, v152
	v_and_b32_e32 v9, v6, v149
	v_bcnt_u32_b32 v12, v8, 0
	v_bcnt_u32_b32 v12, v9, v12
	s_nop 1
	v_add_u32_dpp v12, v12, v12 row_ror:8 row_mask:0xf bank_mask:0xf bound_ctrl:1
	s_nop 1
	v_add_u32_dpp v12, v12, v12 row_ror:4 row_mask:0xf bank_mask:0xf bound_ctrl:1
	s_nop 1
	v_add_u32_dpp v12, v12, v12 row_ror:2 row_mask:0xf bank_mask:0xf bound_ctrl:1
	s_nop 1
	v_add_u32_dpp v12, v12, v12 row_ror:1 row_mask:0xf bank_mask:0xf bound_ctrl:1
	s_nop 0
	v_readlane_b32 s6, v12, 0
	v_readlane_b32 s7, v12, 16
	v_readlane_b32 s8, v12, 32
	v_readlane_b32 s9, v12, 48
	s_add_i32 s6, s6, s7
	s_add_i32 s8, s8, s9
	s_add_i32 s6, s6, s57
	s_add_i32 s8, s6, s8
	s_cmpk_eq_i32 s8, 0x100
	s_cbranch_scc1 .Lrdx_eq
	s_cmpk_lt_i32 s8, 0x100
	s_cselect_b32 s6, -1, 0
	s_cselect_b32 s57, s8, s57
	v_bitop3_b32 v7, v7, v152, s6 bitop3:0x60
	v_bitop3_b32 v6, v6, v149, s6 bitop3:0x60
	v_bitop3_b32 v3, v3, v8, s6 bitop3:0xf8
	v_bitop3_b32 v2, v2, v9, s6 bitop3:0xf8
	v_and_b32_e32 v8, v7, v150
	v_and_b32_e32 v9, v6, v147
	v_bcnt_u32_b32 v12, v8, 0
	v_bcnt_u32_b32 v12, v9, v12
	s_nop 1
	v_add_u32_dpp v12, v12, v12 row_ror:8 row_mask:0xf bank_mask:0xf bound_ctrl:1
	s_nop 1
	v_add_u32_dpp v12, v12, v12 row_ror:4 row_mask:0xf bank_mask:0xf bound_ctrl:1
	s_nop 1
	v_add_u32_dpp v12, v12, v12 row_ror:2 row_mask:0xf bank_mask:0xf bound_ctrl:1
	s_nop 1
	v_add_u32_dpp v12, v12, v12 row_ror:1 row_mask:0xf bank_mask:0xf bound_ctrl:1
	s_nop 0
	v_readlane_b32 s6, v12, 0
	v_readlane_b32 s7, v12, 16
	v_readlane_b32 s8, v12, 32
	v_readlane_b32 s9, v12, 48
	s_add_i32 s6, s6, s7
	s_add_i32 s8, s8, s9
	s_add_i32 s6, s6, s57
	s_add_i32 s8, s6, s8
	s_cmpk_eq_i32 s8, 0x100
	s_cbranch_scc1 .Lrdx_eq
	s_cmpk_lt_i32 s8, 0x100
	s_cselect_b32 s6, -1, 0
	s_cselect_b32 s57, s8, s57
	v_bitop3_b32 v7, v7, v150, s6 bitop3:0x60
	v_bitop3_b32 v6, v6, v147, s6 bitop3:0x60
	v_bitop3_b32 v3, v3, v8, s6 bitop3:0xf8
	v_bitop3_b32 v2, v2, v9, s6 bitop3:0xf8
	v_and_b32_e32 v8, v7, v148
	v_and_b32_e32 v9, v6, v145
	v_bcnt_u32_b32 v12, v8, 0
	v_bcnt_u32_b32 v12, v9, v12
	s_nop 1
	v_add_u32_dpp v12, v12, v12 row_ror:8 row_mask:0xf bank_mask:0xf bound_ctrl:1
	s_nop 1
	v_add_u32_dpp v12, v12, v12 row_ror:4 row_mask:0xf bank_mask:0xf bound_ctrl:1
	s_nop 1
	v_add_u32_dpp v12, v12, v12 row_ror:2 row_mask:0xf bank_mask:0xf bound_ctrl:1
	s_nop 1
	v_add_u32_dpp v12, v12, v12 row_ror:1 row_mask:0xf bank_mask:0xf bound_ctrl:1
	s_nop 0
	v_readlane_b32 s6, v12, 0
	v_readlane_b32 s7, v12, 16
	v_readlane_b32 s8, v12, 32
	v_readlane_b32 s9, v12, 48
	s_add_i32 s6, s6, s7
	s_add_i32 s8, s8, s9
	s_add_i32 s6, s6, s57
	s_add_i32 s8, s6, s8
	s_cmpk_eq_i32 s8, 0x100
	s_cbranch_scc1 .Lrdx_eq
	s_cmpk_lt_i32 s8, 0x100
	s_cselect_b32 s6, -1, 0
	s_cselect_b32 s57, s8, s57
	v_bitop3_b32 v7, v7, v148, s6 bitop3:0x60
	v_bitop3_b32 v6, v6, v145, s6 bitop3:0x60
	v_bitop3_b32 v3, v3, v8, s6 bitop3:0xf8
	v_bitop3_b32 v2, v2, v9, s6 bitop3:0xf8
	v_and_b32_e32 v8, v7, v146
	v_and_b32_e32 v9, v6, v143
	v_bcnt_u32_b32 v12, v8, 0
	v_bcnt_u32_b32 v12, v9, v12
	s_nop 1
	v_add_u32_dpp v12, v12, v12 row_ror:8 row_mask:0xf bank_mask:0xf bound_ctrl:1
	s_nop 1
	v_add_u32_dpp v12, v12, v12 row_ror:4 row_mask:0xf bank_mask:0xf bound_ctrl:1
	s_nop 1
	v_add_u32_dpp v12, v12, v12 row_ror:2 row_mask:0xf bank_mask:0xf bound_ctrl:1
	s_nop 1
	v_add_u32_dpp v12, v12, v12 row_ror:1 row_mask:0xf bank_mask:0xf bound_ctrl:1
	s_nop 0
	v_readlane_b32 s6, v12, 0
	v_readlane_b32 s7, v12, 16
	v_readlane_b32 s8, v12, 32
	v_readlane_b32 s9, v12, 48
	s_add_i32 s6, s6, s7
	s_add_i32 s8, s8, s9
	s_add_i32 s6, s6, s57
	s_add_i32 s8, s6, s8
	s_cmpk_eq_i32 s8, 0x100
	s_cbranch_scc1 .Lrdx_eq
	s_cmpk_lt_i32 s8, 0x100
	s_cselect_b32 s6, -1, 0
	s_cselect_b32 s57, s8, s57
	v_bitop3_b32 v7, v7, v146, s6 bitop3:0x60
	v_bitop3_b32 v6, v6, v143, s6 bitop3:0x60
	v_bitop3_b32 v3, v3, v8, s6 bitop3:0xf8
	v_bitop3_b32 v2, v2, v9, s6 bitop3:0xf8
	v_and_b32_e32 v8, v7, v144
	v_and_b32_e32 v9, v6, v141
	v_bcnt_u32_b32 v12, v8, 0
	v_bcnt_u32_b32 v12, v9, v12
	s_nop 1
	v_add_u32_dpp v12, v12, v12 row_ror:8 row_mask:0xf bank_mask:0xf bound_ctrl:1
	s_nop 1
	v_add_u32_dpp v12, v12, v12 row_ror:4 row_mask:0xf bank_mask:0xf bound_ctrl:1
	s_nop 1
	v_add_u32_dpp v12, v12, v12 row_ror:2 row_mask:0xf bank_mask:0xf bound_ctrl:1
	s_nop 1
	v_add_u32_dpp v12, v12, v12 row_ror:1 row_mask:0xf bank_mask:0xf bound_ctrl:1
	s_nop 0
	v_readlane_b32 s6, v12, 0
	v_readlane_b32 s7, v12, 16
	v_readlane_b32 s8, v12, 32
	v_readlane_b32 s9, v12, 48
	s_add_i32 s6, s6, s7
	s_add_i32 s8, s8, s9
	s_add_i32 s6, s6, s57
	s_add_i32 s8, s6, s8
	s_cmpk_eq_i32 s8, 0x100
	s_cbranch_scc1 .Lrdx_eq
	s_cmpk_lt_i32 s8, 0x100
	s_cselect_b32 s6, -1, 0
	s_cselect_b32 s57, s8, s57
	v_bitop3_b32 v7, v7, v144, s6 bitop3:0x60
	v_bitop3_b32 v6, v6, v141, s6 bitop3:0x60
	v_bitop3_b32 v3, v3, v8, s6 bitop3:0xf8
	v_bitop3_b32 v2, v2, v9, s6 bitop3:0xf8
	v_and_b32_e32 v8, v7, v142
	v_and_b32_e32 v9, v6, v139
	v_bcnt_u32_b32 v12, v8, 0
	v_bcnt_u32_b32 v12, v9, v12
	s_nop 1
	v_add_u32_dpp v12, v12, v12 row_ror:8 row_mask:0xf bank_mask:0xf bound_ctrl:1
	s_nop 1
	v_add_u32_dpp v12, v12, v12 row_ror:4 row_mask:0xf bank_mask:0xf bound_ctrl:1
	s_nop 1
	v_add_u32_dpp v12, v12, v12 row_ror:2 row_mask:0xf bank_mask:0xf bound_ctrl:1
	s_nop 1
	v_add_u32_dpp v12, v12, v12 row_ror:1 row_mask:0xf bank_mask:0xf bound_ctrl:1
	s_nop 0
	v_readlane_b32 s6, v12, 0
	v_readlane_b32 s7, v12, 16
	v_readlane_b32 s8, v12, 32
	v_readlane_b32 s9, v12, 48
	s_add_i32 s6, s6, s7
	s_add_i32 s8, s8, s9
	s_add_i32 s6, s6, s57
	s_add_i32 s8, s6, s8
	s_cmpk_eq_i32 s8, 0x100
	s_cbranch_scc1 .Lrdx_eq
	s_cmpk_lt_i32 s8, 0x100
	s_cselect_b32 s6, -1, 0
	s_cselect_b32 s57, s8, s57
	v_bitop3_b32 v7, v7, v142, s6 bitop3:0x60
	v_bitop3_b32 v6, v6, v139, s6 bitop3:0x60
	v_bitop3_b32 v3, v3, v8, s6 bitop3:0xf8
	v_bitop3_b32 v2, v2, v9, s6 bitop3:0xf8
	v_and_b32_e32 v8, v7, v140
	v_and_b32_e32 v9, v6, v137
	v_bcnt_u32_b32 v12, v8, 0
	v_bcnt_u32_b32 v12, v9, v12
	s_nop 1
	v_add_u32_dpp v12, v12, v12 row_ror:8 row_mask:0xf bank_mask:0xf bound_ctrl:1
	s_nop 1
	v_add_u32_dpp v12, v12, v12 row_ror:4 row_mask:0xf bank_mask:0xf bound_ctrl:1
	s_nop 1
	v_add_u32_dpp v12, v12, v12 row_ror:2 row_mask:0xf bank_mask:0xf bound_ctrl:1
	s_nop 1
	v_add_u32_dpp v12, v12, v12 row_ror:1 row_mask:0xf bank_mask:0xf bound_ctrl:1
	s_nop 0
	v_readlane_b32 s6, v12, 0
	v_readlane_b32 s7, v12, 16
	v_readlane_b32 s8, v12, 32
	v_readlane_b32 s9, v12, 48
	s_add_i32 s6, s6, s7
	s_add_i32 s8, s8, s9
	s_add_i32 s6, s6, s57
	s_add_i32 s8, s6, s8
	s_cmpk_eq_i32 s8, 0x100
	s_cbranch_scc1 .Lrdx_eq
	s_cmpk_lt_i32 s8, 0x100
	s_cselect_b32 s6, -1, 0
	s_cselect_b32 s57, s8, s57
	v_bitop3_b32 v7, v7, v140, s6 bitop3:0x60
	v_bitop3_b32 v6, v6, v137, s6 bitop3:0x60
	v_bitop3_b32 v3, v3, v8, s6 bitop3:0xf8
	v_bitop3_b32 v2, v2, v9, s6 bitop3:0xf8
	v_and_b32_e32 v8, v7, v138
	v_and_b32_e32 v9, v6, v135
	v_bcnt_u32_b32 v12, v8, 0
	v_bcnt_u32_b32 v12, v9, v12
	s_nop 1
	v_add_u32_dpp v12, v12, v12 row_ror:8 row_mask:0xf bank_mask:0xf bound_ctrl:1
	s_nop 1
	v_add_u32_dpp v12, v12, v12 row_ror:4 row_mask:0xf bank_mask:0xf bound_ctrl:1
	s_nop 1
	v_add_u32_dpp v12, v12, v12 row_ror:2 row_mask:0xf bank_mask:0xf bound_ctrl:1
	s_nop 1
	v_add_u32_dpp v12, v12, v12 row_ror:1 row_mask:0xf bank_mask:0xf bound_ctrl:1
	s_nop 0
	v_readlane_b32 s6, v12, 0
	v_readlane_b32 s7, v12, 16
	v_readlane_b32 s8, v12, 32
	v_readlane_b32 s9, v12, 48
	s_add_i32 s6, s6, s7
	s_add_i32 s8, s8, s9
	s_add_i32 s6, s6, s57
	s_add_i32 s8, s6, s8
	s_cmpk_eq_i32 s8, 0x100
	s_cbranch_scc1 .Lrdx_eq
	s_cmpk_lt_i32 s8, 0x100
	s_cselect_b32 s6, -1, 0
	s_cselect_b32 s57, s8, s57
	v_bitop3_b32 v7, v7, v138, s6 bitop3:0x60
	v_bitop3_b32 v6, v6, v135, s6 bitop3:0x60
	v_bitop3_b32 v3, v3, v8, s6 bitop3:0xf8
	v_bitop3_b32 v2, v2, v9, s6 bitop3:0xf8
	v_and_b32_e32 v8, v7, v136
	v_and_b32_e32 v9, v6, v133
	v_bcnt_u32_b32 v12, v8, 0
	v_bcnt_u32_b32 v12, v9, v12
	s_nop 1
	v_add_u32_dpp v12, v12, v12 row_ror:8 row_mask:0xf bank_mask:0xf bound_ctrl:1
	s_nop 1
	v_add_u32_dpp v12, v12, v12 row_ror:4 row_mask:0xf bank_mask:0xf bound_ctrl:1
	s_nop 1
	v_add_u32_dpp v12, v12, v12 row_ror:2 row_mask:0xf bank_mask:0xf bound_ctrl:1
	s_nop 1
	v_add_u32_dpp v12, v12, v12 row_ror:1 row_mask:0xf bank_mask:0xf bound_ctrl:1
	s_nop 0
	v_readlane_b32 s6, v12, 0
	v_readlane_b32 s7, v12, 16
	v_readlane_b32 s8, v12, 32
	v_readlane_b32 s9, v12, 48
	s_add_i32 s6, s6, s7
	s_add_i32 s8, s8, s9
	s_add_i32 s6, s6, s57
	s_add_i32 s8, s6, s8
	s_cmpk_eq_i32 s8, 0x100
	s_cbranch_scc1 .Lrdx_eq
	s_cmpk_lt_i32 s8, 0x100
	s_cselect_b32 s6, -1, 0
	s_cselect_b32 s57, s8, s57
	v_bitop3_b32 v7, v7, v136, s6 bitop3:0x60
	v_bitop3_b32 v6, v6, v133, s6 bitop3:0x60
	v_bitop3_b32 v3, v3, v8, s6 bitop3:0xf8
	v_bitop3_b32 v2, v2, v9, s6 bitop3:0xf8
	v_and_b32_e32 v8, v7, v134
	v_and_b32_e32 v9, v6, v131
	v_bcnt_u32_b32 v12, v8, 0
	v_bcnt_u32_b32 v12, v9, v12
	s_nop 1
	v_add_u32_dpp v12, v12, v12 row_ror:8 row_mask:0xf bank_mask:0xf bound_ctrl:1
	s_nop 1
	v_add_u32_dpp v12, v12, v12 row_ror:4 row_mask:0xf bank_mask:0xf bound_ctrl:1
	s_nop 1
	v_add_u32_dpp v12, v12, v12 row_ror:2 row_mask:0xf bank_mask:0xf bound_ctrl:1
	s_nop 1
	v_add_u32_dpp v12, v12, v12 row_ror:1 row_mask:0xf bank_mask:0xf bound_ctrl:1
	s_nop 0
	v_readlane_b32 s6, v12, 0
	v_readlane_b32 s7, v12, 16
	v_readlane_b32 s8, v12, 32
	v_readlane_b32 s9, v12, 48
	s_add_i32 s6, s6, s7
	s_add_i32 s8, s8, s9
	s_add_i32 s6, s6, s57
	s_add_i32 s8, s6, s8
	s_cmpk_eq_i32 s8, 0x100
	s_cbranch_scc1 .Lrdx_eq
	s_cmpk_lt_i32 s8, 0x100
	s_cselect_b32 s6, -1, 0
	s_cselect_b32 s57, s8, s57
	v_bitop3_b32 v7, v7, v134, s6 bitop3:0x60
	v_bitop3_b32 v6, v6, v131, s6 bitop3:0x60
	v_bitop3_b32 v3, v3, v8, s6 bitop3:0xf8
	v_bitop3_b32 v2, v2, v9, s6 bitop3:0xf8
	v_and_b32_e32 v8, v7, v132
	v_and_b32_e32 v9, v6, v129
	v_bcnt_u32_b32 v12, v8, 0
	v_bcnt_u32_b32 v12, v9, v12
	s_nop 1
	v_add_u32_dpp v12, v12, v12 row_ror:8 row_mask:0xf bank_mask:0xf bound_ctrl:1
	s_nop 1
	v_add_u32_dpp v12, v12, v12 row_ror:4 row_mask:0xf bank_mask:0xf bound_ctrl:1
	s_nop 1
	v_add_u32_dpp v12, v12, v12 row_ror:2 row_mask:0xf bank_mask:0xf bound_ctrl:1
	s_nop 1
	v_add_u32_dpp v12, v12, v12 row_ror:1 row_mask:0xf bank_mask:0xf bound_ctrl:1
	s_nop 0
	v_readlane_b32 s6, v12, 0
	v_readlane_b32 s7, v12, 16
	v_readlane_b32 s8, v12, 32
	v_readlane_b32 s9, v12, 48
	s_add_i32 s6, s6, s7
	s_add_i32 s8, s8, s9
	s_add_i32 s6, s6, s57
	s_add_i32 s8, s6, s8
	s_cmpk_eq_i32 s8, 0x100
	s_cbranch_scc1 .Lrdx_eq
	s_cmpk_lt_i32 s8, 0x100
	s_cselect_b32 s6, -1, 0
	s_cselect_b32 s57, s8, s57
	v_bitop3_b32 v7, v7, v132, s6 bitop3:0x60
	v_bitop3_b32 v6, v6, v129, s6 bitop3:0x60
	v_bitop3_b32 v3, v3, v8, s6 bitop3:0xf8
	v_bitop3_b32 v2, v2, v9, s6 bitop3:0xf8
	v_and_b32_e32 v8, v7, v130
	v_and_b32_e32 v9, v6, v127
	v_bcnt_u32_b32 v12, v8, 0
	v_bcnt_u32_b32 v12, v9, v12
	s_nop 1
	v_add_u32_dpp v12, v12, v12 row_ror:8 row_mask:0xf bank_mask:0xf bound_ctrl:1
	s_nop 1
	v_add_u32_dpp v12, v12, v12 row_ror:4 row_mask:0xf bank_mask:0xf bound_ctrl:1
	s_nop 1
	v_add_u32_dpp v12, v12, v12 row_ror:2 row_mask:0xf bank_mask:0xf bound_ctrl:1
	s_nop 1
	v_add_u32_dpp v12, v12, v12 row_ror:1 row_mask:0xf bank_mask:0xf bound_ctrl:1
	s_nop 0
	v_readlane_b32 s6, v12, 0
	v_readlane_b32 s7, v12, 16
	v_readlane_b32 s8, v12, 32
	v_readlane_b32 s9, v12, 48
	s_add_i32 s6, s6, s7
	s_add_i32 s8, s8, s9
	s_add_i32 s6, s6, s57
	s_add_i32 s8, s6, s8
	s_cmpk_eq_i32 s8, 0x100
	s_cbranch_scc1 .Lrdx_eq
	s_cmpk_lt_i32 s8, 0x100
	s_cselect_b32 s6, -1, 0
	s_cselect_b32 s57, s8, s57
	v_bitop3_b32 v7, v7, v130, s6 bitop3:0x60
	v_bitop3_b32 v6, v6, v127, s6 bitop3:0x60
	v_bitop3_b32 v3, v3, v8, s6 bitop3:0xf8
	v_bitop3_b32 v2, v2, v9, s6 bitop3:0xf8
	v_and_b32_e32 v8, v7, v128
	v_and_b32_e32 v9, v6, v125
	v_bcnt_u32_b32 v12, v8, 0
	v_bcnt_u32_b32 v12, v9, v12
	s_nop 1
	v_add_u32_dpp v12, v12, v12 row_ror:8 row_mask:0xf bank_mask:0xf bound_ctrl:1
	s_nop 1
	v_add_u32_dpp v12, v12, v12 row_ror:4 row_mask:0xf bank_mask:0xf bound_ctrl:1
	s_nop 1
	v_add_u32_dpp v12, v12, v12 row_ror:2 row_mask:0xf bank_mask:0xf bound_ctrl:1
	s_nop 1
	v_add_u32_dpp v12, v12, v12 row_ror:1 row_mask:0xf bank_mask:0xf bound_ctrl:1
	s_nop 0
	v_readlane_b32 s6, v12, 0
	v_readlane_b32 s7, v12, 16
	v_readlane_b32 s8, v12, 32
	v_readlane_b32 s9, v12, 48
	s_add_i32 s6, s6, s7
	s_add_i32 s8, s8, s9
	s_add_i32 s6, s6, s57
	s_add_i32 s8, s6, s8
	s_cmpk_eq_i32 s8, 0x100
	s_cbranch_scc1 .Lrdx_eq
	s_cmpk_lt_i32 s8, 0x100
	s_cselect_b32 s6, -1, 0
	s_cselect_b32 s57, s8, s57
	v_bitop3_b32 v7, v7, v128, s6 bitop3:0x60
	v_bitop3_b32 v6, v6, v125, s6 bitop3:0x60
	v_bitop3_b32 v3, v3, v8, s6 bitop3:0xf8
	v_bitop3_b32 v2, v2, v9, s6 bitop3:0xf8
	v_and_b32_e32 v8, v7, v126
	v_and_b32_e32 v9, v6, v123
	v_bcnt_u32_b32 v12, v8, 0
	v_bcnt_u32_b32 v12, v9, v12
	s_nop 1
	v_add_u32_dpp v12, v12, v12 row_ror:8 row_mask:0xf bank_mask:0xf bound_ctrl:1
	s_nop 1
	v_add_u32_dpp v12, v12, v12 row_ror:4 row_mask:0xf bank_mask:0xf bound_ctrl:1
	s_nop 1
	v_add_u32_dpp v12, v12, v12 row_ror:2 row_mask:0xf bank_mask:0xf bound_ctrl:1
	s_nop 1
	v_add_u32_dpp v12, v12, v12 row_ror:1 row_mask:0xf bank_mask:0xf bound_ctrl:1
	s_nop 0
	v_readlane_b32 s6, v12, 0
	v_readlane_b32 s7, v12, 16
	v_readlane_b32 s8, v12, 32
	v_readlane_b32 s9, v12, 48
	s_add_i32 s6, s6, s7
	s_add_i32 s8, s8, s9
	s_add_i32 s6, s6, s57
	s_add_i32 s8, s6, s8
	s_cmpk_eq_i32 s8, 0x100
	s_cbranch_scc1 .Lrdx_eq
	s_cmpk_lt_i32 s8, 0x100
	s_cselect_b32 s6, -1, 0
	s_cselect_b32 s57, s8, s57
	v_bitop3_b32 v7, v7, v126, s6 bitop3:0x60
	v_bitop3_b32 v6, v6, v123, s6 bitop3:0x60
	v_bitop3_b32 v3, v3, v8, s6 bitop3:0xf8
	v_bitop3_b32 v2, v2, v9, s6 bitop3:0xf8
	v_and_b32_e32 v8, v7, v124
	v_and_b32_e32 v9, v6, v121
	v_bcnt_u32_b32 v12, v8, 0
	v_bcnt_u32_b32 v12, v9, v12
	s_nop 1
	v_add_u32_dpp v12, v12, v12 row_ror:8 row_mask:0xf bank_mask:0xf bound_ctrl:1
	s_nop 1
	v_add_u32_dpp v12, v12, v12 row_ror:4 row_mask:0xf bank_mask:0xf bound_ctrl:1
	s_nop 1
	v_add_u32_dpp v12, v12, v12 row_ror:2 row_mask:0xf bank_mask:0xf bound_ctrl:1
	s_nop 1
	v_add_u32_dpp v12, v12, v12 row_ror:1 row_mask:0xf bank_mask:0xf bound_ctrl:1
	s_nop 0
	v_readlane_b32 s6, v12, 0
	v_readlane_b32 s7, v12, 16
	v_readlane_b32 s8, v12, 32
	v_readlane_b32 s9, v12, 48
	s_add_i32 s6, s6, s7
	s_add_i32 s8, s8, s9
	s_add_i32 s6, s6, s57
	s_add_i32 s8, s6, s8
	s_cmpk_eq_i32 s8, 0x100
	s_cbranch_scc1 .Lrdx_eq
	s_cmpk_lt_i32 s8, 0x100
	s_cselect_b32 s6, -1, 0
	s_cselect_b32 s57, s8, s57
	v_bitop3_b32 v7, v7, v124, s6 bitop3:0x60
	v_bitop3_b32 v6, v6, v121, s6 bitop3:0x60
	v_bitop3_b32 v3, v3, v8, s6 bitop3:0xf8
	v_bitop3_b32 v2, v2, v9, s6 bitop3:0xf8
	v_and_b32_e32 v8, v7, v122
	v_and_b32_e32 v9, v6, v119
	v_bcnt_u32_b32 v12, v8, 0
	v_bcnt_u32_b32 v12, v9, v12
	s_nop 1
	v_add_u32_dpp v12, v12, v12 row_ror:8 row_mask:0xf bank_mask:0xf bound_ctrl:1
	s_nop 1
	v_add_u32_dpp v12, v12, v12 row_ror:4 row_mask:0xf bank_mask:0xf bound_ctrl:1
	s_nop 1
	v_add_u32_dpp v12, v12, v12 row_ror:2 row_mask:0xf bank_mask:0xf bound_ctrl:1
	s_nop 1
	v_add_u32_dpp v12, v12, v12 row_ror:1 row_mask:0xf bank_mask:0xf bound_ctrl:1
	s_nop 0
	v_readlane_b32 s6, v12, 0
	v_readlane_b32 s7, v12, 16
	v_readlane_b32 s8, v12, 32
	v_readlane_b32 s9, v12, 48
	s_add_i32 s6, s6, s7
	s_add_i32 s8, s8, s9
	s_add_i32 s6, s6, s57
	s_add_i32 s8, s6, s8
	s_cmpk_eq_i32 s8, 0x100
	s_cbranch_scc1 .Lrdx_eq
	s_cmpk_lt_i32 s8, 0x100
	s_cselect_b32 s6, -1, 0
	s_cselect_b32 s57, s8, s57
	v_bitop3_b32 v7, v7, v122, s6 bitop3:0x60
	v_bitop3_b32 v6, v6, v119, s6 bitop3:0x60
	v_bitop3_b32 v3, v3, v8, s6 bitop3:0xf8
	v_bitop3_b32 v2, v2, v9, s6 bitop3:0xf8
	v_and_b32_e32 v8, v7, v120
	v_and_b32_e32 v9, v6, v117
	v_bcnt_u32_b32 v12, v8, 0
	v_bcnt_u32_b32 v12, v9, v12
	s_nop 1
	v_add_u32_dpp v12, v12, v12 row_ror:8 row_mask:0xf bank_mask:0xf bound_ctrl:1
	s_nop 1
	v_add_u32_dpp v12, v12, v12 row_ror:4 row_mask:0xf bank_mask:0xf bound_ctrl:1
	s_nop 1
	v_add_u32_dpp v12, v12, v12 row_ror:2 row_mask:0xf bank_mask:0xf bound_ctrl:1
	s_nop 1
	v_add_u32_dpp v12, v12, v12 row_ror:1 row_mask:0xf bank_mask:0xf bound_ctrl:1
	s_nop 0
	v_readlane_b32 s6, v12, 0
	v_readlane_b32 s7, v12, 16
	v_readlane_b32 s8, v12, 32
	v_readlane_b32 s9, v12, 48
	s_add_i32 s6, s6, s7
	s_add_i32 s8, s8, s9
	s_add_i32 s6, s6, s57
	s_add_i32 s8, s6, s8
	s_cmpk_eq_i32 s8, 0x100
	s_cbranch_scc1 .Lrdx_eq
	s_cmpk_lt_i32 s8, 0x100
	s_cselect_b32 s6, -1, 0
	s_cselect_b32 s57, s8, s57
	v_bitop3_b32 v7, v7, v120, s6 bitop3:0x60
	v_bitop3_b32 v6, v6, v117, s6 bitop3:0x60
	v_bitop3_b32 v3, v3, v8, s6 bitop3:0xf8
	v_bitop3_b32 v2, v2, v9, s6 bitop3:0xf8
	v_and_b32_e32 v8, v7, v118
	v_and_b32_e32 v9, v6, v115
	v_bcnt_u32_b32 v12, v8, 0
	v_bcnt_u32_b32 v12, v9, v12
	s_nop 1
	v_add_u32_dpp v12, v12, v12 row_ror:8 row_mask:0xf bank_mask:0xf bound_ctrl:1
	s_nop 1
	v_add_u32_dpp v12, v12, v12 row_ror:4 row_mask:0xf bank_mask:0xf bound_ctrl:1
	s_nop 1
	v_add_u32_dpp v12, v12, v12 row_ror:2 row_mask:0xf bank_mask:0xf bound_ctrl:1
	s_nop 1
	v_add_u32_dpp v12, v12, v12 row_ror:1 row_mask:0xf bank_mask:0xf bound_ctrl:1
	s_nop 0
	v_readlane_b32 s6, v12, 0
	v_readlane_b32 s7, v12, 16
	v_readlane_b32 s8, v12, 32
	v_readlane_b32 s9, v12, 48
	s_add_i32 s6, s6, s7
	s_add_i32 s8, s8, s9
	s_add_i32 s6, s6, s57
	s_add_i32 s8, s6, s8
	s_cmpk_eq_i32 s8, 0x100
	s_cbranch_scc1 .Lrdx_eq
	s_cmpk_lt_i32 s8, 0x100
	s_cselect_b32 s6, -1, 0
	s_cselect_b32 s57, s8, s57
	v_bitop3_b32 v7, v7, v118, s6 bitop3:0x60
	v_bitop3_b32 v6, v6, v115, s6 bitop3:0x60
	v_bitop3_b32 v3, v3, v8, s6 bitop3:0xf8
	v_bitop3_b32 v2, v2, v9, s6 bitop3:0xf8
	v_and_b32_e32 v8, v7, v116
	v_and_b32_e32 v9, v6, v113
	v_bcnt_u32_b32 v12, v8, 0
	v_bcnt_u32_b32 v12, v9, v12
	s_nop 1
	v_add_u32_dpp v12, v12, v12 row_ror:8 row_mask:0xf bank_mask:0xf bound_ctrl:1
	s_nop 1
	v_add_u32_dpp v12, v12, v12 row_ror:4 row_mask:0xf bank_mask:0xf bound_ctrl:1
	s_nop 1
	v_add_u32_dpp v12, v12, v12 row_ror:2 row_mask:0xf bank_mask:0xf bound_ctrl:1
	s_nop 1
	v_add_u32_dpp v12, v12, v12 row_ror:1 row_mask:0xf bank_mask:0xf bound_ctrl:1
	s_nop 0
	v_readlane_b32 s6, v12, 0
	v_readlane_b32 s7, v12, 16
	v_readlane_b32 s8, v12, 32
	v_readlane_b32 s9, v12, 48
	s_add_i32 s6, s6, s7
	s_add_i32 s8, s8, s9
	s_add_i32 s6, s6, s57
	s_add_i32 s8, s6, s8
	s_cmpk_eq_i32 s8, 0x100
	s_cbranch_scc1 .Lrdx_eq
	s_cmpk_lt_i32 s8, 0x100
	s_cselect_b32 s6, -1, 0
	s_cselect_b32 s57, s8, s57
	v_bitop3_b32 v7, v7, v116, s6 bitop3:0x60
	v_bitop3_b32 v6, v6, v113, s6 bitop3:0x60
	v_bitop3_b32 v3, v3, v8, s6 bitop3:0xf8
	v_bitop3_b32 v2, v2, v9, s6 bitop3:0xf8
	v_and_b32_e32 v8, v7, v114
	v_and_b32_e32 v9, v6, v111
	v_bcnt_u32_b32 v12, v8, 0
	v_bcnt_u32_b32 v12, v9, v12
	s_nop 1
	v_add_u32_dpp v12, v12, v12 row_ror:8 row_mask:0xf bank_mask:0xf bound_ctrl:1
	s_nop 1
	v_add_u32_dpp v12, v12, v12 row_ror:4 row_mask:0xf bank_mask:0xf bound_ctrl:1
	s_nop 1
	v_add_u32_dpp v12, v12, v12 row_ror:2 row_mask:0xf bank_mask:0xf bound_ctrl:1
	s_nop 1
	v_add_u32_dpp v12, v12, v12 row_ror:1 row_mask:0xf bank_mask:0xf bound_ctrl:1
	s_nop 0
	v_readlane_b32 s6, v12, 0
	v_readlane_b32 s7, v12, 16
	v_readlane_b32 s8, v12, 32
	v_readlane_b32 s9, v12, 48
	s_add_i32 s6, s6, s7
	s_add_i32 s8, s8, s9
	s_add_i32 s6, s6, s57
	s_add_i32 s8, s6, s8
	s_cmpk_eq_i32 s8, 0x100
	s_cbranch_scc1 .Lrdx_eq
	s_cmpk_lt_i32 s8, 0x100
	s_cselect_b32 s6, -1, 0
	s_cselect_b32 s57, s8, s57
	v_bitop3_b32 v7, v7, v114, s6 bitop3:0x60
	v_bitop3_b32 v6, v6, v111, s6 bitop3:0x60
	v_bitop3_b32 v3, v3, v8, s6 bitop3:0xf8
	v_bitop3_b32 v2, v2, v9, s6 bitop3:0xf8
	v_and_b32_e32 v8, v7, v112
	v_and_b32_e32 v9, v6, v109
	v_bcnt_u32_b32 v12, v8, 0
	v_bcnt_u32_b32 v12, v9, v12
	s_nop 1
	v_add_u32_dpp v12, v12, v12 row_ror:8 row_mask:0xf bank_mask:0xf bound_ctrl:1
	s_nop 1
	v_add_u32_dpp v12, v12, v12 row_ror:4 row_mask:0xf bank_mask:0xf bound_ctrl:1
	s_nop 1
	v_add_u32_dpp v12, v12, v12 row_ror:2 row_mask:0xf bank_mask:0xf bound_ctrl:1
	s_nop 1
	v_add_u32_dpp v12, v12, v12 row_ror:1 row_mask:0xf bank_mask:0xf bound_ctrl:1
	s_nop 0
	v_readlane_b32 s6, v12, 0
	v_readlane_b32 s7, v12, 16
	v_readlane_b32 s8, v12, 32
	v_readlane_b32 s9, v12, 48
	s_add_i32 s6, s6, s7
	s_add_i32 s8, s8, s9
	s_add_i32 s6, s6, s57
	s_add_i32 s8, s6, s8
	s_cmpk_eq_i32 s8, 0x100
	s_cbranch_scc1 .Lrdx_eq
	s_cmpk_lt_i32 s8, 0x100
	s_cselect_b32 s6, -1, 0
	s_cselect_b32 s57, s8, s57
	v_bitop3_b32 v7, v7, v112, s6 bitop3:0x60
	v_bitop3_b32 v6, v6, v109, s6 bitop3:0x60
	v_bitop3_b32 v3, v3, v8, s6 bitop3:0xf8
	v_bitop3_b32 v2, v2, v9, s6 bitop3:0xf8
	v_and_b32_e32 v8, v7, v110
	v_and_b32_e32 v9, v6, v107
	v_bcnt_u32_b32 v12, v8, 0
	v_bcnt_u32_b32 v12, v9, v12
	s_nop 1
	v_add_u32_dpp v12, v12, v12 row_ror:8 row_mask:0xf bank_mask:0xf bound_ctrl:1
	s_nop 1
	v_add_u32_dpp v12, v12, v12 row_ror:4 row_mask:0xf bank_mask:0xf bound_ctrl:1
	s_nop 1
	v_add_u32_dpp v12, v12, v12 row_ror:2 row_mask:0xf bank_mask:0xf bound_ctrl:1
	s_nop 1
	v_add_u32_dpp v12, v12, v12 row_ror:1 row_mask:0xf bank_mask:0xf bound_ctrl:1
	s_nop 0
	v_readlane_b32 s6, v12, 0
	v_readlane_b32 s7, v12, 16
	v_readlane_b32 s8, v12, 32
	v_readlane_b32 s9, v12, 48
	s_add_i32 s6, s6, s7
	s_add_i32 s8, s8, s9
	s_add_i32 s6, s6, s57
	s_add_i32 s8, s6, s8
	s_cmpk_eq_i32 s8, 0x100
	s_cbranch_scc1 .Lrdx_eq
	s_cmpk_lt_i32 s8, 0x100
	s_cselect_b32 s6, -1, 0
	s_cselect_b32 s57, s8, s57
	v_bitop3_b32 v7, v7, v110, s6 bitop3:0x60
	v_bitop3_b32 v6, v6, v107, s6 bitop3:0x60
	v_bitop3_b32 v3, v3, v8, s6 bitop3:0xf8
	v_bitop3_b32 v2, v2, v9, s6 bitop3:0xf8
	v_and_b32_e32 v8, v7, v108
	v_and_b32_e32 v9, v6, v106
	v_bcnt_u32_b32 v12, v8, 0
	v_bcnt_u32_b32 v12, v9, v12
	s_nop 1
	v_add_u32_dpp v12, v12, v12 row_ror:8 row_mask:0xf bank_mask:0xf bound_ctrl:1
	s_nop 1
	v_add_u32_dpp v12, v12, v12 row_ror:4 row_mask:0xf bank_mask:0xf bound_ctrl:1
	s_nop 1
	v_add_u32_dpp v12, v12, v12 row_ror:2 row_mask:0xf bank_mask:0xf bound_ctrl:1
	s_nop 1
	v_add_u32_dpp v12, v12, v12 row_ror:1 row_mask:0xf bank_mask:0xf bound_ctrl:1
	s_nop 0
	v_readlane_b32 s6, v12, 0
	v_readlane_b32 s7, v12, 16
	v_readlane_b32 s8, v12, 32
	v_readlane_b32 s9, v12, 48
	s_add_i32 s6, s6, s7
	s_add_i32 s8, s8, s9
	s_add_i32 s6, s6, s57
	s_add_i32 s8, s6, s8
	s_cmpk_eq_i32 s8, 0x100
	s_cbranch_scc1 .Lrdx_eq
	s_cmpk_lt_i32 s8, 0x100
	s_cselect_b32 s6, -1, 0
	s_cselect_b32 s57, s8, s57
	v_bitop3_b32 v7, v7, v108, s6 bitop3:0x60
	v_bitop3_b32 v6, v6, v106, s6 bitop3:0x60
	v_bitop3_b32 v3, v3, v8, s6 bitop3:0xf8
	v_bitop3_b32 v2, v2, v9, s6 bitop3:0xf8
	s_branch .LBB0_1099
.Lrdx_w3:
	v_mov_b32_e32 v11, 0
	v_and_b32_e32 v8, v7, v189
	v_and_b32_e32 v9, v6, v186
	v_bcnt_u32_b32 v12, v8, 0
	v_and_b32_e32 v10, v5, v95
	v_bcnt_u32_b32 v12, v9, v12
	v_bcnt_u32_b32 v12, v10, v12
	s_nop 1
	v_add_u32_dpp v12, v12, v12 row_ror:8 row_mask:0xf bank_mask:0xf bound_ctrl:1
	s_nop 1
	v_add_u32_dpp v12, v12, v12 row_ror:4 row_mask:0xf bank_mask:0xf bound_ctrl:1
	s_nop 1
	v_add_u32_dpp v12, v12, v12 row_ror:2 row_mask:0xf bank_mask:0xf bound_ctrl:1
	s_nop 1
	v_add_u32_dpp v12, v12, v12 row_ror:1 row_mask:0xf bank_mask:0xf bound_ctrl:1
	s_nop 0
	v_readlane_b32 s6, v12, 0
	v_readlane_b32 s7, v12, 16
	v_readlane_b32 s8, v12, 32
	v_readlane_b32 s9, v12, 48
	s_add_i32 s6, s6, s7
	s_add_i32 s8, s8, s9
	s_add_i32 s6, s6, s57
	s_add_i32 s8, s6, s8
	s_cmpk_eq_i32 s8, 0x100
	s_cbranch_scc1 .Lrdx_eq
	s_cmpk_lt_i32 s8, 0x100
	s_cselect_b32 s6, -1, 0
	s_cselect_b32 s57, s8, s57
	v_bitop3_b32 v7, v7, v189, s6 bitop3:0x60
	v_bitop3_b32 v6, v6, v186, s6 bitop3:0x60
	v_bitop3_b32 v5, v5, v95, s6 bitop3:0x60
	v_bitop3_b32 v3, v3, v8, s6 bitop3:0xf8
	v_bitop3_b32 v2, v2, v9, s6 bitop3:0xf8
	v_bitop3_b32 v1, v1, v10, s6 bitop3:0xf8
	v_and_b32_e32 v8, v7, v188
	v_and_b32_e32 v9, v6, v185
	v_bcnt_u32_b32 v12, v8, 0
	v_and_b32_e32 v10, v5, v94
	v_bcnt_u32_b32 v12, v9, v12
	v_bcnt_u32_b32 v12, v10, v12
	s_nop 1
	v_add_u32_dpp v12, v12, v12 row_ror:8 row_mask:0xf bank_mask:0xf bound_ctrl:1
	s_nop 1
	v_add_u32_dpp v12, v12, v12 row_ror:4 row_mask:0xf bank_mask:0xf bound_ctrl:1
	s_nop 1
	v_add_u32_dpp v12, v12, v12 row_ror:2 row_mask:0xf bank_mask:0xf bound_ctrl:1
	s_nop 1
	v_add_u32_dpp v12, v12, v12 row_ror:1 row_mask:0xf bank_mask:0xf bound_ctrl:1
	s_nop 0
	v_readlane_b32 s6, v12, 0
	v_readlane_b32 s7, v12, 16
	v_readlane_b32 s8, v12, 32
	v_readlane_b32 s9, v12, 48
	s_add_i32 s6, s6, s7
	s_add_i32 s8, s8, s9
	s_add_i32 s6, s6, s57
	s_add_i32 s8, s6, s8
	s_cmpk_eq_i32 s8, 0x100
	s_cbranch_scc1 .Lrdx_eq
	s_cmpk_lt_i32 s8, 0x100
	s_cselect_b32 s6, -1, 0
	s_cselect_b32 s57, s8, s57
	v_bitop3_b32 v7, v7, v188, s6 bitop3:0x60
	v_bitop3_b32 v6, v6, v185, s6 bitop3:0x60
	v_bitop3_b32 v5, v5, v94, s6 bitop3:0x60
	v_bitop3_b32 v3, v3, v8, s6 bitop3:0xf8
	v_bitop3_b32 v2, v2, v9, s6 bitop3:0xf8
	v_bitop3_b32 v1, v1, v10, s6 bitop3:0xf8
	v_and_b32_e32 v8, v7, v187
	v_and_b32_e32 v9, v6, v183
	v_bcnt_u32_b32 v12, v8, 0
	v_and_b32_e32 v10, v5, v93
	v_bcnt_u32_b32 v12, v9, v12
	v_bcnt_u32_b32 v12, v10, v12
	s_nop 1
	v_add_u32_dpp v12, v12, v12 row_ror:8 row_mask:0xf bank_mask:0xf bound_ctrl:1
	s_nop 1
	v_add_u32_dpp v12, v12, v12 row_ror:4 row_mask:0xf bank_mask:0xf bound_ctrl:1
	s_nop 1
	v_add_u32_dpp v12, v12, v12 row_ror:2 row_mask:0xf bank_mask:0xf bound_ctrl:1
	s_nop 1
	v_add_u32_dpp v12, v12, v12 row_ror:1 row_mask:0xf bank_mask:0xf bound_ctrl:1
	s_nop 0
	v_readlane_b32 s6, v12, 0
	v_readlane_b32 s7, v12, 16
	v_readlane_b32 s8, v12, 32
	v_readlane_b32 s9, v12, 48
	s_add_i32 s6, s6, s7
	s_add_i32 s8, s8, s9
	s_add_i32 s6, s6, s57
	s_add_i32 s8, s6, s8
	s_cmpk_eq_i32 s8, 0x100
	s_cbranch_scc1 .Lrdx_eq
	s_cmpk_lt_i32 s8, 0x100
	s_cselect_b32 s6, -1, 0
	s_cselect_b32 s57, s8, s57
	v_bitop3_b32 v7, v7, v187, s6 bitop3:0x60
	v_bitop3_b32 v6, v6, v183, s6 bitop3:0x60
	v_bitop3_b32 v5, v5, v93, s6 bitop3:0x60
	v_bitop3_b32 v3, v3, v8, s6 bitop3:0xf8
	v_bitop3_b32 v2, v2, v9, s6 bitop3:0xf8
	v_bitop3_b32 v1, v1, v10, s6 bitop3:0xf8
	v_and_b32_e32 v8, v7, v184
	v_and_b32_e32 v9, v6, v161
	v_bcnt_u32_b32 v12, v8, 0
	v_and_b32_e32 v10, v5, v91
	v_bcnt_u32_b32 v12, v9, v12
	v_bcnt_u32_b32 v12, v10, v12
	s_nop 1
	v_add_u32_dpp v12, v12, v12 row_ror:8 row_mask:0xf bank_mask:0xf bound_ctrl:1
	s_nop 1
	v_add_u32_dpp v12, v12, v12 row_ror:4 row_mask:0xf bank_mask:0xf bound_ctrl:1
	s_nop 1
	v_add_u32_dpp v12, v12, v12 row_ror:2 row_mask:0xf bank_mask:0xf bound_ctrl:1
	s_nop 1
	v_add_u32_dpp v12, v12, v12 row_ror:1 row_mask:0xf bank_mask:0xf bound_ctrl:1
	s_nop 0
	v_readlane_b32 s6, v12, 0
	v_readlane_b32 s7, v12, 16
	v_readlane_b32 s8, v12, 32
	v_readlane_b32 s9, v12, 48
	s_add_i32 s6, s6, s7
	s_add_i32 s8, s8, s9
	s_add_i32 s6, s6, s57
	s_add_i32 s8, s6, s8
	s_cmpk_eq_i32 s8, 0x100
	s_cbranch_scc1 .Lrdx_eq
	s_cmpk_lt_i32 s8, 0x100
	s_cselect_b32 s6, -1, 0
	s_cselect_b32 s57, s8, s57
	v_bitop3_b32 v7, v7, v184, s6 bitop3:0x60
	v_bitop3_b32 v6, v6, v161, s6 bitop3:0x60
	v_bitop3_b32 v5, v5, v91, s6 bitop3:0x60
	v_bitop3_b32 v3, v3, v8, s6 bitop3:0xf8
	v_bitop3_b32 v2, v2, v9, s6 bitop3:0xf8
	v_bitop3_b32 v1, v1, v10, s6 bitop3:0xf8
	v_and_b32_e32 v8, v7, v181
	v_and_b32_e32 v9, v6, v159
	v_bcnt_u32_b32 v12, v8, 0
	v_and_b32_e32 v10, v5, v89
	v_bcnt_u32_b32 v12, v9, v12
	v_bcnt_u32_b32 v12, v10, v12
	s_nop 1
	v_add_u32_dpp v12, v12, v12 row_ror:8 row_mask:0xf bank_mask:0xf bound_ctrl:1
	s_nop 1
	v_add_u32_dpp v12, v12, v12 row_ror:4 row_mask:0xf bank_mask:0xf bound_ctrl:1
	s_nop 1
	v_add_u32_dpp v12, v12, v12 row_ror:2 row_mask:0xf bank_mask:0xf bound_ctrl:1
	s_nop 1
	v_add_u32_dpp v12, v12, v12 row_ror:1 row_mask:0xf bank_mask:0xf bound_ctrl:1
	s_nop 0
	v_readlane_b32 s6, v12, 0
	v_readlane_b32 s7, v12, 16
	v_readlane_b32 s8, v12, 32
	v_readlane_b32 s9, v12, 48
	s_add_i32 s6, s6, s7
	s_add_i32 s8, s8, s9
	s_add_i32 s6, s6, s57
	s_add_i32 s8, s6, s8
	s_cmpk_eq_i32 s8, 0x100
	s_cbranch_scc1 .Lrdx_eq
	s_cmpk_lt_i32 s8, 0x100
	s_cselect_b32 s6, -1, 0
	s_cselect_b32 s57, s8, s57
	v_bitop3_b32 v7, v7, v181, s6 bitop3:0x60
	v_bitop3_b32 v6, v6, v159, s6 bitop3:0x60
	v_bitop3_b32 v5, v5, v89, s6 bitop3:0x60
	v_bitop3_b32 v3, v3, v8, s6 bitop3:0xf8
	v_bitop3_b32 v2, v2, v9, s6 bitop3:0xf8
	v_bitop3_b32 v1, v1, v10, s6 bitop3:0xf8
	v_and_b32_e32 v8, v7, v160
	v_and_b32_e32 v9, v6, v157
	v_bcnt_u32_b32 v12, v8, 0
	v_and_b32_e32 v10, v5, v87
	v_bcnt_u32_b32 v12, v9, v12
	v_bcnt_u32_b32 v12, v10, v12
	s_nop 1
	v_add_u32_dpp v12, v12, v12 row_ror:8 row_mask:0xf bank_mask:0xf bound_ctrl:1
	s_nop 1
	v_add_u32_dpp v12, v12, v12 row_ror:4 row_mask:0xf bank_mask:0xf bound_ctrl:1
	s_nop 1
	v_add_u32_dpp v12, v12, v12 row_ror:2 row_mask:0xf bank_mask:0xf bound_ctrl:1
	s_nop 1
	v_add_u32_dpp v12, v12, v12 row_ror:1 row_mask:0xf bank_mask:0xf bound_ctrl:1
	s_nop 0
	v_readlane_b32 s6, v12, 0
	v_readlane_b32 s7, v12, 16
	v_readlane_b32 s8, v12, 32
	v_readlane_b32 s9, v12, 48
	s_add_i32 s6, s6, s7
	s_add_i32 s8, s8, s9
	s_add_i32 s6, s6, s57
	s_add_i32 s8, s6, s8
	s_cmpk_eq_i32 s8, 0x100
	s_cbranch_scc1 .Lrdx_eq
	s_cmpk_lt_i32 s8, 0x100
	s_cselect_b32 s6, -1, 0
	s_cselect_b32 s57, s8, s57
	v_bitop3_b32 v7, v7, v160, s6 bitop3:0x60
	v_bitop3_b32 v6, v6, v157, s6 bitop3:0x60
	v_bitop3_b32 v5, v5, v87, s6 bitop3:0x60
	v_bitop3_b32 v3, v3, v8, s6 bitop3:0xf8
	v_bitop3_b32 v2, v2, v9, s6 bitop3:0xf8
	v_bitop3_b32 v1, v1, v10, s6 bitop3:0xf8
	v_and_b32_e32 v8, v7, v158
	v_and_b32_e32 v9, v6, v155
	v_bcnt_u32_b32 v12, v8, 0
	v_and_b32_e32 v10, v5, v85
	v_bcnt_u32_b32 v12, v9, v12
	v_bcnt_u32_b32 v12, v10, v12
	s_nop 1
	v_add_u32_dpp v12, v12, v12 row_ror:8 row_mask:0xf bank_mask:0xf bound_ctrl:1
	s_nop 1
	v_add_u32_dpp v12, v12, v12 row_ror:4 row_mask:0xf bank_mask:0xf bound_ctrl:1
	s_nop 1
	v_add_u32_dpp v12, v12, v12 row_ror:2 row_mask:0xf bank_mask:0xf bound_ctrl:1
	s_nop 1
	v_add_u32_dpp v12, v12, v12 row_ror:1 row_mask:0xf bank_mask:0xf bound_ctrl:1
	s_nop 0
	v_readlane_b32 s6, v12, 0
	v_readlane_b32 s7, v12, 16
	v_readlane_b32 s8, v12, 32
	v_readlane_b32 s9, v12, 48
	s_add_i32 s6, s6, s7
	s_add_i32 s8, s8, s9
	s_add_i32 s6, s6, s57
	s_add_i32 s8, s6, s8
	s_cmpk_eq_i32 s8, 0x100
	s_cbranch_scc1 .Lrdx_eq
	s_cmpk_lt_i32 s8, 0x100
	s_cselect_b32 s6, -1, 0
	s_cselect_b32 s57, s8, s57
	v_bitop3_b32 v7, v7, v158, s6 bitop3:0x60
	v_bitop3_b32 v6, v6, v155, s6 bitop3:0x60
	v_bitop3_b32 v5, v5, v85, s6 bitop3:0x60
	v_bitop3_b32 v3, v3, v8, s6 bitop3:0xf8
	v_bitop3_b32 v2, v2, v9, s6 bitop3:0xf8
	v_bitop3_b32 v1, v1, v10, s6 bitop3:0xf8
	v_and_b32_e32 v8, v7, v156
	v_and_b32_e32 v9, v6, v153
	v_bcnt_u32_b32 v12, v8, 0
	v_and_b32_e32 v10, v5, v83
	v_bcnt_u32_b32 v12, v9, v12
	v_bcnt_u32_b32 v12, v10, v12
	s_nop 1
	v_add_u32_dpp v12, v12, v12 row_ror:8 row_mask:0xf bank_mask:0xf bound_ctrl:1
	s_nop 1
	v_add_u32_dpp v12, v12, v12 row_ror:4 row_mask:0xf bank_mask:0xf bound_ctrl:1
	s_nop 1
	v_add_u32_dpp v12, v12, v12 row_ror:2 row_mask:0xf bank_mask:0xf bound_ctrl:1
	s_nop 1
	v_add_u32_dpp v12, v12, v12 row_ror:1 row_mask:0xf bank_mask:0xf bound_ctrl:1
	s_nop 0
	v_readlane_b32 s6, v12, 0
	v_readlane_b32 s7, v12, 16
	v_readlane_b32 s8, v12, 32
	v_readlane_b32 s9, v12, 48
	s_add_i32 s6, s6, s7
	s_add_i32 s8, s8, s9
	s_add_i32 s6, s6, s57
	s_add_i32 s8, s6, s8
	s_cmpk_eq_i32 s8, 0x100
	s_cbranch_scc1 .Lrdx_eq
	s_cmpk_lt_i32 s8, 0x100
	s_cselect_b32 s6, -1, 0
	s_cselect_b32 s57, s8, s57
	v_bitop3_b32 v7, v7, v156, s6 bitop3:0x60
	v_bitop3_b32 v6, v6, v153, s6 bitop3:0x60
	v_bitop3_b32 v5, v5, v83, s6 bitop3:0x60
	v_bitop3_b32 v3, v3, v8, s6 bitop3:0xf8
	v_bitop3_b32 v2, v2, v9, s6 bitop3:0xf8
	v_bitop3_b32 v1, v1, v10, s6 bitop3:0xf8
	v_and_b32_e32 v8, v7, v154
	v_and_b32_e32 v9, v6, v151
	v_bcnt_u32_b32 v12, v8, 0
	v_and_b32_e32 v10, v5, v81
	v_bcnt_u32_b32 v12, v9, v12
	v_bcnt_u32_b32 v12, v10, v12
	s_nop 1
	v_add_u32_dpp v12, v12, v12 row_ror:8 row_mask:0xf bank_mask:0xf bound_ctrl:1
	s_nop 1
	v_add_u32_dpp v12, v12, v12 row_ror:4 row_mask:0xf bank_mask:0xf bound_ctrl:1
	s_nop 1
	v_add_u32_dpp v12, v12, v12 row_ror:2 row_mask:0xf bank_mask:0xf bound_ctrl:1
	s_nop 1
	v_add_u32_dpp v12, v12, v12 row_ror:1 row_mask:0xf bank_mask:0xf bound_ctrl:1
	s_nop 0
	v_readlane_b32 s6, v12, 0
	v_readlane_b32 s7, v12, 16
	v_readlane_b32 s8, v12, 32
	v_readlane_b32 s9, v12, 48
	s_add_i32 s6, s6, s7
	s_add_i32 s8, s8, s9
	s_add_i32 s6, s6, s57
	s_add_i32 s8, s6, s8
	s_cmpk_eq_i32 s8, 0x100
	s_cbranch_scc1 .Lrdx_eq
	s_cmpk_lt_i32 s8, 0x100
	s_cselect_b32 s6, -1, 0
	s_cselect_b32 s57, s8, s57
	v_bitop3_b32 v7, v7, v154, s6 bitop3:0x60
	v_bitop3_b32 v6, v6, v151, s6 bitop3:0x60
	v_bitop3_b32 v5, v5, v81, s6 bitop3:0x60
	v_bitop3_b32 v3, v3, v8, s6 bitop3:0xf8
	v_bitop3_b32 v2, v2, v9, s6 bitop3:0xf8
	v_bitop3_b32 v1, v1, v10, s6 bitop3:0xf8
	v_and_b32_e32 v8, v7, v152
	v_and_b32_e32 v9, v6, v149
	v_bcnt_u32_b32 v12, v8, 0
	v_and_b32_e32 v10, v5, v79
	v_bcnt_u32_b32 v12, v9, v12
	v_bcnt_u32_b32 v12, v10, v12
	s_nop 1
	v_add_u32_dpp v12, v12, v12 row_ror:8 row_mask:0xf bank_mask:0xf bound_ctrl:1
	s_nop 1
	v_add_u32_dpp v12, v12, v12 row_ror:4 row_mask:0xf bank_mask:0xf bound_ctrl:1
	s_nop 1
	v_add_u32_dpp v12, v12, v12 row_ror:2 row_mask:0xf bank_mask:0xf bound_ctrl:1
	s_nop 1
	v_add_u32_dpp v12, v12, v12 row_ror:1 row_mask:0xf bank_mask:0xf bound_ctrl:1
	s_nop 0
	v_readlane_b32 s6, v12, 0
	v_readlane_b32 s7, v12, 16
	v_readlane_b32 s8, v12, 32
	v_readlane_b32 s9, v12, 48
	s_add_i32 s6, s6, s7
	s_add_i32 s8, s8, s9
	s_add_i32 s6, s6, s57
	s_add_i32 s8, s6, s8
	s_cmpk_eq_i32 s8, 0x100
	s_cbranch_scc1 .Lrdx_eq
	s_cmpk_lt_i32 s8, 0x100
	s_cselect_b32 s6, -1, 0
	s_cselect_b32 s57, s8, s57
	v_bitop3_b32 v7, v7, v152, s6 bitop3:0x60
	v_bitop3_b32 v6, v6, v149, s6 bitop3:0x60
	v_bitop3_b32 v5, v5, v79, s6 bitop3:0x60
	v_bitop3_b32 v3, v3, v8, s6 bitop3:0xf8
	v_bitop3_b32 v2, v2, v9, s6 bitop3:0xf8
	v_bitop3_b32 v1, v1, v10, s6 bitop3:0xf8
	v_and_b32_e32 v8, v7, v150
	v_and_b32_e32 v9, v6, v147
	v_bcnt_u32_b32 v12, v8, 0
	v_and_b32_e32 v10, v5, v77
	v_bcnt_u32_b32 v12, v9, v12
	v_bcnt_u32_b32 v12, v10, v12
	s_nop 1
	v_add_u32_dpp v12, v12, v12 row_ror:8 row_mask:0xf bank_mask:0xf bound_ctrl:1
	s_nop 1
	v_add_u32_dpp v12, v12, v12 row_ror:4 row_mask:0xf bank_mask:0xf bound_ctrl:1
	s_nop 1
	v_add_u32_dpp v12, v12, v12 row_ror:2 row_mask:0xf bank_mask:0xf bound_ctrl:1
	s_nop 1
	v_add_u32_dpp v12, v12, v12 row_ror:1 row_mask:0xf bank_mask:0xf bound_ctrl:1
	s_nop 0
	v_readlane_b32 s6, v12, 0
	v_readlane_b32 s7, v12, 16
	v_readlane_b32 s8, v12, 32
	v_readlane_b32 s9, v12, 48
	s_add_i32 s6, s6, s7
	s_add_i32 s8, s8, s9
	s_add_i32 s6, s6, s57
	s_add_i32 s8, s6, s8
	s_cmpk_eq_i32 s8, 0x100
	s_cbranch_scc1 .Lrdx_eq
	s_cmpk_lt_i32 s8, 0x100
	s_cselect_b32 s6, -1, 0
	s_cselect_b32 s57, s8, s57
	v_bitop3_b32 v7, v7, v150, s6 bitop3:0x60
	v_bitop3_b32 v6, v6, v147, s6 bitop3:0x60
	v_bitop3_b32 v5, v5, v77, s6 bitop3:0x60
	v_bitop3_b32 v3, v3, v8, s6 bitop3:0xf8
	v_bitop3_b32 v2, v2, v9, s6 bitop3:0xf8
	v_bitop3_b32 v1, v1, v10, s6 bitop3:0xf8
	v_and_b32_e32 v8, v7, v148
	v_and_b32_e32 v9, v6, v145
	v_bcnt_u32_b32 v12, v8, 0
	v_and_b32_e32 v10, v5, v75
	v_bcnt_u32_b32 v12, v9, v12
	v_bcnt_u32_b32 v12, v10, v12
	s_nop 1
	v_add_u32_dpp v12, v12, v12 row_ror:8 row_mask:0xf bank_mask:0xf bound_ctrl:1
	s_nop 1
	v_add_u32_dpp v12, v12, v12 row_ror:4 row_mask:0xf bank_mask:0xf bound_ctrl:1
	s_nop 1
	v_add_u32_dpp v12, v12, v12 row_ror:2 row_mask:0xf bank_mask:0xf bound_ctrl:1
	s_nop 1
	v_add_u32_dpp v12, v12, v12 row_ror:1 row_mask:0xf bank_mask:0xf bound_ctrl:1
	s_nop 0
	v_readlane_b32 s6, v12, 0
	v_readlane_b32 s7, v12, 16
	v_readlane_b32 s8, v12, 32
	v_readlane_b32 s9, v12, 48
	s_add_i32 s6, s6, s7
	s_add_i32 s8, s8, s9
	s_add_i32 s6, s6, s57
	s_add_i32 s8, s6, s8
	s_cmpk_eq_i32 s8, 0x100
	s_cbranch_scc1 .Lrdx_eq
	s_cmpk_lt_i32 s8, 0x100
	s_cselect_b32 s6, -1, 0
	s_cselect_b32 s57, s8, s57
	v_bitop3_b32 v7, v7, v148, s6 bitop3:0x60
	v_bitop3_b32 v6, v6, v145, s6 bitop3:0x60
	v_bitop3_b32 v5, v5, v75, s6 bitop3:0x60
	v_bitop3_b32 v3, v3, v8, s6 bitop3:0xf8
	v_bitop3_b32 v2, v2, v9, s6 bitop3:0xf8
	v_bitop3_b32 v1, v1, v10, s6 bitop3:0xf8
	v_and_b32_e32 v8, v7, v146
	v_and_b32_e32 v9, v6, v143
	v_bcnt_u32_b32 v12, v8, 0
	v_and_b32_e32 v10, v5, v73
	v_bcnt_u32_b32 v12, v9, v12
	v_bcnt_u32_b32 v12, v10, v12
	s_nop 1
	v_add_u32_dpp v12, v12, v12 row_ror:8 row_mask:0xf bank_mask:0xf bound_ctrl:1
	s_nop 1
	v_add_u32_dpp v12, v12, v12 row_ror:4 row_mask:0xf bank_mask:0xf bound_ctrl:1
	s_nop 1
	v_add_u32_dpp v12, v12, v12 row_ror:2 row_mask:0xf bank_mask:0xf bound_ctrl:1
	s_nop 1
	v_add_u32_dpp v12, v12, v12 row_ror:1 row_mask:0xf bank_mask:0xf bound_ctrl:1
	s_nop 0
	v_readlane_b32 s6, v12, 0
	v_readlane_b32 s7, v12, 16
	v_readlane_b32 s8, v12, 32
	v_readlane_b32 s9, v12, 48
	s_add_i32 s6, s6, s7
	s_add_i32 s8, s8, s9
	s_add_i32 s6, s6, s57
	s_add_i32 s8, s6, s8
	s_cmpk_eq_i32 s8, 0x100
	s_cbranch_scc1 .Lrdx_eq
	s_cmpk_lt_i32 s8, 0x100
	s_cselect_b32 s6, -1, 0
	s_cselect_b32 s57, s8, s57
	v_bitop3_b32 v7, v7, v146, s6 bitop3:0x60
	v_bitop3_b32 v6, v6, v143, s6 bitop3:0x60
	v_bitop3_b32 v5, v5, v73, s6 bitop3:0x60
	v_bitop3_b32 v3, v3, v8, s6 bitop3:0xf8
	v_bitop3_b32 v2, v2, v9, s6 bitop3:0xf8
	v_bitop3_b32 v1, v1, v10, s6 bitop3:0xf8
	v_and_b32_e32 v8, v7, v144
	v_and_b32_e32 v9, v6, v141
	v_bcnt_u32_b32 v12, v8, 0
	v_and_b32_e32 v10, v5, v71
	v_bcnt_u32_b32 v12, v9, v12
	v_bcnt_u32_b32 v12, v10, v12
	s_nop 1
	v_add_u32_dpp v12, v12, v12 row_ror:8 row_mask:0xf bank_mask:0xf bound_ctrl:1
	s_nop 1
	v_add_u32_dpp v12, v12, v12 row_ror:4 row_mask:0xf bank_mask:0xf bound_ctrl:1
	s_nop 1
	v_add_u32_dpp v12, v12, v12 row_ror:2 row_mask:0xf bank_mask:0xf bound_ctrl:1
	s_nop 1
	v_add_u32_dpp v12, v12, v12 row_ror:1 row_mask:0xf bank_mask:0xf bound_ctrl:1
	s_nop 0
	v_readlane_b32 s6, v12, 0
	v_readlane_b32 s7, v12, 16
	v_readlane_b32 s8, v12, 32
	v_readlane_b32 s9, v12, 48
	s_add_i32 s6, s6, s7
	s_add_i32 s8, s8, s9
	s_add_i32 s6, s6, s57
	s_add_i32 s8, s6, s8
	s_cmpk_eq_i32 s8, 0x100
	s_cbranch_scc1 .Lrdx_eq
	s_cmpk_lt_i32 s8, 0x100
	s_cselect_b32 s6, -1, 0
	s_cselect_b32 s57, s8, s57
	v_bitop3_b32 v7, v7, v144, s6 bitop3:0x60
	v_bitop3_b32 v6, v6, v141, s6 bitop3:0x60
	v_bitop3_b32 v5, v5, v71, s6 bitop3:0x60
	v_bitop3_b32 v3, v3, v8, s6 bitop3:0xf8
	v_bitop3_b32 v2, v2, v9, s6 bitop3:0xf8
	v_bitop3_b32 v1, v1, v10, s6 bitop3:0xf8
	v_and_b32_e32 v8, v7, v142
	v_and_b32_e32 v9, v6, v139
	v_bcnt_u32_b32 v12, v8, 0
	v_and_b32_e32 v10, v5, v69
	v_bcnt_u32_b32 v12, v9, v12
	v_bcnt_u32_b32 v12, v10, v12
	s_nop 1
	v_add_u32_dpp v12, v12, v12 row_ror:8 row_mask:0xf bank_mask:0xf bound_ctrl:1
	s_nop 1
	v_add_u32_dpp v12, v12, v12 row_ror:4 row_mask:0xf bank_mask:0xf bound_ctrl:1
	s_nop 1
	v_add_u32_dpp v12, v12, v12 row_ror:2 row_mask:0xf bank_mask:0xf bound_ctrl:1
	s_nop 1
	v_add_u32_dpp v12, v12, v12 row_ror:1 row_mask:0xf bank_mask:0xf bound_ctrl:1
	s_nop 0
	v_readlane_b32 s6, v12, 0
	v_readlane_b32 s7, v12, 16
	v_readlane_b32 s8, v12, 32
	v_readlane_b32 s9, v12, 48
	s_add_i32 s6, s6, s7
	s_add_i32 s8, s8, s9
	s_add_i32 s6, s6, s57
	s_add_i32 s8, s6, s8
	s_cmpk_eq_i32 s8, 0x100
	s_cbranch_scc1 .Lrdx_eq
	s_cmpk_lt_i32 s8, 0x100
	s_cselect_b32 s6, -1, 0
	s_cselect_b32 s57, s8, s57
	v_bitop3_b32 v7, v7, v142, s6 bitop3:0x60
	v_bitop3_b32 v6, v6, v139, s6 bitop3:0x60
	v_bitop3_b32 v5, v5, v69, s6 bitop3:0x60
	v_bitop3_b32 v3, v3, v8, s6 bitop3:0xf8
	v_bitop3_b32 v2, v2, v9, s6 bitop3:0xf8
	v_bitop3_b32 v1, v1, v10, s6 bitop3:0xf8
	v_and_b32_e32 v8, v7, v140
	v_and_b32_e32 v9, v6, v137
	v_bcnt_u32_b32 v12, v8, 0
	v_and_b32_e32 v10, v5, v67
	v_bcnt_u32_b32 v12, v9, v12
	v_bcnt_u32_b32 v12, v10, v12
	s_nop 1
	v_add_u32_dpp v12, v12, v12 row_ror:8 row_mask:0xf bank_mask:0xf bound_ctrl:1
	s_nop 1
	v_add_u32_dpp v12, v12, v12 row_ror:4 row_mask:0xf bank_mask:0xf bound_ctrl:1
	s_nop 1
	v_add_u32_dpp v12, v12, v12 row_ror:2 row_mask:0xf bank_mask:0xf bound_ctrl:1
	s_nop 1
	v_add_u32_dpp v12, v12, v12 row_ror:1 row_mask:0xf bank_mask:0xf bound_ctrl:1
	s_nop 0
	v_readlane_b32 s6, v12, 0
	v_readlane_b32 s7, v12, 16
	v_readlane_b32 s8, v12, 32
	v_readlane_b32 s9, v12, 48
	s_add_i32 s6, s6, s7
	s_add_i32 s8, s8, s9
	s_add_i32 s6, s6, s57
	s_add_i32 s8, s6, s8
	s_cmpk_eq_i32 s8, 0x100
	s_cbranch_scc1 .Lrdx_eq
	s_cmpk_lt_i32 s8, 0x100
	s_cselect_b32 s6, -1, 0
	s_cselect_b32 s57, s8, s57
	v_bitop3_b32 v7, v7, v140, s6 bitop3:0x60
	v_bitop3_b32 v6, v6, v137, s6 bitop3:0x60
	v_bitop3_b32 v5, v5, v67, s6 bitop3:0x60
	v_bitop3_b32 v3, v3, v8, s6 bitop3:0xf8
	v_bitop3_b32 v2, v2, v9, s6 bitop3:0xf8
	v_bitop3_b32 v1, v1, v10, s6 bitop3:0xf8
	v_and_b32_e32 v8, v7, v138
	v_and_b32_e32 v9, v6, v135
	v_bcnt_u32_b32 v12, v8, 0
	v_and_b32_e32 v10, v5, v65
	v_bcnt_u32_b32 v12, v9, v12
	v_bcnt_u32_b32 v12, v10, v12
	s_nop 1
	v_add_u32_dpp v12, v12, v12 row_ror:8 row_mask:0xf bank_mask:0xf bound_ctrl:1
	s_nop 1
	v_add_u32_dpp v12, v12, v12 row_ror:4 row_mask:0xf bank_mask:0xf bound_ctrl:1
	s_nop 1
	v_add_u32_dpp v12, v12, v12 row_ror:2 row_mask:0xf bank_mask:0xf bound_ctrl:1
	s_nop 1
	v_add_u32_dpp v12, v12, v12 row_ror:1 row_mask:0xf bank_mask:0xf bound_ctrl:1
	s_nop 0
	v_readlane_b32 s6, v12, 0
	v_readlane_b32 s7, v12, 16
	v_readlane_b32 s8, v12, 32
	v_readlane_b32 s9, v12, 48
	s_add_i32 s6, s6, s7
	s_add_i32 s8, s8, s9
	s_add_i32 s6, s6, s57
	s_add_i32 s8, s6, s8
	s_cmpk_eq_i32 s8, 0x100
	s_cbranch_scc1 .Lrdx_eq
	s_cmpk_lt_i32 s8, 0x100
	s_cselect_b32 s6, -1, 0
	s_cselect_b32 s57, s8, s57
	v_bitop3_b32 v7, v7, v138, s6 bitop3:0x60
	v_bitop3_b32 v6, v6, v135, s6 bitop3:0x60
	v_bitop3_b32 v5, v5, v65, s6 bitop3:0x60
	v_bitop3_b32 v3, v3, v8, s6 bitop3:0xf8
	v_bitop3_b32 v2, v2, v9, s6 bitop3:0xf8
	v_bitop3_b32 v1, v1, v10, s6 bitop3:0xf8
	v_and_b32_e32 v8, v7, v136
	v_and_b32_e32 v9, v6, v133
	v_bcnt_u32_b32 v12, v8, 0
	v_and_b32_e32 v10, v5, v63
	v_bcnt_u32_b32 v12, v9, v12
	v_bcnt_u32_b32 v12, v10, v12
	s_nop 1
	v_add_u32_dpp v12, v12, v12 row_ror:8 row_mask:0xf bank_mask:0xf bound_ctrl:1
	s_nop 1
	v_add_u32_dpp v12, v12, v12 row_ror:4 row_mask:0xf bank_mask:0xf bound_ctrl:1
	s_nop 1
	v_add_u32_dpp v12, v12, v12 row_ror:2 row_mask:0xf bank_mask:0xf bound_ctrl:1
	s_nop 1
	v_add_u32_dpp v12, v12, v12 row_ror:1 row_mask:0xf bank_mask:0xf bound_ctrl:1
	s_nop 0
	v_readlane_b32 s6, v12, 0
	v_readlane_b32 s7, v12, 16
	v_readlane_b32 s8, v12, 32
	v_readlane_b32 s9, v12, 48
	s_add_i32 s6, s6, s7
	s_add_i32 s8, s8, s9
	s_add_i32 s6, s6, s57
	s_add_i32 s8, s6, s8
	s_cmpk_eq_i32 s8, 0x100
	s_cbranch_scc1 .Lrdx_eq
	s_cmpk_lt_i32 s8, 0x100
	s_cselect_b32 s6, -1, 0
	s_cselect_b32 s57, s8, s57
	v_bitop3_b32 v7, v7, v136, s6 bitop3:0x60
	v_bitop3_b32 v6, v6, v133, s6 bitop3:0x60
	v_bitop3_b32 v5, v5, v63, s6 bitop3:0x60
	v_bitop3_b32 v3, v3, v8, s6 bitop3:0xf8
	v_bitop3_b32 v2, v2, v9, s6 bitop3:0xf8
	v_bitop3_b32 v1, v1, v10, s6 bitop3:0xf8
	v_and_b32_e32 v8, v7, v134
	v_and_b32_e32 v9, v6, v131
	v_bcnt_u32_b32 v12, v8, 0
	v_and_b32_e32 v10, v5, v61
	v_bcnt_u32_b32 v12, v9, v12
	v_bcnt_u32_b32 v12, v10, v12
	s_nop 1
	v_add_u32_dpp v12, v12, v12 row_ror:8 row_mask:0xf bank_mask:0xf bound_ctrl:1
	s_nop 1
	v_add_u32_dpp v12, v12, v12 row_ror:4 row_mask:0xf bank_mask:0xf bound_ctrl:1
	s_nop 1
	v_add_u32_dpp v12, v12, v12 row_ror:2 row_mask:0xf bank_mask:0xf bound_ctrl:1
	s_nop 1
	v_add_u32_dpp v12, v12, v12 row_ror:1 row_mask:0xf bank_mask:0xf bound_ctrl:1
	s_nop 0
	v_readlane_b32 s6, v12, 0
	v_readlane_b32 s7, v12, 16
	v_readlane_b32 s8, v12, 32
	v_readlane_b32 s9, v12, 48
	s_add_i32 s6, s6, s7
	s_add_i32 s8, s8, s9
	s_add_i32 s6, s6, s57
	s_add_i32 s8, s6, s8
	s_cmpk_eq_i32 s8, 0x100
	s_cbranch_scc1 .Lrdx_eq
	s_cmpk_lt_i32 s8, 0x100
	s_cselect_b32 s6, -1, 0
	s_cselect_b32 s57, s8, s57
	v_bitop3_b32 v7, v7, v134, s6 bitop3:0x60
	v_bitop3_b32 v6, v6, v131, s6 bitop3:0x60
	v_bitop3_b32 v5, v5, v61, s6 bitop3:0x60
	v_bitop3_b32 v3, v3, v8, s6 bitop3:0xf8
	v_bitop3_b32 v2, v2, v9, s6 bitop3:0xf8
	v_bitop3_b32 v1, v1, v10, s6 bitop3:0xf8
	v_and_b32_e32 v8, v7, v132
	v_and_b32_e32 v9, v6, v129
	v_bcnt_u32_b32 v12, v8, 0
	v_and_b32_e32 v10, v5, v59
	v_bcnt_u32_b32 v12, v9, v12
	v_bcnt_u32_b32 v12, v10, v12
	s_nop 1
	v_add_u32_dpp v12, v12, v12 row_ror:8 row_mask:0xf bank_mask:0xf bound_ctrl:1
	s_nop 1
	v_add_u32_dpp v12, v12, v12 row_ror:4 row_mask:0xf bank_mask:0xf bound_ctrl:1
	s_nop 1
	v_add_u32_dpp v12, v12, v12 row_ror:2 row_mask:0xf bank_mask:0xf bound_ctrl:1
	s_nop 1
	v_add_u32_dpp v12, v12, v12 row_ror:1 row_mask:0xf bank_mask:0xf bound_ctrl:1
	s_nop 0
	v_readlane_b32 s6, v12, 0
	v_readlane_b32 s7, v12, 16
	v_readlane_b32 s8, v12, 32
	v_readlane_b32 s9, v12, 48
	s_add_i32 s6, s6, s7
	s_add_i32 s8, s8, s9
	s_add_i32 s6, s6, s57
	s_add_i32 s8, s6, s8
	s_cmpk_eq_i32 s8, 0x100
	s_cbranch_scc1 .Lrdx_eq
	s_cmpk_lt_i32 s8, 0x100
	s_cselect_b32 s6, -1, 0
	s_cselect_b32 s57, s8, s57
	v_bitop3_b32 v7, v7, v132, s6 bitop3:0x60
	v_bitop3_b32 v6, v6, v129, s6 bitop3:0x60
	v_bitop3_b32 v5, v5, v59, s6 bitop3:0x60
	v_bitop3_b32 v3, v3, v8, s6 bitop3:0xf8
	v_bitop3_b32 v2, v2, v9, s6 bitop3:0xf8
	v_bitop3_b32 v1, v1, v10, s6 bitop3:0xf8
	v_and_b32_e32 v8, v7, v130
	v_and_b32_e32 v9, v6, v127
	v_bcnt_u32_b32 v12, v8, 0
	v_and_b32_e32 v10, v5, v57
	v_bcnt_u32_b32 v12, v9, v12
	v_bcnt_u32_b32 v12, v10, v12
	s_nop 1
	v_add_u32_dpp v12, v12, v12 row_ror:8 row_mask:0xf bank_mask:0xf bound_ctrl:1
	s_nop 1
	v_add_u32_dpp v12, v12, v12 row_ror:4 row_mask:0xf bank_mask:0xf bound_ctrl:1
	s_nop 1
	v_add_u32_dpp v12, v12, v12 row_ror:2 row_mask:0xf bank_mask:0xf bound_ctrl:1
	s_nop 1
	v_add_u32_dpp v12, v12, v12 row_ror:1 row_mask:0xf bank_mask:0xf bound_ctrl:1
	s_nop 0
	v_readlane_b32 s6, v12, 0
	v_readlane_b32 s7, v12, 16
	v_readlane_b32 s8, v12, 32
	v_readlane_b32 s9, v12, 48
	s_add_i32 s6, s6, s7
	s_add_i32 s8, s8, s9
	s_add_i32 s6, s6, s57
	s_add_i32 s8, s6, s8
	s_cmpk_eq_i32 s8, 0x100
	s_cbranch_scc1 .Lrdx_eq
	s_cmpk_lt_i32 s8, 0x100
	s_cselect_b32 s6, -1, 0
	s_cselect_b32 s57, s8, s57
	v_bitop3_b32 v7, v7, v130, s6 bitop3:0x60
	v_bitop3_b32 v6, v6, v127, s6 bitop3:0x60
	v_bitop3_b32 v5, v5, v57, s6 bitop3:0x60
	v_bitop3_b32 v3, v3, v8, s6 bitop3:0xf8
	v_bitop3_b32 v2, v2, v9, s6 bitop3:0xf8
	v_bitop3_b32 v1, v1, v10, s6 bitop3:0xf8
	v_and_b32_e32 v8, v7, v128
	v_and_b32_e32 v9, v6, v125
	v_bcnt_u32_b32 v12, v8, 0
	v_and_b32_e32 v10, v5, v55
	v_bcnt_u32_b32 v12, v9, v12
	v_bcnt_u32_b32 v12, v10, v12
	s_nop 1
	v_add_u32_dpp v12, v12, v12 row_ror:8 row_mask:0xf bank_mask:0xf bound_ctrl:1
	s_nop 1
	v_add_u32_dpp v12, v12, v12 row_ror:4 row_mask:0xf bank_mask:0xf bound_ctrl:1
	s_nop 1
	v_add_u32_dpp v12, v12, v12 row_ror:2 row_mask:0xf bank_mask:0xf bound_ctrl:1
	s_nop 1
	v_add_u32_dpp v12, v12, v12 row_ror:1 row_mask:0xf bank_mask:0xf bound_ctrl:1
	s_nop 0
	v_readlane_b32 s6, v12, 0
	v_readlane_b32 s7, v12, 16
	v_readlane_b32 s8, v12, 32
	v_readlane_b32 s9, v12, 48
	s_add_i32 s6, s6, s7
	s_add_i32 s8, s8, s9
	s_add_i32 s6, s6, s57
	s_add_i32 s8, s6, s8
	s_cmpk_eq_i32 s8, 0x100
	s_cbranch_scc1 .Lrdx_eq
	s_cmpk_lt_i32 s8, 0x100
	s_cselect_b32 s6, -1, 0
	s_cselect_b32 s57, s8, s57
	v_bitop3_b32 v7, v7, v128, s6 bitop3:0x60
	v_bitop3_b32 v6, v6, v125, s6 bitop3:0x60
	v_bitop3_b32 v5, v5, v55, s6 bitop3:0x60
	v_bitop3_b32 v3, v3, v8, s6 bitop3:0xf8
	v_bitop3_b32 v2, v2, v9, s6 bitop3:0xf8
	v_bitop3_b32 v1, v1, v10, s6 bitop3:0xf8
	v_and_b32_e32 v8, v7, v126
	v_and_b32_e32 v9, v6, v123
	v_bcnt_u32_b32 v12, v8, 0
	v_and_b32_e32 v10, v5, v53
	v_bcnt_u32_b32 v12, v9, v12
	v_bcnt_u32_b32 v12, v10, v12
	s_nop 1
	v_add_u32_dpp v12, v12, v12 row_ror:8 row_mask:0xf bank_mask:0xf bound_ctrl:1
	s_nop 1
	v_add_u32_dpp v12, v12, v12 row_ror:4 row_mask:0xf bank_mask:0xf bound_ctrl:1
	s_nop 1
	v_add_u32_dpp v12, v12, v12 row_ror:2 row_mask:0xf bank_mask:0xf bound_ctrl:1
	s_nop 1
	v_add_u32_dpp v12, v12, v12 row_ror:1 row_mask:0xf bank_mask:0xf bound_ctrl:1
	s_nop 0
	v_readlane_b32 s6, v12, 0
	v_readlane_b32 s7, v12, 16
	v_readlane_b32 s8, v12, 32
	v_readlane_b32 s9, v12, 48
	s_add_i32 s6, s6, s7
	s_add_i32 s8, s8, s9
	s_add_i32 s6, s6, s57
	s_add_i32 s8, s6, s8
	s_cmpk_eq_i32 s8, 0x100
	s_cbranch_scc1 .Lrdx_eq
	s_cmpk_lt_i32 s8, 0x100
	s_cselect_b32 s6, -1, 0
	s_cselect_b32 s57, s8, s57
	v_bitop3_b32 v7, v7, v126, s6 bitop3:0x60
	v_bitop3_b32 v6, v6, v123, s6 bitop3:0x60
	v_bitop3_b32 v5, v5, v53, s6 bitop3:0x60
	v_bitop3_b32 v3, v3, v8, s6 bitop3:0xf8
	v_bitop3_b32 v2, v2, v9, s6 bitop3:0xf8
	v_bitop3_b32 v1, v1, v10, s6 bitop3:0xf8
	v_and_b32_e32 v8, v7, v124
	v_and_b32_e32 v9, v6, v121
	v_bcnt_u32_b32 v12, v8, 0
	v_and_b32_e32 v10, v5, v51
	v_bcnt_u32_b32 v12, v9, v12
	v_bcnt_u32_b32 v12, v10, v12
	s_nop 1
	v_add_u32_dpp v12, v12, v12 row_ror:8 row_mask:0xf bank_mask:0xf bound_ctrl:1
	s_nop 1
	v_add_u32_dpp v12, v12, v12 row_ror:4 row_mask:0xf bank_mask:0xf bound_ctrl:1
	s_nop 1
	v_add_u32_dpp v12, v12, v12 row_ror:2 row_mask:0xf bank_mask:0xf bound_ctrl:1
	s_nop 1
	v_add_u32_dpp v12, v12, v12 row_ror:1 row_mask:0xf bank_mask:0xf bound_ctrl:1
	s_nop 0
	v_readlane_b32 s6, v12, 0
	v_readlane_b32 s7, v12, 16
	v_readlane_b32 s8, v12, 32
	v_readlane_b32 s9, v12, 48
	s_add_i32 s6, s6, s7
	s_add_i32 s8, s8, s9
	s_add_i32 s6, s6, s57
	s_add_i32 s8, s6, s8
	s_cmpk_eq_i32 s8, 0x100
	s_cbranch_scc1 .Lrdx_eq
	s_cmpk_lt_i32 s8, 0x100
	s_cselect_b32 s6, -1, 0
	s_cselect_b32 s57, s8, s57
	v_bitop3_b32 v7, v7, v124, s6 bitop3:0x60
	v_bitop3_b32 v6, v6, v121, s6 bitop3:0x60
	v_bitop3_b32 v5, v5, v51, s6 bitop3:0x60
	v_bitop3_b32 v3, v3, v8, s6 bitop3:0xf8
	v_bitop3_b32 v2, v2, v9, s6 bitop3:0xf8
	v_bitop3_b32 v1, v1, v10, s6 bitop3:0xf8
	v_and_b32_e32 v8, v7, v122
	v_and_b32_e32 v9, v6, v119
	v_bcnt_u32_b32 v12, v8, 0
	v_and_b32_e32 v10, v5, v49
	v_bcnt_u32_b32 v12, v9, v12
	v_bcnt_u32_b32 v12, v10, v12
	s_nop 1
	v_add_u32_dpp v12, v12, v12 row_ror:8 row_mask:0xf bank_mask:0xf bound_ctrl:1
	s_nop 1
	v_add_u32_dpp v12, v12, v12 row_ror:4 row_mask:0xf bank_mask:0xf bound_ctrl:1
	s_nop 1
	v_add_u32_dpp v12, v12, v12 row_ror:2 row_mask:0xf bank_mask:0xf bound_ctrl:1
	s_nop 1
	v_add_u32_dpp v12, v12, v12 row_ror:1 row_mask:0xf bank_mask:0xf bound_ctrl:1
	s_nop 0
	v_readlane_b32 s6, v12, 0
	v_readlane_b32 s7, v12, 16
	v_readlane_b32 s8, v12, 32
	v_readlane_b32 s9, v12, 48
	s_add_i32 s6, s6, s7
	s_add_i32 s8, s8, s9
	s_add_i32 s6, s6, s57
	s_add_i32 s8, s6, s8
	s_cmpk_eq_i32 s8, 0x100
	s_cbranch_scc1 .Lrdx_eq
	s_cmpk_lt_i32 s8, 0x100
	s_cselect_b32 s6, -1, 0
	s_cselect_b32 s57, s8, s57
	v_bitop3_b32 v7, v7, v122, s6 bitop3:0x60
	v_bitop3_b32 v6, v6, v119, s6 bitop3:0x60
	v_bitop3_b32 v5, v5, v49, s6 bitop3:0x60
	v_bitop3_b32 v3, v3, v8, s6 bitop3:0xf8
	v_bitop3_b32 v2, v2, v9, s6 bitop3:0xf8
	v_bitop3_b32 v1, v1, v10, s6 bitop3:0xf8
	v_and_b32_e32 v8, v7, v120
	v_and_b32_e32 v9, v6, v117
	v_bcnt_u32_b32 v12, v8, 0
	v_and_b32_e32 v10, v5, v47
	v_bcnt_u32_b32 v12, v9, v12
	v_bcnt_u32_b32 v12, v10, v12
	s_nop 1
	v_add_u32_dpp v12, v12, v12 row_ror:8 row_mask:0xf bank_mask:0xf bound_ctrl:1
	s_nop 1
	v_add_u32_dpp v12, v12, v12 row_ror:4 row_mask:0xf bank_mask:0xf bound_ctrl:1
	s_nop 1
	v_add_u32_dpp v12, v12, v12 row_ror:2 row_mask:0xf bank_mask:0xf bound_ctrl:1
	s_nop 1
	v_add_u32_dpp v12, v12, v12 row_ror:1 row_mask:0xf bank_mask:0xf bound_ctrl:1
	s_nop 0
	v_readlane_b32 s6, v12, 0
	v_readlane_b32 s7, v12, 16
	v_readlane_b32 s8, v12, 32
	v_readlane_b32 s9, v12, 48
	s_add_i32 s6, s6, s7
	s_add_i32 s8, s8, s9
	s_add_i32 s6, s6, s57
	s_add_i32 s8, s6, s8
	s_cmpk_eq_i32 s8, 0x100
	s_cbranch_scc1 .Lrdx_eq
	s_cmpk_lt_i32 s8, 0x100
	s_cselect_b32 s6, -1, 0
	s_cselect_b32 s57, s8, s57
	v_bitop3_b32 v7, v7, v120, s6 bitop3:0x60
	v_bitop3_b32 v6, v6, v117, s6 bitop3:0x60
	v_bitop3_b32 v5, v5, v47, s6 bitop3:0x60
	v_bitop3_b32 v3, v3, v8, s6 bitop3:0xf8
	v_bitop3_b32 v2, v2, v9, s6 bitop3:0xf8
	v_bitop3_b32 v1, v1, v10, s6 bitop3:0xf8
	v_and_b32_e32 v8, v7, v118
	v_and_b32_e32 v9, v6, v115
	v_bcnt_u32_b32 v12, v8, 0
	v_and_b32_e32 v10, v5, v45
	v_bcnt_u32_b32 v12, v9, v12
	v_bcnt_u32_b32 v12, v10, v12
	s_nop 1
	v_add_u32_dpp v12, v12, v12 row_ror:8 row_mask:0xf bank_mask:0xf bound_ctrl:1
	s_nop 1
	v_add_u32_dpp v12, v12, v12 row_ror:4 row_mask:0xf bank_mask:0xf bound_ctrl:1
	s_nop 1
	v_add_u32_dpp v12, v12, v12 row_ror:2 row_mask:0xf bank_mask:0xf bound_ctrl:1
	s_nop 1
	v_add_u32_dpp v12, v12, v12 row_ror:1 row_mask:0xf bank_mask:0xf bound_ctrl:1
	s_nop 0
	v_readlane_b32 s6, v12, 0
	v_readlane_b32 s7, v12, 16
	v_readlane_b32 s8, v12, 32
	v_readlane_b32 s9, v12, 48
	s_add_i32 s6, s6, s7
	s_add_i32 s8, s8, s9
	s_add_i32 s6, s6, s57
	s_add_i32 s8, s6, s8
	s_cmpk_eq_i32 s8, 0x100
	s_cbranch_scc1 .Lrdx_eq
	s_cmpk_lt_i32 s8, 0x100
	s_cselect_b32 s6, -1, 0
	s_cselect_b32 s57, s8, s57
	v_bitop3_b32 v7, v7, v118, s6 bitop3:0x60
	v_bitop3_b32 v6, v6, v115, s6 bitop3:0x60
	v_bitop3_b32 v5, v5, v45, s6 bitop3:0x60
	v_bitop3_b32 v3, v3, v8, s6 bitop3:0xf8
	v_bitop3_b32 v2, v2, v9, s6 bitop3:0xf8
	v_bitop3_b32 v1, v1, v10, s6 bitop3:0xf8
	v_and_b32_e32 v8, v7, v116
	v_and_b32_e32 v9, v6, v113
	v_bcnt_u32_b32 v12, v8, 0
	v_and_b32_e32 v10, v5, v42
	v_bcnt_u32_b32 v12, v9, v12
	v_bcnt_u32_b32 v12, v10, v12
	s_nop 1
	v_add_u32_dpp v12, v12, v12 row_ror:8 row_mask:0xf bank_mask:0xf bound_ctrl:1
	s_nop 1
	v_add_u32_dpp v12, v12, v12 row_ror:4 row_mask:0xf bank_mask:0xf bound_ctrl:1
	s_nop 1
	v_add_u32_dpp v12, v12, v12 row_ror:2 row_mask:0xf bank_mask:0xf bound_ctrl:1
	s_nop 1
	v_add_u32_dpp v12, v12, v12 row_ror:1 row_mask:0xf bank_mask:0xf bound_ctrl:1
	s_nop 0
	v_readlane_b32 s6, v12, 0
	v_readlane_b32 s7, v12, 16
	v_readlane_b32 s8, v12, 32
	v_readlane_b32 s9, v12, 48
	s_add_i32 s6, s6, s7
	s_add_i32 s8, s8, s9
	s_add_i32 s6, s6, s57
	s_add_i32 s8, s6, s8
	s_cmpk_eq_i32 s8, 0x100
	s_cbranch_scc1 .Lrdx_eq
	s_cmpk_lt_i32 s8, 0x100
	s_cselect_b32 s6, -1, 0
	s_cselect_b32 s57, s8, s57
	v_bitop3_b32 v7, v7, v116, s6 bitop3:0x60
	v_bitop3_b32 v6, v6, v113, s6 bitop3:0x60
	v_bitop3_b32 v5, v5, v42, s6 bitop3:0x60
	v_bitop3_b32 v3, v3, v8, s6 bitop3:0xf8
	v_bitop3_b32 v2, v2, v9, s6 bitop3:0xf8
	v_bitop3_b32 v1, v1, v10, s6 bitop3:0xf8
	v_and_b32_e32 v8, v7, v114
	v_and_b32_e32 v9, v6, v111
	v_bcnt_u32_b32 v12, v8, 0
	v_and_b32_e32 v10, v5, v40
	v_bcnt_u32_b32 v12, v9, v12
	v_bcnt_u32_b32 v12, v10, v12
	s_nop 1
	v_add_u32_dpp v12, v12, v12 row_ror:8 row_mask:0xf bank_mask:0xf bound_ctrl:1
	s_nop 1
	v_add_u32_dpp v12, v12, v12 row_ror:4 row_mask:0xf bank_mask:0xf bound_ctrl:1
	s_nop 1
	v_add_u32_dpp v12, v12, v12 row_ror:2 row_mask:0xf bank_mask:0xf bound_ctrl:1
	s_nop 1
	v_add_u32_dpp v12, v12, v12 row_ror:1 row_mask:0xf bank_mask:0xf bound_ctrl:1
	s_nop 0
	v_readlane_b32 s6, v12, 0
	v_readlane_b32 s7, v12, 16
	v_readlane_b32 s8, v12, 32
	v_readlane_b32 s9, v12, 48
	s_add_i32 s6, s6, s7
	s_add_i32 s8, s8, s9
	s_add_i32 s6, s6, s57
	s_add_i32 s8, s6, s8
	s_cmpk_eq_i32 s8, 0x100
	s_cbranch_scc1 .Lrdx_eq
	s_cmpk_lt_i32 s8, 0x100
	s_cselect_b32 s6, -1, 0
	s_cselect_b32 s57, s8, s57
	v_bitop3_b32 v7, v7, v114, s6 bitop3:0x60
	v_bitop3_b32 v6, v6, v111, s6 bitop3:0x60
	v_bitop3_b32 v5, v5, v40, s6 bitop3:0x60
	v_bitop3_b32 v3, v3, v8, s6 bitop3:0xf8
	v_bitop3_b32 v2, v2, v9, s6 bitop3:0xf8
	v_bitop3_b32 v1, v1, v10, s6 bitop3:0xf8
	v_and_b32_e32 v8, v7, v112
	v_and_b32_e32 v9, v6, v109
	v_bcnt_u32_b32 v12, v8, 0
	v_and_b32_e32 v10, v5, v38
	v_bcnt_u32_b32 v12, v9, v12
	v_bcnt_u32_b32 v12, v10, v12
	s_nop 1
	v_add_u32_dpp v12, v12, v12 row_ror:8 row_mask:0xf bank_mask:0xf bound_ctrl:1
	s_nop 1
	v_add_u32_dpp v12, v12, v12 row_ror:4 row_mask:0xf bank_mask:0xf bound_ctrl:1
	s_nop 1
	v_add_u32_dpp v12, v12, v12 row_ror:2 row_mask:0xf bank_mask:0xf bound_ctrl:1
	s_nop 1
	v_add_u32_dpp v12, v12, v12 row_ror:1 row_mask:0xf bank_mask:0xf bound_ctrl:1
	s_nop 0
	v_readlane_b32 s6, v12, 0
	v_readlane_b32 s7, v12, 16
	v_readlane_b32 s8, v12, 32
	v_readlane_b32 s9, v12, 48
	s_add_i32 s6, s6, s7
	s_add_i32 s8, s8, s9
	s_add_i32 s6, s6, s57
	s_add_i32 s8, s6, s8
	s_cmpk_eq_i32 s8, 0x100
	s_cbranch_scc1 .Lrdx_eq
	s_cmpk_lt_i32 s8, 0x100
	s_cselect_b32 s6, -1, 0
	s_cselect_b32 s57, s8, s57
	v_bitop3_b32 v7, v7, v112, s6 bitop3:0x60
	v_bitop3_b32 v6, v6, v109, s6 bitop3:0x60
	v_bitop3_b32 v5, v5, v38, s6 bitop3:0x60
	v_bitop3_b32 v3, v3, v8, s6 bitop3:0xf8
	v_bitop3_b32 v2, v2, v9, s6 bitop3:0xf8
	v_bitop3_b32 v1, v1, v10, s6 bitop3:0xf8
	v_and_b32_e32 v8, v7, v110
	v_and_b32_e32 v9, v6, v107
	v_bcnt_u32_b32 v12, v8, 0
	v_and_b32_e32 v10, v5, v36
	v_bcnt_u32_b32 v12, v9, v12
	v_bcnt_u32_b32 v12, v10, v12
	s_nop 1
	v_add_u32_dpp v12, v12, v12 row_ror:8 row_mask:0xf bank_mask:0xf bound_ctrl:1
	s_nop 1
	v_add_u32_dpp v12, v12, v12 row_ror:4 row_mask:0xf bank_mask:0xf bound_ctrl:1
	s_nop 1
	v_add_u32_dpp v12, v12, v12 row_ror:2 row_mask:0xf bank_mask:0xf bound_ctrl:1
	s_nop 1
	v_add_u32_dpp v12, v12, v12 row_ror:1 row_mask:0xf bank_mask:0xf bound_ctrl:1
	s_nop 0
	v_readlane_b32 s6, v12, 0
	v_readlane_b32 s7, v12, 16
	v_readlane_b32 s8, v12, 32
	v_readlane_b32 s9, v12, 48
	s_add_i32 s6, s6, s7
	s_add_i32 s8, s8, s9
	s_add_i32 s6, s6, s57
	s_add_i32 s8, s6, s8
	s_cmpk_eq_i32 s8, 0x100
	s_cbranch_scc1 .Lrdx_eq
	s_cmpk_lt_i32 s8, 0x100
	s_cselect_b32 s6, -1, 0
	s_cselect_b32 s57, s8, s57
	v_bitop3_b32 v7, v7, v110, s6 bitop3:0x60
	v_bitop3_b32 v6, v6, v107, s6 bitop3:0x60
	v_bitop3_b32 v5, v5, v36, s6 bitop3:0x60
	v_bitop3_b32 v3, v3, v8, s6 bitop3:0xf8
	v_bitop3_b32 v2, v2, v9, s6 bitop3:0xf8
	v_bitop3_b32 v1, v1, v10, s6 bitop3:0xf8
	v_and_b32_e32 v8, v7, v108
	v_and_b32_e32 v9, v6, v106
	v_bcnt_u32_b32 v12, v8, 0
	v_and_b32_e32 v10, v5, v34
	v_bcnt_u32_b32 v12, v9, v12
	v_bcnt_u32_b32 v12, v10, v12
	s_nop 1
	v_add_u32_dpp v12, v12, v12 row_ror:8 row_mask:0xf bank_mask:0xf bound_ctrl:1
	s_nop 1
	v_add_u32_dpp v12, v12, v12 row_ror:4 row_mask:0xf bank_mask:0xf bound_ctrl:1
	s_nop 1
	v_add_u32_dpp v12, v12, v12 row_ror:2 row_mask:0xf bank_mask:0xf bound_ctrl:1
	s_nop 1
	v_add_u32_dpp v12, v12, v12 row_ror:1 row_mask:0xf bank_mask:0xf bound_ctrl:1
	s_nop 0
	v_readlane_b32 s6, v12, 0
	v_readlane_b32 s7, v12, 16
	v_readlane_b32 s8, v12, 32
	v_readlane_b32 s9, v12, 48
	s_add_i32 s6, s6, s7
	s_add_i32 s8, s8, s9
	s_add_i32 s6, s6, s57
	s_add_i32 s8, s6, s8
	s_cmpk_eq_i32 s8, 0x100
	s_cbranch_scc1 .Lrdx_eq
	s_cmpk_lt_i32 s8, 0x100
	s_cselect_b32 s6, -1, 0
	s_cselect_b32 s57, s8, s57
	v_bitop3_b32 v7, v7, v108, s6 bitop3:0x60
	v_bitop3_b32 v6, v6, v106, s6 bitop3:0x60
	v_bitop3_b32 v5, v5, v34, s6 bitop3:0x60
	v_bitop3_b32 v3, v3, v8, s6 bitop3:0xf8
	v_bitop3_b32 v2, v2, v9, s6 bitop3:0xf8
	v_bitop3_b32 v1, v1, v10, s6 bitop3:0xf8
	s_branch .LBB0_1099
.Lrdx_w4:
	v_and_b32_e32 v8, v7, v189
	v_and_b32_e32 v9, v6, v186
	v_bcnt_u32_b32 v12, v8, 0
	v_and_b32_e32 v10, v5, v95
	v_bcnt_u32_b32 v12, v9, v12
	v_and_b32_e32 v11, v4, v92
	v_bcnt_u32_b32 v12, v10, v12
	v_bcnt_u32_b32 v12, v11, v12
	s_nop 1
	v_add_u32_dpp v12, v12, v12 row_ror:8 row_mask:0xf bank_mask:0xf bound_ctrl:1
	s_nop 1
	v_add_u32_dpp v12, v12, v12 row_ror:4 row_mask:0xf bank_mask:0xf bound_ctrl:1
	s_nop 1
	v_add_u32_dpp v12, v12, v12 row_ror:2 row_mask:0xf bank_mask:0xf bound_ctrl:1
	s_nop 1
	v_add_u32_dpp v12, v12, v12 row_ror:1 row_mask:0xf bank_mask:0xf bound_ctrl:1
	s_nop 0
	v_readlane_b32 s6, v12, 0
	v_readlane_b32 s7, v12, 16
	v_readlane_b32 s8, v12, 32
	v_readlane_b32 s9, v12, 48
	s_add_i32 s6, s6, s7
	s_add_i32 s8, s8, s9
	s_add_i32 s6, s6, s57
	s_add_i32 s8, s6, s8
	s_cmpk_eq_i32 s8, 0x100
	s_cbranch_scc1 .Lrdx_eq
	s_cmpk_lt_i32 s8, 0x100
	s_cselect_b32 s6, -1, 0
	s_cselect_b32 s57, s8, s57
	v_bitop3_b32 v7, v7, v189, s6 bitop3:0x60
	v_bitop3_b32 v6, v6, v186, s6 bitop3:0x60
	v_bitop3_b32 v5, v5, v95, s6 bitop3:0x60
	v_bitop3_b32 v4, v4, v92, s6 bitop3:0x60
	v_bitop3_b32 v3, v3, v8, s6 bitop3:0xf8
	v_bitop3_b32 v2, v2, v9, s6 bitop3:0xf8
	v_bitop3_b32 v1, v1, v10, s6 bitop3:0xf8
	v_bitop3_b32 v0, v0, v11, s6 bitop3:0xf8
	v_and_b32_e32 v8, v7, v188
	v_and_b32_e32 v9, v6, v185
	v_bcnt_u32_b32 v12, v8, 0
	v_and_b32_e32 v10, v5, v94
	v_bcnt_u32_b32 v12, v9, v12
	v_and_b32_e32 v11, v4, v90
	v_bcnt_u32_b32 v12, v10, v12
	v_bcnt_u32_b32 v12, v11, v12
	s_nop 1
	v_add_u32_dpp v12, v12, v12 row_ror:8 row_mask:0xf bank_mask:0xf bound_ctrl:1
	s_nop 1
	v_add_u32_dpp v12, v12, v12 row_ror:4 row_mask:0xf bank_mask:0xf bound_ctrl:1
	s_nop 1
	v_add_u32_dpp v12, v12, v12 row_ror:2 row_mask:0xf bank_mask:0xf bound_ctrl:1
	s_nop 1
	v_add_u32_dpp v12, v12, v12 row_ror:1 row_mask:0xf bank_mask:0xf bound_ctrl:1
	s_nop 0
	v_readlane_b32 s6, v12, 0
	v_readlane_b32 s7, v12, 16
	v_readlane_b32 s8, v12, 32
	v_readlane_b32 s9, v12, 48
	s_add_i32 s6, s6, s7
	s_add_i32 s8, s8, s9
	s_add_i32 s6, s6, s57
	s_add_i32 s8, s6, s8
	s_cmpk_eq_i32 s8, 0x100
	s_cbranch_scc1 .Lrdx_eq
	s_cmpk_lt_i32 s8, 0x100
	s_cselect_b32 s6, -1, 0
	s_cselect_b32 s57, s8, s57
	v_bitop3_b32 v7, v7, v188, s6 bitop3:0x60
	v_bitop3_b32 v6, v6, v185, s6 bitop3:0x60
	v_bitop3_b32 v5, v5, v94, s6 bitop3:0x60
	v_bitop3_b32 v4, v4, v90, s6 bitop3:0x60
	v_bitop3_b32 v3, v3, v8, s6 bitop3:0xf8
	v_bitop3_b32 v2, v2, v9, s6 bitop3:0xf8
	v_bitop3_b32 v1, v1, v10, s6 bitop3:0xf8
	v_bitop3_b32 v0, v0, v11, s6 bitop3:0xf8
	v_and_b32_e32 v8, v7, v187
	v_and_b32_e32 v9, v6, v183
	v_bcnt_u32_b32 v12, v8, 0
	v_and_b32_e32 v10, v5, v93
	v_bcnt_u32_b32 v12, v9, v12
	v_and_b32_e32 v11, v4, v88
	v_bcnt_u32_b32 v12, v10, v12
	v_bcnt_u32_b32 v12, v11, v12
	s_nop 1
	v_add_u32_dpp v12, v12, v12 row_ror:8 row_mask:0xf bank_mask:0xf bound_ctrl:1
	s_nop 1
	v_add_u32_dpp v12, v12, v12 row_ror:4 row_mask:0xf bank_mask:0xf bound_ctrl:1
	s_nop 1
	v_add_u32_dpp v12, v12, v12 row_ror:2 row_mask:0xf bank_mask:0xf bound_ctrl:1
	s_nop 1
	v_add_u32_dpp v12, v12, v12 row_ror:1 row_mask:0xf bank_mask:0xf bound_ctrl:1
	s_nop 0
	v_readlane_b32 s6, v12, 0
	v_readlane_b32 s7, v12, 16
	v_readlane_b32 s8, v12, 32
	v_readlane_b32 s9, v12, 48
	s_add_i32 s6, s6, s7
	s_add_i32 s8, s8, s9
	s_add_i32 s6, s6, s57
	s_add_i32 s8, s6, s8
	s_cmpk_eq_i32 s8, 0x100
	s_cbranch_scc1 .Lrdx_eq
	s_cmpk_lt_i32 s8, 0x100
	s_cselect_b32 s6, -1, 0
	s_cselect_b32 s57, s8, s57
	v_bitop3_b32 v7, v7, v187, s6 bitop3:0x60
	v_bitop3_b32 v6, v6, v183, s6 bitop3:0x60
	v_bitop3_b32 v5, v5, v93, s6 bitop3:0x60
	v_bitop3_b32 v4, v4, v88, s6 bitop3:0x60
	v_bitop3_b32 v3, v3, v8, s6 bitop3:0xf8
	v_bitop3_b32 v2, v2, v9, s6 bitop3:0xf8
	v_bitop3_b32 v1, v1, v10, s6 bitop3:0xf8
	v_bitop3_b32 v0, v0, v11, s6 bitop3:0xf8
	v_and_b32_e32 v8, v7, v184
	v_and_b32_e32 v9, v6, v161
	v_bcnt_u32_b32 v12, v8, 0
	v_and_b32_e32 v10, v5, v91
	v_bcnt_u32_b32 v12, v9, v12
	v_and_b32_e32 v11, v4, v86
	v_bcnt_u32_b32 v12, v10, v12
	v_bcnt_u32_b32 v12, v11, v12
	s_nop 1
	v_add_u32_dpp v12, v12, v12 row_ror:8 row_mask:0xf bank_mask:0xf bound_ctrl:1
	s_nop 1
	v_add_u32_dpp v12, v12, v12 row_ror:4 row_mask:0xf bank_mask:0xf bound_ctrl:1
	s_nop 1
	v_add_u32_dpp v12, v12, v12 row_ror:2 row_mask:0xf bank_mask:0xf bound_ctrl:1
	s_nop 1
	v_add_u32_dpp v12, v12, v12 row_ror:1 row_mask:0xf bank_mask:0xf bound_ctrl:1
	s_nop 0
	v_readlane_b32 s6, v12, 0
	v_readlane_b32 s7, v12, 16
	v_readlane_b32 s8, v12, 32
	v_readlane_b32 s9, v12, 48
	s_add_i32 s6, s6, s7
	s_add_i32 s8, s8, s9
	s_add_i32 s6, s6, s57
	s_add_i32 s8, s6, s8
	s_cmpk_eq_i32 s8, 0x100
	s_cbranch_scc1 .Lrdx_eq
	s_cmpk_lt_i32 s8, 0x100
	s_cselect_b32 s6, -1, 0
	s_cselect_b32 s57, s8, s57
	v_bitop3_b32 v7, v7, v184, s6 bitop3:0x60
	v_bitop3_b32 v6, v6, v161, s6 bitop3:0x60
	v_bitop3_b32 v5, v5, v91, s6 bitop3:0x60
	v_bitop3_b32 v4, v4, v86, s6 bitop3:0x60
	v_bitop3_b32 v3, v3, v8, s6 bitop3:0xf8
	v_bitop3_b32 v2, v2, v9, s6 bitop3:0xf8
	v_bitop3_b32 v1, v1, v10, s6 bitop3:0xf8
	v_bitop3_b32 v0, v0, v11, s6 bitop3:0xf8
	v_and_b32_e32 v8, v7, v181
	v_and_b32_e32 v9, v6, v159
	v_bcnt_u32_b32 v12, v8, 0
	v_and_b32_e32 v10, v5, v89
	v_bcnt_u32_b32 v12, v9, v12
	v_and_b32_e32 v11, v4, v84
	v_bcnt_u32_b32 v12, v10, v12
	v_bcnt_u32_b32 v12, v11, v12
	s_nop 1
	v_add_u32_dpp v12, v12, v12 row_ror:8 row_mask:0xf bank_mask:0xf bound_ctrl:1
	s_nop 1
	v_add_u32_dpp v12, v12, v12 row_ror:4 row_mask:0xf bank_mask:0xf bound_ctrl:1
	s_nop 1
	v_add_u32_dpp v12, v12, v12 row_ror:2 row_mask:0xf bank_mask:0xf bound_ctrl:1
	s_nop 1
	v_add_u32_dpp v12, v12, v12 row_ror:1 row_mask:0xf bank_mask:0xf bound_ctrl:1
	s_nop 0
	v_readlane_b32 s6, v12, 0
	v_readlane_b32 s7, v12, 16
	v_readlane_b32 s8, v12, 32
	v_readlane_b32 s9, v12, 48
	s_add_i32 s6, s6, s7
	s_add_i32 s8, s8, s9
	s_add_i32 s6, s6, s57
	s_add_i32 s8, s6, s8
	s_cmpk_eq_i32 s8, 0x100
	s_cbranch_scc1 .Lrdx_eq
	s_cmpk_lt_i32 s8, 0x100
	s_cselect_b32 s6, -1, 0
	s_cselect_b32 s57, s8, s57
	v_bitop3_b32 v7, v7, v181, s6 bitop3:0x60
	v_bitop3_b32 v6, v6, v159, s6 bitop3:0x60
	v_bitop3_b32 v5, v5, v89, s6 bitop3:0x60
	v_bitop3_b32 v4, v4, v84, s6 bitop3:0x60
	v_bitop3_b32 v3, v3, v8, s6 bitop3:0xf8
	v_bitop3_b32 v2, v2, v9, s6 bitop3:0xf8
	v_bitop3_b32 v1, v1, v10, s6 bitop3:0xf8
	v_bitop3_b32 v0, v0, v11, s6 bitop3:0xf8
	v_and_b32_e32 v8, v7, v160
	v_and_b32_e32 v9, v6, v157
	v_bcnt_u32_b32 v12, v8, 0
	v_and_b32_e32 v10, v5, v87
	v_bcnt_u32_b32 v12, v9, v12
	v_and_b32_e32 v11, v4, v82
	v_bcnt_u32_b32 v12, v10, v12
	v_bcnt_u32_b32 v12, v11, v12
	s_nop 1
	v_add_u32_dpp v12, v12, v12 row_ror:8 row_mask:0xf bank_mask:0xf bound_ctrl:1
	s_nop 1
	v_add_u32_dpp v12, v12, v12 row_ror:4 row_mask:0xf bank_mask:0xf bound_ctrl:1
	s_nop 1
	v_add_u32_dpp v12, v12, v12 row_ror:2 row_mask:0xf bank_mask:0xf bound_ctrl:1
	s_nop 1
	v_add_u32_dpp v12, v12, v12 row_ror:1 row_mask:0xf bank_mask:0xf bound_ctrl:1
	s_nop 0
	v_readlane_b32 s6, v12, 0
	v_readlane_b32 s7, v12, 16
	v_readlane_b32 s8, v12, 32
	v_readlane_b32 s9, v12, 48
	s_add_i32 s6, s6, s7
	s_add_i32 s8, s8, s9
	s_add_i32 s6, s6, s57
	s_add_i32 s8, s6, s8
	s_cmpk_eq_i32 s8, 0x100
	s_cbranch_scc1 .Lrdx_eq
	s_cmpk_lt_i32 s8, 0x100
	s_cselect_b32 s6, -1, 0
	s_cselect_b32 s57, s8, s57
	v_bitop3_b32 v7, v7, v160, s6 bitop3:0x60
	v_bitop3_b32 v6, v6, v157, s6 bitop3:0x60
	v_bitop3_b32 v5, v5, v87, s6 bitop3:0x60
	v_bitop3_b32 v4, v4, v82, s6 bitop3:0x60
	v_bitop3_b32 v3, v3, v8, s6 bitop3:0xf8
	v_bitop3_b32 v2, v2, v9, s6 bitop3:0xf8
	v_bitop3_b32 v1, v1, v10, s6 bitop3:0xf8
	v_bitop3_b32 v0, v0, v11, s6 bitop3:0xf8
	v_and_b32_e32 v8, v7, v158
	v_and_b32_e32 v9, v6, v155
	v_bcnt_u32_b32 v12, v8, 0
	v_and_b32_e32 v10, v5, v85
	v_bcnt_u32_b32 v12, v9, v12
	v_and_b32_e32 v11, v4, v80
	v_bcnt_u32_b32 v12, v10, v12
	v_bcnt_u32_b32 v12, v11, v12
	s_nop 1
	v_add_u32_dpp v12, v12, v12 row_ror:8 row_mask:0xf bank_mask:0xf bound_ctrl:1
	s_nop 1
	v_add_u32_dpp v12, v12, v12 row_ror:4 row_mask:0xf bank_mask:0xf bound_ctrl:1
	s_nop 1
	v_add_u32_dpp v12, v12, v12 row_ror:2 row_mask:0xf bank_mask:0xf bound_ctrl:1
	s_nop 1
	v_add_u32_dpp v12, v12, v12 row_ror:1 row_mask:0xf bank_mask:0xf bound_ctrl:1
	s_nop 0
	v_readlane_b32 s6, v12, 0
	v_readlane_b32 s7, v12, 16
	v_readlane_b32 s8, v12, 32
	v_readlane_b32 s9, v12, 48
	s_add_i32 s6, s6, s7
	s_add_i32 s8, s8, s9
	s_add_i32 s6, s6, s57
	s_add_i32 s8, s6, s8
	s_cmpk_eq_i32 s8, 0x100
	s_cbranch_scc1 .Lrdx_eq
	s_cmpk_lt_i32 s8, 0x100
	s_cselect_b32 s6, -1, 0
	s_cselect_b32 s57, s8, s57
	v_bitop3_b32 v7, v7, v158, s6 bitop3:0x60
	v_bitop3_b32 v6, v6, v155, s6 bitop3:0x60
	v_bitop3_b32 v5, v5, v85, s6 bitop3:0x60
	v_bitop3_b32 v4, v4, v80, s6 bitop3:0x60
	v_bitop3_b32 v3, v3, v8, s6 bitop3:0xf8
	v_bitop3_b32 v2, v2, v9, s6 bitop3:0xf8
	v_bitop3_b32 v1, v1, v10, s6 bitop3:0xf8
	v_bitop3_b32 v0, v0, v11, s6 bitop3:0xf8
	v_and_b32_e32 v8, v7, v156
	v_and_b32_e32 v9, v6, v153
	v_bcnt_u32_b32 v12, v8, 0
	v_and_b32_e32 v10, v5, v83
	v_bcnt_u32_b32 v12, v9, v12
	v_and_b32_e32 v11, v4, v78
	v_bcnt_u32_b32 v12, v10, v12
	v_bcnt_u32_b32 v12, v11, v12
	s_nop 1
	v_add_u32_dpp v12, v12, v12 row_ror:8 row_mask:0xf bank_mask:0xf bound_ctrl:1
	s_nop 1
	v_add_u32_dpp v12, v12, v12 row_ror:4 row_mask:0xf bank_mask:0xf bound_ctrl:1
	s_nop 1
	v_add_u32_dpp v12, v12, v12 row_ror:2 row_mask:0xf bank_mask:0xf bound_ctrl:1
	s_nop 1
	v_add_u32_dpp v12, v12, v12 row_ror:1 row_mask:0xf bank_mask:0xf bound_ctrl:1
	s_nop 0
	v_readlane_b32 s6, v12, 0
	v_readlane_b32 s7, v12, 16
	v_readlane_b32 s8, v12, 32
	v_readlane_b32 s9, v12, 48
	s_add_i32 s6, s6, s7
	s_add_i32 s8, s8, s9
	s_add_i32 s6, s6, s57
	s_add_i32 s8, s6, s8
	s_cmpk_eq_i32 s8, 0x100
	s_cbranch_scc1 .Lrdx_eq
	s_cmpk_lt_i32 s8, 0x100
	s_cselect_b32 s6, -1, 0
	s_cselect_b32 s57, s8, s57
	v_bitop3_b32 v7, v7, v156, s6 bitop3:0x60
	v_bitop3_b32 v6, v6, v153, s6 bitop3:0x60
	v_bitop3_b32 v5, v5, v83, s6 bitop3:0x60
	v_bitop3_b32 v4, v4, v78, s6 bitop3:0x60
	v_bitop3_b32 v3, v3, v8, s6 bitop3:0xf8
	v_bitop3_b32 v2, v2, v9, s6 bitop3:0xf8
	v_bitop3_b32 v1, v1, v10, s6 bitop3:0xf8
	v_bitop3_b32 v0, v0, v11, s6 bitop3:0xf8
	v_and_b32_e32 v8, v7, v154
	v_and_b32_e32 v9, v6, v151
	v_bcnt_u32_b32 v12, v8, 0
	v_and_b32_e32 v10, v5, v81
	v_bcnt_u32_b32 v12, v9, v12
	v_and_b32_e32 v11, v4, v76
	v_bcnt_u32_b32 v12, v10, v12
	v_bcnt_u32_b32 v12, v11, v12
	s_nop 1
	v_add_u32_dpp v12, v12, v12 row_ror:8 row_mask:0xf bank_mask:0xf bound_ctrl:1
	s_nop 1
	v_add_u32_dpp v12, v12, v12 row_ror:4 row_mask:0xf bank_mask:0xf bound_ctrl:1
	s_nop 1
	v_add_u32_dpp v12, v12, v12 row_ror:2 row_mask:0xf bank_mask:0xf bound_ctrl:1
	s_nop 1
	v_add_u32_dpp v12, v12, v12 row_ror:1 row_mask:0xf bank_mask:0xf bound_ctrl:1
	s_nop 0
	v_readlane_b32 s6, v12, 0
	v_readlane_b32 s7, v12, 16
	v_readlane_b32 s8, v12, 32
	v_readlane_b32 s9, v12, 48
	s_add_i32 s6, s6, s7
	s_add_i32 s8, s8, s9
	s_add_i32 s6, s6, s57
	s_add_i32 s8, s6, s8
	s_cmpk_eq_i32 s8, 0x100
	s_cbranch_scc1 .Lrdx_eq
	s_cmpk_lt_i32 s8, 0x100
	s_cselect_b32 s6, -1, 0
	s_cselect_b32 s57, s8, s57
	v_bitop3_b32 v7, v7, v154, s6 bitop3:0x60
	v_bitop3_b32 v6, v6, v151, s6 bitop3:0x60
	v_bitop3_b32 v5, v5, v81, s6 bitop3:0x60
	v_bitop3_b32 v4, v4, v76, s6 bitop3:0x60
	v_bitop3_b32 v3, v3, v8, s6 bitop3:0xf8
	v_bitop3_b32 v2, v2, v9, s6 bitop3:0xf8
	v_bitop3_b32 v1, v1, v10, s6 bitop3:0xf8
	v_bitop3_b32 v0, v0, v11, s6 bitop3:0xf8
	v_and_b32_e32 v8, v7, v152
	v_and_b32_e32 v9, v6, v149
	v_bcnt_u32_b32 v12, v8, 0
	v_and_b32_e32 v10, v5, v79
	v_bcnt_u32_b32 v12, v9, v12
	v_and_b32_e32 v11, v4, v74
	v_bcnt_u32_b32 v12, v10, v12
	v_bcnt_u32_b32 v12, v11, v12
	s_nop 1
	v_add_u32_dpp v12, v12, v12 row_ror:8 row_mask:0xf bank_mask:0xf bound_ctrl:1
	s_nop 1
	v_add_u32_dpp v12, v12, v12 row_ror:4 row_mask:0xf bank_mask:0xf bound_ctrl:1
	s_nop 1
	v_add_u32_dpp v12, v12, v12 row_ror:2 row_mask:0xf bank_mask:0xf bound_ctrl:1
	s_nop 1
	v_add_u32_dpp v12, v12, v12 row_ror:1 row_mask:0xf bank_mask:0xf bound_ctrl:1
	s_nop 0
	v_readlane_b32 s6, v12, 0
	v_readlane_b32 s7, v12, 16
	v_readlane_b32 s8, v12, 32
	v_readlane_b32 s9, v12, 48
	s_add_i32 s6, s6, s7
	s_add_i32 s8, s8, s9
	s_add_i32 s6, s6, s57
	s_add_i32 s8, s6, s8
	s_cmpk_eq_i32 s8, 0x100
	s_cbranch_scc1 .Lrdx_eq
	s_cmpk_lt_i32 s8, 0x100
	s_cselect_b32 s6, -1, 0
	s_cselect_b32 s57, s8, s57
	v_bitop3_b32 v7, v7, v152, s6 bitop3:0x60
	v_bitop3_b32 v6, v6, v149, s6 bitop3:0x60
	v_bitop3_b32 v5, v5, v79, s6 bitop3:0x60
	v_bitop3_b32 v4, v4, v74, s6 bitop3:0x60
	v_bitop3_b32 v3, v3, v8, s6 bitop3:0xf8
	v_bitop3_b32 v2, v2, v9, s6 bitop3:0xf8
	v_bitop3_b32 v1, v1, v10, s6 bitop3:0xf8
	v_bitop3_b32 v0, v0, v11, s6 bitop3:0xf8
	v_and_b32_e32 v8, v7, v150
	v_and_b32_e32 v9, v6, v147
	v_bcnt_u32_b32 v12, v8, 0
	v_and_b32_e32 v10, v5, v77
	v_bcnt_u32_b32 v12, v9, v12
	v_and_b32_e32 v11, v4, v72
	v_bcnt_u32_b32 v12, v10, v12
	v_bcnt_u32_b32 v12, v11, v12
	s_nop 1
	v_add_u32_dpp v12, v12, v12 row_ror:8 row_mask:0xf bank_mask:0xf bound_ctrl:1
	s_nop 1
	v_add_u32_dpp v12, v12, v12 row_ror:4 row_mask:0xf bank_mask:0xf bound_ctrl:1
	s_nop 1
	v_add_u32_dpp v12, v12, v12 row_ror:2 row_mask:0xf bank_mask:0xf bound_ctrl:1
	s_nop 1
	v_add_u32_dpp v12, v12, v12 row_ror:1 row_mask:0xf bank_mask:0xf bound_ctrl:1
	s_nop 0
	v_readlane_b32 s6, v12, 0
	v_readlane_b32 s7, v12, 16
	v_readlane_b32 s8, v12, 32
	v_readlane_b32 s9, v12, 48
	s_add_i32 s6, s6, s7
	s_add_i32 s8, s8, s9
	s_add_i32 s6, s6, s57
	s_add_i32 s8, s6, s8
	s_cmpk_eq_i32 s8, 0x100
	s_cbranch_scc1 .Lrdx_eq
	s_cmpk_lt_i32 s8, 0x100
	s_cselect_b32 s6, -1, 0
	s_cselect_b32 s57, s8, s57
	v_bitop3_b32 v7, v7, v150, s6 bitop3:0x60
	v_bitop3_b32 v6, v6, v147, s6 bitop3:0x60
	v_bitop3_b32 v5, v5, v77, s6 bitop3:0x60
	v_bitop3_b32 v4, v4, v72, s6 bitop3:0x60
	v_bitop3_b32 v3, v3, v8, s6 bitop3:0xf8
	v_bitop3_b32 v2, v2, v9, s6 bitop3:0xf8
	v_bitop3_b32 v1, v1, v10, s6 bitop3:0xf8
	v_bitop3_b32 v0, v0, v11, s6 bitop3:0xf8
	v_and_b32_e32 v8, v7, v148
	v_and_b32_e32 v9, v6, v145
	v_bcnt_u32_b32 v12, v8, 0
	v_and_b32_e32 v10, v5, v75
	v_bcnt_u32_b32 v12, v9, v12
	v_and_b32_e32 v11, v4, v70
	v_bcnt_u32_b32 v12, v10, v12
	v_bcnt_u32_b32 v12, v11, v12
	s_nop 1
	v_add_u32_dpp v12, v12, v12 row_ror:8 row_mask:0xf bank_mask:0xf bound_ctrl:1
	s_nop 1
	v_add_u32_dpp v12, v12, v12 row_ror:4 row_mask:0xf bank_mask:0xf bound_ctrl:1
	s_nop 1
	v_add_u32_dpp v12, v12, v12 row_ror:2 row_mask:0xf bank_mask:0xf bound_ctrl:1
	s_nop 1
	v_add_u32_dpp v12, v12, v12 row_ror:1 row_mask:0xf bank_mask:0xf bound_ctrl:1
	s_nop 0
	v_readlane_b32 s6, v12, 0
	v_readlane_b32 s7, v12, 16
	v_readlane_b32 s8, v12, 32
	v_readlane_b32 s9, v12, 48
	s_add_i32 s6, s6, s7
	s_add_i32 s8, s8, s9
	s_add_i32 s6, s6, s57
	s_add_i32 s8, s6, s8
	s_cmpk_eq_i32 s8, 0x100
	s_cbranch_scc1 .Lrdx_eq
	s_cmpk_lt_i32 s8, 0x100
	s_cselect_b32 s6, -1, 0
	s_cselect_b32 s57, s8, s57
	v_bitop3_b32 v7, v7, v148, s6 bitop3:0x60
	v_bitop3_b32 v6, v6, v145, s6 bitop3:0x60
	v_bitop3_b32 v5, v5, v75, s6 bitop3:0x60
	v_bitop3_b32 v4, v4, v70, s6 bitop3:0x60
	v_bitop3_b32 v3, v3, v8, s6 bitop3:0xf8
	v_bitop3_b32 v2, v2, v9, s6 bitop3:0xf8
	v_bitop3_b32 v1, v1, v10, s6 bitop3:0xf8
	v_bitop3_b32 v0, v0, v11, s6 bitop3:0xf8
	v_and_b32_e32 v8, v7, v146
	v_and_b32_e32 v9, v6, v143
	v_bcnt_u32_b32 v12, v8, 0
	v_and_b32_e32 v10, v5, v73
	v_bcnt_u32_b32 v12, v9, v12
	v_and_b32_e32 v11, v4, v68
	v_bcnt_u32_b32 v12, v10, v12
	v_bcnt_u32_b32 v12, v11, v12
	s_nop 1
	v_add_u32_dpp v12, v12, v12 row_ror:8 row_mask:0xf bank_mask:0xf bound_ctrl:1
	s_nop 1
	v_add_u32_dpp v12, v12, v12 row_ror:4 row_mask:0xf bank_mask:0xf bound_ctrl:1
	s_nop 1
	v_add_u32_dpp v12, v12, v12 row_ror:2 row_mask:0xf bank_mask:0xf bound_ctrl:1
	s_nop 1
	v_add_u32_dpp v12, v12, v12 row_ror:1 row_mask:0xf bank_mask:0xf bound_ctrl:1
	s_nop 0
	v_readlane_b32 s6, v12, 0
	v_readlane_b32 s7, v12, 16
	v_readlane_b32 s8, v12, 32
	v_readlane_b32 s9, v12, 48
	s_add_i32 s6, s6, s7
	s_add_i32 s8, s8, s9
	s_add_i32 s6, s6, s57
	s_add_i32 s8, s6, s8
	s_cmpk_eq_i32 s8, 0x100
	s_cbranch_scc1 .Lrdx_eq
	s_cmpk_lt_i32 s8, 0x100
	s_cselect_b32 s6, -1, 0
	s_cselect_b32 s57, s8, s57
	v_bitop3_b32 v7, v7, v146, s6 bitop3:0x60
	v_bitop3_b32 v6, v6, v143, s6 bitop3:0x60
	v_bitop3_b32 v5, v5, v73, s6 bitop3:0x60
	v_bitop3_b32 v4, v4, v68, s6 bitop3:0x60
	v_bitop3_b32 v3, v3, v8, s6 bitop3:0xf8
	v_bitop3_b32 v2, v2, v9, s6 bitop3:0xf8
	v_bitop3_b32 v1, v1, v10, s6 bitop3:0xf8
	v_bitop3_b32 v0, v0, v11, s6 bitop3:0xf8
	v_and_b32_e32 v8, v7, v144
	v_and_b32_e32 v9, v6, v141
	v_bcnt_u32_b32 v12, v8, 0
	v_and_b32_e32 v10, v5, v71
	v_bcnt_u32_b32 v12, v9, v12
	v_and_b32_e32 v11, v4, v66
	v_bcnt_u32_b32 v12, v10, v12
	v_bcnt_u32_b32 v12, v11, v12
	s_nop 1
	v_add_u32_dpp v12, v12, v12 row_ror:8 row_mask:0xf bank_mask:0xf bound_ctrl:1
	s_nop 1
	v_add_u32_dpp v12, v12, v12 row_ror:4 row_mask:0xf bank_mask:0xf bound_ctrl:1
	s_nop 1
	v_add_u32_dpp v12, v12, v12 row_ror:2 row_mask:0xf bank_mask:0xf bound_ctrl:1
	s_nop 1
	v_add_u32_dpp v12, v12, v12 row_ror:1 row_mask:0xf bank_mask:0xf bound_ctrl:1
	s_nop 0
	v_readlane_b32 s6, v12, 0
	v_readlane_b32 s7, v12, 16
	v_readlane_b32 s8, v12, 32
	v_readlane_b32 s9, v12, 48
	s_add_i32 s6, s6, s7
	s_add_i32 s8, s8, s9
	s_add_i32 s6, s6, s57
	s_add_i32 s8, s6, s8
	s_cmpk_eq_i32 s8, 0x100
	s_cbranch_scc1 .Lrdx_eq
	s_cmpk_lt_i32 s8, 0x100
	s_cselect_b32 s6, -1, 0
	s_cselect_b32 s57, s8, s57
	v_bitop3_b32 v7, v7, v144, s6 bitop3:0x60
	v_bitop3_b32 v6, v6, v141, s6 bitop3:0x60
	v_bitop3_b32 v5, v5, v71, s6 bitop3:0x60
	v_bitop3_b32 v4, v4, v66, s6 bitop3:0x60
	v_bitop3_b32 v3, v3, v8, s6 bitop3:0xf8
	v_bitop3_b32 v2, v2, v9, s6 bitop3:0xf8
	v_bitop3_b32 v1, v1, v10, s6 bitop3:0xf8
	v_bitop3_b32 v0, v0, v11, s6 bitop3:0xf8
	v_and_b32_e32 v8, v7, v142
	v_and_b32_e32 v9, v6, v139
	v_bcnt_u32_b32 v12, v8, 0
	v_and_b32_e32 v10, v5, v69
	v_bcnt_u32_b32 v12, v9, v12
	v_and_b32_e32 v11, v4, v64
	v_bcnt_u32_b32 v12, v10, v12
	v_bcnt_u32_b32 v12, v11, v12
	s_nop 1
	v_add_u32_dpp v12, v12, v12 row_ror:8 row_mask:0xf bank_mask:0xf bound_ctrl:1
	s_nop 1
	v_add_u32_dpp v12, v12, v12 row_ror:4 row_mask:0xf bank_mask:0xf bound_ctrl:1
	s_nop 1
	v_add_u32_dpp v12, v12, v12 row_ror:2 row_mask:0xf bank_mask:0xf bound_ctrl:1
	s_nop 1
	v_add_u32_dpp v12, v12, v12 row_ror:1 row_mask:0xf bank_mask:0xf bound_ctrl:1
	s_nop 0
	v_readlane_b32 s6, v12, 0
	v_readlane_b32 s7, v12, 16
	v_readlane_b32 s8, v12, 32
	v_readlane_b32 s9, v12, 48
	s_add_i32 s6, s6, s7
	s_add_i32 s8, s8, s9
	s_add_i32 s6, s6, s57
	s_add_i32 s8, s6, s8
	s_cmpk_eq_i32 s8, 0x100
	s_cbranch_scc1 .Lrdx_eq
	s_cmpk_lt_i32 s8, 0x100
	s_cselect_b32 s6, -1, 0
	s_cselect_b32 s57, s8, s57
	v_bitop3_b32 v7, v7, v142, s6 bitop3:0x60
	v_bitop3_b32 v6, v6, v139, s6 bitop3:0x60
	v_bitop3_b32 v5, v5, v69, s6 bitop3:0x60
	v_bitop3_b32 v4, v4, v64, s6 bitop3:0x60
	v_bitop3_b32 v3, v3, v8, s6 bitop3:0xf8
	v_bitop3_b32 v2, v2, v9, s6 bitop3:0xf8
	v_bitop3_b32 v1, v1, v10, s6 bitop3:0xf8
	v_bitop3_b32 v0, v0, v11, s6 bitop3:0xf8
	v_and_b32_e32 v8, v7, v140
	v_and_b32_e32 v9, v6, v137
	v_bcnt_u32_b32 v12, v8, 0
	v_and_b32_e32 v10, v5, v67
	v_bcnt_u32_b32 v12, v9, v12
	v_and_b32_e32 v11, v4, v62
	v_bcnt_u32_b32 v12, v10, v12
	v_bcnt_u32_b32 v12, v11, v12
	s_nop 1
	v_add_u32_dpp v12, v12, v12 row_ror:8 row_mask:0xf bank_mask:0xf bound_ctrl:1
	s_nop 1
	v_add_u32_dpp v12, v12, v12 row_ror:4 row_mask:0xf bank_mask:0xf bound_ctrl:1
	s_nop 1
	v_add_u32_dpp v12, v12, v12 row_ror:2 row_mask:0xf bank_mask:0xf bound_ctrl:1
	s_nop 1
	v_add_u32_dpp v12, v12, v12 row_ror:1 row_mask:0xf bank_mask:0xf bound_ctrl:1
	s_nop 0
	v_readlane_b32 s6, v12, 0
	v_readlane_b32 s7, v12, 16
	v_readlane_b32 s8, v12, 32
	v_readlane_b32 s9, v12, 48
	s_add_i32 s6, s6, s7
	s_add_i32 s8, s8, s9
	s_add_i32 s6, s6, s57
	s_add_i32 s8, s6, s8
	s_cmpk_eq_i32 s8, 0x100
	s_cbranch_scc1 .Lrdx_eq
	s_cmpk_lt_i32 s8, 0x100
	s_cselect_b32 s6, -1, 0
	s_cselect_b32 s57, s8, s57
	v_bitop3_b32 v7, v7, v140, s6 bitop3:0x60
	v_bitop3_b32 v6, v6, v137, s6 bitop3:0x60
	v_bitop3_b32 v5, v5, v67, s6 bitop3:0x60
	v_bitop3_b32 v4, v4, v62, s6 bitop3:0x60
	v_bitop3_b32 v3, v3, v8, s6 bitop3:0xf8
	v_bitop3_b32 v2, v2, v9, s6 bitop3:0xf8
	v_bitop3_b32 v1, v1, v10, s6 bitop3:0xf8
	v_bitop3_b32 v0, v0, v11, s6 bitop3:0xf8
	v_and_b32_e32 v8, v7, v138
	v_and_b32_e32 v9, v6, v135
	v_bcnt_u32_b32 v12, v8, 0
	v_and_b32_e32 v10, v5, v65
	v_bcnt_u32_b32 v12, v9, v12
	v_and_b32_e32 v11, v4, v60
	v_bcnt_u32_b32 v12, v10, v12
	v_bcnt_u32_b32 v12, v11, v12
	s_nop 1
	v_add_u32_dpp v12, v12, v12 row_ror:8 row_mask:0xf bank_mask:0xf bound_ctrl:1
	s_nop 1
	v_add_u32_dpp v12, v12, v12 row_ror:4 row_mask:0xf bank_mask:0xf bound_ctrl:1
	s_nop 1
	v_add_u32_dpp v12, v12, v12 row_ror:2 row_mask:0xf bank_mask:0xf bound_ctrl:1
	s_nop 1
	v_add_u32_dpp v12, v12, v12 row_ror:1 row_mask:0xf bank_mask:0xf bound_ctrl:1
	s_nop 0
	v_readlane_b32 s6, v12, 0
	v_readlane_b32 s7, v12, 16
	v_readlane_b32 s8, v12, 32
	v_readlane_b32 s9, v12, 48
	s_add_i32 s6, s6, s7
	s_add_i32 s8, s8, s9
	s_add_i32 s6, s6, s57
	s_add_i32 s8, s6, s8
	s_cmpk_eq_i32 s8, 0x100
	s_cbranch_scc1 .Lrdx_eq
	s_cmpk_lt_i32 s8, 0x100
	s_cselect_b32 s6, -1, 0
	s_cselect_b32 s57, s8, s57
	v_bitop3_b32 v7, v7, v138, s6 bitop3:0x60
	v_bitop3_b32 v6, v6, v135, s6 bitop3:0x60
	v_bitop3_b32 v5, v5, v65, s6 bitop3:0x60
	v_bitop3_b32 v4, v4, v60, s6 bitop3:0x60
	v_bitop3_b32 v3, v3, v8, s6 bitop3:0xf8
	v_bitop3_b32 v2, v2, v9, s6 bitop3:0xf8
	v_bitop3_b32 v1, v1, v10, s6 bitop3:0xf8
	v_bitop3_b32 v0, v0, v11, s6 bitop3:0xf8
	v_and_b32_e32 v8, v7, v136
	v_and_b32_e32 v9, v6, v133
	v_bcnt_u32_b32 v12, v8, 0
	v_and_b32_e32 v10, v5, v63
	v_bcnt_u32_b32 v12, v9, v12
	v_and_b32_e32 v11, v4, v58
	v_bcnt_u32_b32 v12, v10, v12
	v_bcnt_u32_b32 v12, v11, v12
	s_nop 1
	v_add_u32_dpp v12, v12, v12 row_ror:8 row_mask:0xf bank_mask:0xf bound_ctrl:1
	s_nop 1
	v_add_u32_dpp v12, v12, v12 row_ror:4 row_mask:0xf bank_mask:0xf bound_ctrl:1
	s_nop 1
	v_add_u32_dpp v12, v12, v12 row_ror:2 row_mask:0xf bank_mask:0xf bound_ctrl:1
	s_nop 1
	v_add_u32_dpp v12, v12, v12 row_ror:1 row_mask:0xf bank_mask:0xf bound_ctrl:1
	s_nop 0
	v_readlane_b32 s6, v12, 0
	v_readlane_b32 s7, v12, 16
	v_readlane_b32 s8, v12, 32
	v_readlane_b32 s9, v12, 48
	s_add_i32 s6, s6, s7
	s_add_i32 s8, s8, s9
	s_add_i32 s6, s6, s57
	s_add_i32 s8, s6, s8
	s_cmpk_eq_i32 s8, 0x100
	s_cbranch_scc1 .Lrdx_eq
	s_cmpk_lt_i32 s8, 0x100
	s_cselect_b32 s6, -1, 0
	s_cselect_b32 s57, s8, s57
	v_bitop3_b32 v7, v7, v136, s6 bitop3:0x60
	v_bitop3_b32 v6, v6, v133, s6 bitop3:0x60
	v_bitop3_b32 v5, v5, v63, s6 bitop3:0x60
	v_bitop3_b32 v4, v4, v58, s6 bitop3:0x60
	v_bitop3_b32 v3, v3, v8, s6 bitop3:0xf8
	v_bitop3_b32 v2, v2, v9, s6 bitop3:0xf8
	v_bitop3_b32 v1, v1, v10, s6 bitop3:0xf8
	v_bitop3_b32 v0, v0, v11, s6 bitop3:0xf8
	v_and_b32_e32 v8, v7, v134
	v_and_b32_e32 v9, v6, v131
	v_bcnt_u32_b32 v12, v8, 0
	v_and_b32_e32 v10, v5, v61
	v_bcnt_u32_b32 v12, v9, v12
	v_and_b32_e32 v11, v4, v56
	v_bcnt_u32_b32 v12, v10, v12
	v_bcnt_u32_b32 v12, v11, v12
	s_nop 1
	v_add_u32_dpp v12, v12, v12 row_ror:8 row_mask:0xf bank_mask:0xf bound_ctrl:1
	s_nop 1
	v_add_u32_dpp v12, v12, v12 row_ror:4 row_mask:0xf bank_mask:0xf bound_ctrl:1
	s_nop 1
	v_add_u32_dpp v12, v12, v12 row_ror:2 row_mask:0xf bank_mask:0xf bound_ctrl:1
	s_nop 1
	v_add_u32_dpp v12, v12, v12 row_ror:1 row_mask:0xf bank_mask:0xf bound_ctrl:1
	s_nop 0
	v_readlane_b32 s6, v12, 0
	v_readlane_b32 s7, v12, 16
	v_readlane_b32 s8, v12, 32
	v_readlane_b32 s9, v12, 48
	s_add_i32 s6, s6, s7
	s_add_i32 s8, s8, s9
	s_add_i32 s6, s6, s57
	s_add_i32 s8, s6, s8
	s_cmpk_eq_i32 s8, 0x100
	s_cbranch_scc1 .Lrdx_eq
	s_cmpk_lt_i32 s8, 0x100
	s_cselect_b32 s6, -1, 0
	s_cselect_b32 s57, s8, s57
	v_bitop3_b32 v7, v7, v134, s6 bitop3:0x60
	v_bitop3_b32 v6, v6, v131, s6 bitop3:0x60
	v_bitop3_b32 v5, v5, v61, s6 bitop3:0x60
	v_bitop3_b32 v4, v4, v56, s6 bitop3:0x60
	v_bitop3_b32 v3, v3, v8, s6 bitop3:0xf8
	v_bitop3_b32 v2, v2, v9, s6 bitop3:0xf8
	v_bitop3_b32 v1, v1, v10, s6 bitop3:0xf8
	v_bitop3_b32 v0, v0, v11, s6 bitop3:0xf8
	v_and_b32_e32 v8, v7, v132
	v_and_b32_e32 v9, v6, v129
	v_bcnt_u32_b32 v12, v8, 0
	v_and_b32_e32 v10, v5, v59
	v_bcnt_u32_b32 v12, v9, v12
	v_and_b32_e32 v11, v4, v54
	v_bcnt_u32_b32 v12, v10, v12
	v_bcnt_u32_b32 v12, v11, v12
	s_nop 1
	v_add_u32_dpp v12, v12, v12 row_ror:8 row_mask:0xf bank_mask:0xf bound_ctrl:1
	s_nop 1
	v_add_u32_dpp v12, v12, v12 row_ror:4 row_mask:0xf bank_mask:0xf bound_ctrl:1
	s_nop 1
	v_add_u32_dpp v12, v12, v12 row_ror:2 row_mask:0xf bank_mask:0xf bound_ctrl:1
	s_nop 1
	v_add_u32_dpp v12, v12, v12 row_ror:1 row_mask:0xf bank_mask:0xf bound_ctrl:1
	s_nop 0
	v_readlane_b32 s6, v12, 0
	v_readlane_b32 s7, v12, 16
	v_readlane_b32 s8, v12, 32
	v_readlane_b32 s9, v12, 48
	s_add_i32 s6, s6, s7
	s_add_i32 s8, s8, s9
	s_add_i32 s6, s6, s57
	s_add_i32 s8, s6, s8
	s_cmpk_eq_i32 s8, 0x100
	s_cbranch_scc1 .Lrdx_eq
	s_cmpk_lt_i32 s8, 0x100
	s_cselect_b32 s6, -1, 0
	s_cselect_b32 s57, s8, s57
	v_bitop3_b32 v7, v7, v132, s6 bitop3:0x60
	v_bitop3_b32 v6, v6, v129, s6 bitop3:0x60
	v_bitop3_b32 v5, v5, v59, s6 bitop3:0x60
	v_bitop3_b32 v4, v4, v54, s6 bitop3:0x60
	v_bitop3_b32 v3, v3, v8, s6 bitop3:0xf8
	v_bitop3_b32 v2, v2, v9, s6 bitop3:0xf8
	v_bitop3_b32 v1, v1, v10, s6 bitop3:0xf8
	v_bitop3_b32 v0, v0, v11, s6 bitop3:0xf8
	v_and_b32_e32 v8, v7, v130
	v_and_b32_e32 v9, v6, v127
	v_bcnt_u32_b32 v12, v8, 0
	v_and_b32_e32 v10, v5, v57
	v_bcnt_u32_b32 v12, v9, v12
	v_and_b32_e32 v11, v4, v52
	v_bcnt_u32_b32 v12, v10, v12
	v_bcnt_u32_b32 v12, v11, v12
	s_nop 1
	v_add_u32_dpp v12, v12, v12 row_ror:8 row_mask:0xf bank_mask:0xf bound_ctrl:1
	s_nop 1
	v_add_u32_dpp v12, v12, v12 row_ror:4 row_mask:0xf bank_mask:0xf bound_ctrl:1
	s_nop 1
	v_add_u32_dpp v12, v12, v12 row_ror:2 row_mask:0xf bank_mask:0xf bound_ctrl:1
	s_nop 1
	v_add_u32_dpp v12, v12, v12 row_ror:1 row_mask:0xf bank_mask:0xf bound_ctrl:1
	s_nop 0
	v_readlane_b32 s6, v12, 0
	v_readlane_b32 s7, v12, 16
	v_readlane_b32 s8, v12, 32
	v_readlane_b32 s9, v12, 48
	s_add_i32 s6, s6, s7
	s_add_i32 s8, s8, s9
	s_add_i32 s6, s6, s57
	s_add_i32 s8, s6, s8
	s_cmpk_eq_i32 s8, 0x100
	s_cbranch_scc1 .Lrdx_eq
	s_cmpk_lt_i32 s8, 0x100
	s_cselect_b32 s6, -1, 0
	s_cselect_b32 s57, s8, s57
	v_bitop3_b32 v7, v7, v130, s6 bitop3:0x60
	v_bitop3_b32 v6, v6, v127, s6 bitop3:0x60
	v_bitop3_b32 v5, v5, v57, s6 bitop3:0x60
	v_bitop3_b32 v4, v4, v52, s6 bitop3:0x60
	v_bitop3_b32 v3, v3, v8, s6 bitop3:0xf8
	v_bitop3_b32 v2, v2, v9, s6 bitop3:0xf8
	v_bitop3_b32 v1, v1, v10, s6 bitop3:0xf8
	v_bitop3_b32 v0, v0, v11, s6 bitop3:0xf8
	v_and_b32_e32 v8, v7, v128
	v_and_b32_e32 v9, v6, v125
	v_bcnt_u32_b32 v12, v8, 0
	v_and_b32_e32 v10, v5, v55
	v_bcnt_u32_b32 v12, v9, v12
	v_and_b32_e32 v11, v4, v50
	v_bcnt_u32_b32 v12, v10, v12
	v_bcnt_u32_b32 v12, v11, v12
	s_nop 1
	v_add_u32_dpp v12, v12, v12 row_ror:8 row_mask:0xf bank_mask:0xf bound_ctrl:1
	s_nop 1
	v_add_u32_dpp v12, v12, v12 row_ror:4 row_mask:0xf bank_mask:0xf bound_ctrl:1
	s_nop 1
	v_add_u32_dpp v12, v12, v12 row_ror:2 row_mask:0xf bank_mask:0xf bound_ctrl:1
	s_nop 1
	v_add_u32_dpp v12, v12, v12 row_ror:1 row_mask:0xf bank_mask:0xf bound_ctrl:1
	s_nop 0
	v_readlane_b32 s6, v12, 0
	v_readlane_b32 s7, v12, 16
	v_readlane_b32 s8, v12, 32
	v_readlane_b32 s9, v12, 48
	s_add_i32 s6, s6, s7
	s_add_i32 s8, s8, s9
	s_add_i32 s6, s6, s57
	s_add_i32 s8, s6, s8
	s_cmpk_eq_i32 s8, 0x100
	s_cbranch_scc1 .Lrdx_eq
	s_cmpk_lt_i32 s8, 0x100
	s_cselect_b32 s6, -1, 0
	s_cselect_b32 s57, s8, s57
	v_bitop3_b32 v7, v7, v128, s6 bitop3:0x60
	v_bitop3_b32 v6, v6, v125, s6 bitop3:0x60
	v_bitop3_b32 v5, v5, v55, s6 bitop3:0x60
	v_bitop3_b32 v4, v4, v50, s6 bitop3:0x60
	v_bitop3_b32 v3, v3, v8, s6 bitop3:0xf8
	v_bitop3_b32 v2, v2, v9, s6 bitop3:0xf8
	v_bitop3_b32 v1, v1, v10, s6 bitop3:0xf8
	v_bitop3_b32 v0, v0, v11, s6 bitop3:0xf8
	v_and_b32_e32 v8, v7, v126
	v_and_b32_e32 v9, v6, v123
	v_bcnt_u32_b32 v12, v8, 0
	v_and_b32_e32 v10, v5, v53
	v_bcnt_u32_b32 v12, v9, v12
	v_and_b32_e32 v11, v4, v48
	v_bcnt_u32_b32 v12, v10, v12
	v_bcnt_u32_b32 v12, v11, v12
	s_nop 1
	v_add_u32_dpp v12, v12, v12 row_ror:8 row_mask:0xf bank_mask:0xf bound_ctrl:1
	s_nop 1
	v_add_u32_dpp v12, v12, v12 row_ror:4 row_mask:0xf bank_mask:0xf bound_ctrl:1
	s_nop 1
	v_add_u32_dpp v12, v12, v12 row_ror:2 row_mask:0xf bank_mask:0xf bound_ctrl:1
	s_nop 1
	v_add_u32_dpp v12, v12, v12 row_ror:1 row_mask:0xf bank_mask:0xf bound_ctrl:1
	s_nop 0
	v_readlane_b32 s6, v12, 0
	v_readlane_b32 s7, v12, 16
	v_readlane_b32 s8, v12, 32
	v_readlane_b32 s9, v12, 48
	s_add_i32 s6, s6, s7
	s_add_i32 s8, s8, s9
	s_add_i32 s6, s6, s57
	s_add_i32 s8, s6, s8
	s_cmpk_eq_i32 s8, 0x100
	s_cbranch_scc1 .Lrdx_eq
	s_cmpk_lt_i32 s8, 0x100
	s_cselect_b32 s6, -1, 0
	s_cselect_b32 s57, s8, s57
	v_bitop3_b32 v7, v7, v126, s6 bitop3:0x60
	v_bitop3_b32 v6, v6, v123, s6 bitop3:0x60
	v_bitop3_b32 v5, v5, v53, s6 bitop3:0x60
	v_bitop3_b32 v4, v4, v48, s6 bitop3:0x60
	v_bitop3_b32 v3, v3, v8, s6 bitop3:0xf8
	v_bitop3_b32 v2, v2, v9, s6 bitop3:0xf8
	v_bitop3_b32 v1, v1, v10, s6 bitop3:0xf8
	v_bitop3_b32 v0, v0, v11, s6 bitop3:0xf8
	v_and_b32_e32 v8, v7, v124
	v_and_b32_e32 v9, v6, v121
	v_bcnt_u32_b32 v12, v8, 0
	v_and_b32_e32 v10, v5, v51
	v_bcnt_u32_b32 v12, v9, v12
	v_and_b32_e32 v11, v4, v46
	v_bcnt_u32_b32 v12, v10, v12
	v_bcnt_u32_b32 v12, v11, v12
	s_nop 1
	v_add_u32_dpp v12, v12, v12 row_ror:8 row_mask:0xf bank_mask:0xf bound_ctrl:1
	s_nop 1
	v_add_u32_dpp v12, v12, v12 row_ror:4 row_mask:0xf bank_mask:0xf bound_ctrl:1
	s_nop 1
	v_add_u32_dpp v12, v12, v12 row_ror:2 row_mask:0xf bank_mask:0xf bound_ctrl:1
	s_nop 1
	v_add_u32_dpp v12, v12, v12 row_ror:1 row_mask:0xf bank_mask:0xf bound_ctrl:1
	s_nop 0
	v_readlane_b32 s6, v12, 0
	v_readlane_b32 s7, v12, 16
	v_readlane_b32 s8, v12, 32
	v_readlane_b32 s9, v12, 48
	s_add_i32 s6, s6, s7
	s_add_i32 s8, s8, s9
	s_add_i32 s6, s6, s57
	s_add_i32 s8, s6, s8
	s_cmpk_eq_i32 s8, 0x100
	s_cbranch_scc1 .Lrdx_eq
	s_cmpk_lt_i32 s8, 0x100
	s_cselect_b32 s6, -1, 0
	s_cselect_b32 s57, s8, s57
	v_bitop3_b32 v7, v7, v124, s6 bitop3:0x60
	v_bitop3_b32 v6, v6, v121, s6 bitop3:0x60
	v_bitop3_b32 v5, v5, v51, s6 bitop3:0x60
	v_bitop3_b32 v4, v4, v46, s6 bitop3:0x60
	v_bitop3_b32 v3, v3, v8, s6 bitop3:0xf8
	v_bitop3_b32 v2, v2, v9, s6 bitop3:0xf8
	v_bitop3_b32 v1, v1, v10, s6 bitop3:0xf8
	v_bitop3_b32 v0, v0, v11, s6 bitop3:0xf8
	v_and_b32_e32 v8, v7, v122
	v_and_b32_e32 v9, v6, v119
	v_bcnt_u32_b32 v12, v8, 0
	v_and_b32_e32 v10, v5, v49
	v_bcnt_u32_b32 v12, v9, v12
	v_and_b32_e32 v11, v4, v44
	v_bcnt_u32_b32 v12, v10, v12
	v_bcnt_u32_b32 v12, v11, v12
	s_nop 1
	v_add_u32_dpp v12, v12, v12 row_ror:8 row_mask:0xf bank_mask:0xf bound_ctrl:1
	s_nop 1
	v_add_u32_dpp v12, v12, v12 row_ror:4 row_mask:0xf bank_mask:0xf bound_ctrl:1
	s_nop 1
	v_add_u32_dpp v12, v12, v12 row_ror:2 row_mask:0xf bank_mask:0xf bound_ctrl:1
	s_nop 1
	v_add_u32_dpp v12, v12, v12 row_ror:1 row_mask:0xf bank_mask:0xf bound_ctrl:1
	s_nop 0
	v_readlane_b32 s6, v12, 0
	v_readlane_b32 s7, v12, 16
	v_readlane_b32 s8, v12, 32
	v_readlane_b32 s9, v12, 48
	s_add_i32 s6, s6, s7
	s_add_i32 s8, s8, s9
	s_add_i32 s6, s6, s57
	s_add_i32 s8, s6, s8
	s_cmpk_eq_i32 s8, 0x100
	s_cbranch_scc1 .Lrdx_eq
	s_cmpk_lt_i32 s8, 0x100
	s_cselect_b32 s6, -1, 0
	s_cselect_b32 s57, s8, s57
	v_bitop3_b32 v7, v7, v122, s6 bitop3:0x60
	v_bitop3_b32 v6, v6, v119, s6 bitop3:0x60
	v_bitop3_b32 v5, v5, v49, s6 bitop3:0x60
	v_bitop3_b32 v4, v4, v44, s6 bitop3:0x60
	v_bitop3_b32 v3, v3, v8, s6 bitop3:0xf8
	v_bitop3_b32 v2, v2, v9, s6 bitop3:0xf8
	v_bitop3_b32 v1, v1, v10, s6 bitop3:0xf8
	v_bitop3_b32 v0, v0, v11, s6 bitop3:0xf8
	v_and_b32_e32 v8, v7, v120
	v_and_b32_e32 v9, v6, v117
	v_bcnt_u32_b32 v12, v8, 0
	v_and_b32_e32 v10, v5, v47
	v_bcnt_u32_b32 v12, v9, v12
	v_and_b32_e32 v11, v4, v43
	v_bcnt_u32_b32 v12, v10, v12
	v_bcnt_u32_b32 v12, v11, v12
	s_nop 1
	v_add_u32_dpp v12, v12, v12 row_ror:8 row_mask:0xf bank_mask:0xf bound_ctrl:1
	s_nop 1
	v_add_u32_dpp v12, v12, v12 row_ror:4 row_mask:0xf bank_mask:0xf bound_ctrl:1
	s_nop 1
	v_add_u32_dpp v12, v12, v12 row_ror:2 row_mask:0xf bank_mask:0xf bound_ctrl:1
	s_nop 1
	v_add_u32_dpp v12, v12, v12 row_ror:1 row_mask:0xf bank_mask:0xf bound_ctrl:1
	s_nop 0
	v_readlane_b32 s6, v12, 0
	v_readlane_b32 s7, v12, 16
	v_readlane_b32 s8, v12, 32
	v_readlane_b32 s9, v12, 48
	s_add_i32 s6, s6, s7
	s_add_i32 s8, s8, s9
	s_add_i32 s6, s6, s57
	s_add_i32 s8, s6, s8
	s_cmpk_eq_i32 s8, 0x100
	s_cbranch_scc1 .Lrdx_eq
	s_cmpk_lt_i32 s8, 0x100
	s_cselect_b32 s6, -1, 0
	s_cselect_b32 s57, s8, s57
	v_bitop3_b32 v7, v7, v120, s6 bitop3:0x60
	v_bitop3_b32 v6, v6, v117, s6 bitop3:0x60
	v_bitop3_b32 v5, v5, v47, s6 bitop3:0x60
	v_bitop3_b32 v4, v4, v43, s6 bitop3:0x60
	v_bitop3_b32 v3, v3, v8, s6 bitop3:0xf8
	v_bitop3_b32 v2, v2, v9, s6 bitop3:0xf8
	v_bitop3_b32 v1, v1, v10, s6 bitop3:0xf8
	v_bitop3_b32 v0, v0, v11, s6 bitop3:0xf8
	v_and_b32_e32 v8, v7, v118
	v_and_b32_e32 v9, v6, v115
	v_bcnt_u32_b32 v12, v8, 0
	v_and_b32_e32 v10, v5, v45
	v_bcnt_u32_b32 v12, v9, v12
	v_and_b32_e32 v11, v4, v41
	v_bcnt_u32_b32 v12, v10, v12
	v_bcnt_u32_b32 v12, v11, v12
	s_nop 1
	v_add_u32_dpp v12, v12, v12 row_ror:8 row_mask:0xf bank_mask:0xf bound_ctrl:1
	s_nop 1
	v_add_u32_dpp v12, v12, v12 row_ror:4 row_mask:0xf bank_mask:0xf bound_ctrl:1
	s_nop 1
	v_add_u32_dpp v12, v12, v12 row_ror:2 row_mask:0xf bank_mask:0xf bound_ctrl:1
	s_nop 1
	v_add_u32_dpp v12, v12, v12 row_ror:1 row_mask:0xf bank_mask:0xf bound_ctrl:1
	s_nop 0
	v_readlane_b32 s6, v12, 0
	v_readlane_b32 s7, v12, 16
	v_readlane_b32 s8, v12, 32
	v_readlane_b32 s9, v12, 48
	s_add_i32 s6, s6, s7
	s_add_i32 s8, s8, s9
	s_add_i32 s6, s6, s57
	s_add_i32 s8, s6, s8
	s_cmpk_eq_i32 s8, 0x100
	s_cbranch_scc1 .Lrdx_eq
	s_cmpk_lt_i32 s8, 0x100
	s_cselect_b32 s6, -1, 0
	s_cselect_b32 s57, s8, s57
	v_bitop3_b32 v7, v7, v118, s6 bitop3:0x60
	v_bitop3_b32 v6, v6, v115, s6 bitop3:0x60
	v_bitop3_b32 v5, v5, v45, s6 bitop3:0x60
	v_bitop3_b32 v4, v4, v41, s6 bitop3:0x60
	v_bitop3_b32 v3, v3, v8, s6 bitop3:0xf8
	v_bitop3_b32 v2, v2, v9, s6 bitop3:0xf8
	v_bitop3_b32 v1, v1, v10, s6 bitop3:0xf8
	v_bitop3_b32 v0, v0, v11, s6 bitop3:0xf8
	v_and_b32_e32 v8, v7, v116
	v_and_b32_e32 v9, v6, v113
	v_bcnt_u32_b32 v12, v8, 0
	v_and_b32_e32 v10, v5, v42
	v_bcnt_u32_b32 v12, v9, v12
	v_and_b32_e32 v11, v4, v39
	v_bcnt_u32_b32 v12, v10, v12
	v_bcnt_u32_b32 v12, v11, v12
	s_nop 1
	v_add_u32_dpp v12, v12, v12 row_ror:8 row_mask:0xf bank_mask:0xf bound_ctrl:1
	s_nop 1
	v_add_u32_dpp v12, v12, v12 row_ror:4 row_mask:0xf bank_mask:0xf bound_ctrl:1
	s_nop 1
	v_add_u32_dpp v12, v12, v12 row_ror:2 row_mask:0xf bank_mask:0xf bound_ctrl:1
	s_nop 1
	v_add_u32_dpp v12, v12, v12 row_ror:1 row_mask:0xf bank_mask:0xf bound_ctrl:1
	s_nop 0
	v_readlane_b32 s6, v12, 0
	v_readlane_b32 s7, v12, 16
	v_readlane_b32 s8, v12, 32
	v_readlane_b32 s9, v12, 48
	s_add_i32 s6, s6, s7
	s_add_i32 s8, s8, s9
	s_add_i32 s6, s6, s57
	s_add_i32 s8, s6, s8
	s_cmpk_eq_i32 s8, 0x100
	s_cbranch_scc1 .Lrdx_eq
	s_cmpk_lt_i32 s8, 0x100
	s_cselect_b32 s6, -1, 0
	s_cselect_b32 s57, s8, s57
	v_bitop3_b32 v7, v7, v116, s6 bitop3:0x60
	v_bitop3_b32 v6, v6, v113, s6 bitop3:0x60
	v_bitop3_b32 v5, v5, v42, s6 bitop3:0x60
	v_bitop3_b32 v4, v4, v39, s6 bitop3:0x60
	v_bitop3_b32 v3, v3, v8, s6 bitop3:0xf8
	v_bitop3_b32 v2, v2, v9, s6 bitop3:0xf8
	v_bitop3_b32 v1, v1, v10, s6 bitop3:0xf8
	v_bitop3_b32 v0, v0, v11, s6 bitop3:0xf8
	v_and_b32_e32 v8, v7, v114
	v_and_b32_e32 v9, v6, v111
	v_bcnt_u32_b32 v12, v8, 0
	v_and_b32_e32 v10, v5, v40
	v_bcnt_u32_b32 v12, v9, v12
	v_and_b32_e32 v11, v4, v37
	v_bcnt_u32_b32 v12, v10, v12
	v_bcnt_u32_b32 v12, v11, v12
	s_nop 1
	v_add_u32_dpp v12, v12, v12 row_ror:8 row_mask:0xf bank_mask:0xf bound_ctrl:1
	s_nop 1
	v_add_u32_dpp v12, v12, v12 row_ror:4 row_mask:0xf bank_mask:0xf bound_ctrl:1
	s_nop 1
	v_add_u32_dpp v12, v12, v12 row_ror:2 row_mask:0xf bank_mask:0xf bound_ctrl:1
	s_nop 1
	v_add_u32_dpp v12, v12, v12 row_ror:1 row_mask:0xf bank_mask:0xf bound_ctrl:1
	s_nop 0
	v_readlane_b32 s6, v12, 0
	v_readlane_b32 s7, v12, 16
	v_readlane_b32 s8, v12, 32
	v_readlane_b32 s9, v12, 48
	s_add_i32 s6, s6, s7
	s_add_i32 s8, s8, s9
	s_add_i32 s6, s6, s57
	s_add_i32 s8, s6, s8
	s_cmpk_eq_i32 s8, 0x100
	s_cbranch_scc1 .Lrdx_eq
	s_cmpk_lt_i32 s8, 0x100
	s_cselect_b32 s6, -1, 0
	s_cselect_b32 s57, s8, s57
	v_bitop3_b32 v7, v7, v114, s6 bitop3:0x60
	v_bitop3_b32 v6, v6, v111, s6 bitop3:0x60
	v_bitop3_b32 v5, v5, v40, s6 bitop3:0x60
	v_bitop3_b32 v4, v4, v37, s6 bitop3:0x60
	v_bitop3_b32 v3, v3, v8, s6 bitop3:0xf8
	v_bitop3_b32 v2, v2, v9, s6 bitop3:0xf8
	v_bitop3_b32 v1, v1, v10, s6 bitop3:0xf8
	v_bitop3_b32 v0, v0, v11, s6 bitop3:0xf8
	v_and_b32_e32 v8, v7, v112
	v_and_b32_e32 v9, v6, v109
	v_bcnt_u32_b32 v12, v8, 0
	v_and_b32_e32 v10, v5, v38
	v_bcnt_u32_b32 v12, v9, v12
	v_and_b32_e32 v11, v4, v35
	v_bcnt_u32_b32 v12, v10, v12
	v_bcnt_u32_b32 v12, v11, v12
	s_nop 1
	v_add_u32_dpp v12, v12, v12 row_ror:8 row_mask:0xf bank_mask:0xf bound_ctrl:1
	s_nop 1
	v_add_u32_dpp v12, v12, v12 row_ror:4 row_mask:0xf bank_mask:0xf bound_ctrl:1
	s_nop 1
	v_add_u32_dpp v12, v12, v12 row_ror:2 row_mask:0xf bank_mask:0xf bound_ctrl:1
	s_nop 1
	v_add_u32_dpp v12, v12, v12 row_ror:1 row_mask:0xf bank_mask:0xf bound_ctrl:1
	s_nop 0
	v_readlane_b32 s6, v12, 0
	v_readlane_b32 s7, v12, 16
	v_readlane_b32 s8, v12, 32
	v_readlane_b32 s9, v12, 48
	s_add_i32 s6, s6, s7
	s_add_i32 s8, s8, s9
	s_add_i32 s6, s6, s57
	s_add_i32 s8, s6, s8
	s_cmpk_eq_i32 s8, 0x100
	s_cbranch_scc1 .Lrdx_eq
	s_cmpk_lt_i32 s8, 0x100
	s_cselect_b32 s6, -1, 0
	s_cselect_b32 s57, s8, s57
	v_bitop3_b32 v7, v7, v112, s6 bitop3:0x60
	v_bitop3_b32 v6, v6, v109, s6 bitop3:0x60
	v_bitop3_b32 v5, v5, v38, s6 bitop3:0x60
	v_bitop3_b32 v4, v4, v35, s6 bitop3:0x60
	v_bitop3_b32 v3, v3, v8, s6 bitop3:0xf8
	v_bitop3_b32 v2, v2, v9, s6 bitop3:0xf8
	v_bitop3_b32 v1, v1, v10, s6 bitop3:0xf8
	v_bitop3_b32 v0, v0, v11, s6 bitop3:0xf8
	v_and_b32_e32 v8, v7, v110
	v_and_b32_e32 v9, v6, v107
	v_bcnt_u32_b32 v12, v8, 0
	v_and_b32_e32 v10, v5, v36
	v_bcnt_u32_b32 v12, v9, v12
	v_and_b32_e32 v11, v4, v33
	v_bcnt_u32_b32 v12, v10, v12
	v_bcnt_u32_b32 v12, v11, v12
	s_nop 1
	v_add_u32_dpp v12, v12, v12 row_ror:8 row_mask:0xf bank_mask:0xf bound_ctrl:1
	s_nop 1
	v_add_u32_dpp v12, v12, v12 row_ror:4 row_mask:0xf bank_mask:0xf bound_ctrl:1
	s_nop 1
	v_add_u32_dpp v12, v12, v12 row_ror:2 row_mask:0xf bank_mask:0xf bound_ctrl:1
	s_nop 1
	v_add_u32_dpp v12, v12, v12 row_ror:1 row_mask:0xf bank_mask:0xf bound_ctrl:1
	s_nop 0
	v_readlane_b32 s6, v12, 0
	v_readlane_b32 s7, v12, 16
	v_readlane_b32 s8, v12, 32
	v_readlane_b32 s9, v12, 48
	s_add_i32 s6, s6, s7
	s_add_i32 s8, s8, s9
	s_add_i32 s6, s6, s57
	s_add_i32 s8, s6, s8
	s_cmpk_eq_i32 s8, 0x100
	s_cbranch_scc1 .Lrdx_eq
	s_cmpk_lt_i32 s8, 0x100
	s_cselect_b32 s6, -1, 0
	s_cselect_b32 s57, s8, s57
	v_bitop3_b32 v7, v7, v110, s6 bitop3:0x60
	v_bitop3_b32 v6, v6, v107, s6 bitop3:0x60
	v_bitop3_b32 v5, v5, v36, s6 bitop3:0x60
	v_bitop3_b32 v4, v4, v33, s6 bitop3:0x60
	v_bitop3_b32 v3, v3, v8, s6 bitop3:0xf8
	v_bitop3_b32 v2, v2, v9, s6 bitop3:0xf8
	v_bitop3_b32 v1, v1, v10, s6 bitop3:0xf8
	v_bitop3_b32 v0, v0, v11, s6 bitop3:0xf8
	v_and_b32_e32 v8, v7, v108
	v_and_b32_e32 v9, v6, v106
	v_bcnt_u32_b32 v12, v8, 0
	v_and_b32_e32 v10, v5, v34
	v_bcnt_u32_b32 v12, v9, v12
	v_and_b32_e32 v11, v4, v32
	v_bcnt_u32_b32 v12, v10, v12
	v_bcnt_u32_b32 v12, v11, v12
	s_nop 1
	v_add_u32_dpp v12, v12, v12 row_ror:8 row_mask:0xf bank_mask:0xf bound_ctrl:1
	s_nop 1
	v_add_u32_dpp v12, v12, v12 row_ror:4 row_mask:0xf bank_mask:0xf bound_ctrl:1
	s_nop 1
	v_add_u32_dpp v12, v12, v12 row_ror:2 row_mask:0xf bank_mask:0xf bound_ctrl:1
	s_nop 1
	v_add_u32_dpp v12, v12, v12 row_ror:1 row_mask:0xf bank_mask:0xf bound_ctrl:1
	s_nop 0
	v_readlane_b32 s6, v12, 0
	v_readlane_b32 s7, v12, 16
	v_readlane_b32 s8, v12, 32
	v_readlane_b32 s9, v12, 48
	s_add_i32 s6, s6, s7
	s_add_i32 s8, s8, s9
	s_add_i32 s6, s6, s57
	s_add_i32 s8, s6, s8
	s_cmpk_eq_i32 s8, 0x100
	s_cbranch_scc1 .Lrdx_eq
	s_cmpk_lt_i32 s8, 0x100
	s_cselect_b32 s6, -1, 0
	s_cselect_b32 s57, s8, s57
	v_bitop3_b32 v7, v7, v108, s6 bitop3:0x60
	v_bitop3_b32 v6, v6, v106, s6 bitop3:0x60
	v_bitop3_b32 v5, v5, v34, s6 bitop3:0x60
	v_bitop3_b32 v4, v4, v32, s6 bitop3:0x60
	v_bitop3_b32 v3, v3, v8, s6 bitop3:0xf8
	v_bitop3_b32 v2, v2, v9, s6 bitop3:0xf8
	v_bitop3_b32 v1, v1, v10, s6 bitop3:0xf8
	v_bitop3_b32 v0, v0, v11, s6 bitop3:0xf8
	s_branch .LBB0_1099
